# peel first K-iteration of all 13 GEMM loops: first-step MFMAs take C=0, 128 v_mov zeroing per tile removed; plus in-proj epilogue wait fix
# speedup vs baseline: 1.0092x; 1.0092x over previous
; #define PG8_STAGE(bufoff, gbase, voff) do { _Pragma("unroll") for (int _i = 0; _i < 2; ++_i) \
;         __builtin_amdgcn_global_load_lds((const unsigned*)((const char*)(gbase) + (voff)[_i]), (LAS unsigned*)(lds + (bufoff) + ldsw + _i * 8192), 16, 0, 0); } while (0)
; #define PG8_LDA(dst, b, h) do { _Pragma("unroll") for (int m = 0; m < 4; ++m) _Pragma("unroll") for (int k = 0; k < 2; ++k) dst[m][k] = *(const LAS bf16x8*)(lds + PG8_SA(b, h) + aoff + m * 2048 + k * 1024); } while (0)
; #define PG8_LDB(dst, b, h) do { _Pragma("unroll") for (int n = 0; n < 2; ++n) _Pragma("unroll") for (int k = 0; k < 2; ++k) dst[n][k] = *(const LAS bf16x8*)(lds + PG8_SB(b, h) + boff + n * 2048 + k * 1024); } while (0)
; #define PG8_WAIT_V(n) asm volatile("s_waitcnt vmcnt(" #n ")" ::: "memory")
; #define PG8_WAIT_L(n) asm volatile("s_waitcnt lgkmcnt(" #n ")" ::: "memory")
; #define PG8_BAR __builtin_amdgcn_s_barrier()
; #define PG8_SCHED __builtin_amdgcn_sched_barrier(0)
; template <class Epi, class Sched>
; __device__ __forceinline__ void gemm_phase(LAS unsigned char* lds, const Gemm g, const Sched& S, const Epi& E) {
;     ...
;         const bool has_next = S.next(ui + 1, nxt);
;         const char* nA = has_next ? (const char*)g.A + (size_t)nxt.pm * tstep : cA; const char* nB = has_next ? (const char*)g.Bt + (size_t)nxt.pn * tstep : cB;
;         for (int t = 0; t < nt; t += 2) {
;             const bool last = (t == nt - 2);
;             const char* a1 = cA + (size_t)(t + 1) * kstep;
;             const char* a2 = last ? nA : cA + (size_t)(t + 2) * kstep; const char* b2 = last ? nB : cB + (size_t)(t + 2) * kstep;
;             const char* a3 = a2 + kstep; const char* b3 = b2 + kstep;
;             PG8_LDB(B0, 0, 0); PG8_SCHED; PG8_LDA(At, 0, 0); PG8_STAGE(PG8_SA(1, 1), a1 + hstep, voffA);
;             PG8_WAIT_L(8); PG8_BAR; PG8_WAIT_L(0); PG8_MMA(0, 0, At, B0); PG8_BAR; PG8_SCHED;
;             PG8_LDB(B1, 0, 1); PG8_STAGE(PG8_SB(0, 0), b2, voffB);
;             PG8_BAR; PG8_WAIT_L(0); PG8_MMA(0, 1, At, B1); PG8_BAR;
;             PG8_LDA(At, 0, 1); PG8_STAGE(PG8_SA(0, 0), a2, voffA);
;             PG8_BAR; PG8_WAIT_L(0); PG8_MMA(1, 0, At, B0); PG8_BAR; PG8_SCHED;
;             PG8_STAGE(PG8_SB(0, 1), b2 + hstep, voffB);
;             PG8_WAIT_V(6); PG8_BAR; PG8_MMA(1, 1, At, B1); PG8_BAR;
.LBB0_234:
	s_ashr_i32 s7, s6, 31
	v_cmp_lt_i64_e32 vcc, s[8:9], v[140:141]
	s_lshl_b64 s[8:9], s[6:7], 19
	s_add_u32 s8, s96, s8
	s_addc_u32 s9, s97, s9
	s_and_b64 s[10:11], vcc, exec
	s_cselect_b32 s7, s9, s15
	s_cselect_b32 s44, s8, s14
	s_ashr_i32 s5, s4, 31
	s_lshl_b64 s[10:11], s[4:5], 19
	s_add_u32 s10, s72, s10
	s_addc_u32 s11, s73, s11
	s_and_b64 s[16:17], vcc, exec
	s_cselect_b32 s5, s11, s19
	s_cselect_b32 s45, s10, s18
	s_add_u32 s14, s14, 0x40080
	s_addc_u32 s15, s15, 0
	s_add_u32 s46, s18, 0x100
	s_addc_u32 s47, s19, 0
	s_mov_b32 s48, -2
	ds_read_b128 v[150:153], v147
	ds_read_b128 v[154:157], v147 offset:1024
	ds_read_b128 v[158:161], v147 offset:2048
	ds_read_b128 v[162:165], v147 offset:3072
	s_add_u32 s16, s14, 0xfffc0080
	s_addc_u32 s17, s15, -1
	s_cmp_eq_u32 s48, 12
	s_cselect_b32 s23, s7, s17
	s_cselect_b32 s22, s44, s16
	s_cselect_b32 s19, s5, s47
	s_cselect_b32 s18, s45, s46
	v_lshl_add_u64 v[198:199], s[14:15], 0, v[136:137]
	s_add_i32 m0, s13, 0xc000
	ds_read_b128 v[166:169], v148
	ds_read_b128 v[170:173], v148 offset:1024
	ds_read_b128 v[174:177], v148 offset:2048
	ds_read_b128 v[178:181], v148 offset:3072
	ds_read_b128 v[182:185], v148 offset:4096
	ds_read_b128 v[186:189], v148 offset:5120
	ds_read_b128 v[190:193], v148 offset:6144
	ds_read_b128 v[194:197], v148 offset:7168
	global_load_lds_dwordx4 v[198:199], off
	v_lshl_add_u64 v[198:199], s[14:15], 0, v[138:139]
	s_add_i32 m0, s13, 0xe000
	s_nop 0
	global_load_lds_dwordx4 v[198:199], off
	s_waitcnt lgkmcnt(8)
	s_barrier
	s_waitcnt lgkmcnt(0)
	s_setprio 1
	s_waitcnt lgkmcnt(0)
	v_mfma_f32_16x16x32_bf16 v[124:127], v[150:153], v[166:169], 0
	v_mfma_f32_16x16x32_bf16 v[116:119], v[158:161], v[166:169], 0
	v_mfma_f32_16x16x32_bf16 v[108:111], v[150:153], v[174:177], 0
	v_mfma_f32_16x16x32_bf16 v[100:103], v[158:161], v[174:177], 0
	v_mfma_f32_16x16x32_bf16 v[92:95], v[150:153], v[182:185], 0
	v_mfma_f32_16x16x32_bf16 v[84:87], v[158:161], v[182:185], 0
	v_mfma_f32_16x16x32_bf16 v[76:79], v[150:153], v[190:193], 0
	v_mfma_f32_16x16x32_bf16 v[68:71], v[158:161], v[190:193], 0
	v_mfma_f32_16x16x32_bf16 v[124:127], v[154:157], v[170:173], v[124:127]
	v_mfma_f32_16x16x32_bf16 v[116:119], v[162:165], v[170:173], v[116:119]
	v_mfma_f32_16x16x32_bf16 v[108:111], v[154:157], v[178:181], v[108:111]
	v_mfma_f32_16x16x32_bf16 v[100:103], v[162:165], v[178:181], v[100:103]
	v_mfma_f32_16x16x32_bf16 v[92:95], v[154:157], v[186:189], v[92:95]
	v_mfma_f32_16x16x32_bf16 v[84:87], v[162:165], v[186:189], v[84:87]
	v_mfma_f32_16x16x32_bf16 v[76:79], v[154:157], v[194:197], v[76:79]
	v_mfma_f32_16x16x32_bf16 v[68:71], v[162:165], v[194:197], v[68:71]
	s_setprio 0
	s_barrier
	s_add_i32 s16, s40, s25
	v_lshl_add_u64 v[198:199], s[18:19], 0, v[132:133]
	s_mov_b32 m0, s16
	ds_read_b128 v[202:205], v149
	ds_read_b128 v[206:209], v149 offset:1024
	ds_read_b128 v[210:213], v149 offset:2048
	ds_read_b128 v[214:217], v149 offset:3072
	global_load_lds_dwordx4 v[198:199], off
	v_lshl_add_u64 v[218:219], s[18:19], 0, v[128:129]
	s_add_i32 m0, s16, 0x2000
	s_nop 0
	global_load_lds_dwordx4 v[218:219], off
	s_barrier
	s_waitcnt lgkmcnt(0)
	s_setprio 1
	s_waitcnt lgkmcnt(0)
	v_mfma_f32_16x16x32_bf16 v[120:123], v[202:205], v[166:169], 0
	v_mfma_f32_16x16x32_bf16 v[112:115], v[210:213], v[166:169], 0
	v_mfma_f32_16x16x32_bf16 v[104:107], v[202:205], v[174:177], 0
	v_mfma_f32_16x16x32_bf16 v[96:99], v[210:213], v[174:177], 0
	v_mfma_f32_16x16x32_bf16 v[88:91], v[202:205], v[182:185], 0
	v_mfma_f32_16x16x32_bf16 v[80:83], v[210:213], v[182:185], 0
	v_mfma_f32_16x16x32_bf16 v[72:75], v[202:205], v[190:193], 0
	v_mfma_f32_16x16x32_bf16 v[64:67], v[210:213], v[190:193], 0
	v_mfma_f32_16x16x32_bf16 v[120:123], v[206:209], v[170:173], v[120:123]
	v_mfma_f32_16x16x32_bf16 v[112:115], v[214:217], v[170:173], v[112:115]
	v_mfma_f32_16x16x32_bf16 v[104:107], v[206:209], v[178:181], v[104:107]
	v_mfma_f32_16x16x32_bf16 v[96:99], v[214:217], v[178:181], v[96:99]
	v_mfma_f32_16x16x32_bf16 v[88:91], v[206:209], v[186:189], v[88:91]
	v_mfma_f32_16x16x32_bf16 v[80:83], v[214:217], v[186:189], v[80:83]
	v_mfma_f32_16x16x32_bf16 v[72:75], v[206:209], v[194:197], v[72:75]
	v_mfma_f32_16x16x32_bf16 v[64:67], v[214:217], v[194:197], v[64:67]
	s_setprio 0
	s_mov_b32 m0, s13
	v_lshl_add_u64 v[220:221], s[22:23], 0, v[134:135]
	s_barrier
	ds_read_b128 v[166:169], v148 offset:16384
	ds_read_b128 v[170:173], v148 offset:17408
	ds_read_b128 v[174:177], v148 offset:18432
	ds_read_b128 v[178:181], v148 offset:19456
	ds_read_b128 v[182:185], v148 offset:20480
	ds_read_b128 v[186:189], v148 offset:21504
	ds_read_b128 v[190:193], v148 offset:22528
	ds_read_b128 v[194:197], v148 offset:23552
	global_load_lds_dwordx4 v[220:221], off
	v_lshl_add_u64 v[222:223], s[22:23], 0, v[130:131]
	s_mov_b32 m0, s28
	s_nop 0
	global_load_lds_dwordx4 v[222:223], off
	s_barrier
	s_waitcnt lgkmcnt(0)
	s_setprio 1
	s_waitcnt lgkmcnt(0)
	v_mfma_f32_16x16x32_bf16 v[60:63], v[150:153], v[166:169], 0
	v_mfma_f32_16x16x32_bf16 v[56:59], v[158:161], v[166:169], 0
	v_mfma_f32_16x16x32_bf16 v[44:47], v[150:153], v[174:177], 0
	v_mfma_f32_16x16x32_bf16 v[40:43], v[158:161], v[174:177], 0
	v_mfma_f32_16x16x32_bf16 v[28:31], v[150:153], v[182:185], 0
	v_mfma_f32_16x16x32_bf16 v[24:27], v[158:161], v[182:185], 0
	v_mfma_f32_16x16x32_bf16 v[12:15], v[150:153], v[190:193], 0
	v_mfma_f32_16x16x32_bf16 v[8:11], v[158:161], v[190:193], 0
	v_mfma_f32_16x16x32_bf16 v[60:63], v[154:157], v[170:173], v[60:63]
	v_mfma_f32_16x16x32_bf16 v[56:59], v[162:165], v[170:173], v[56:59]
	v_mfma_f32_16x16x32_bf16 v[44:47], v[154:157], v[178:181], v[44:47]
	v_mfma_f32_16x16x32_bf16 v[40:43], v[162:165], v[178:181], v[40:43]
	v_mfma_f32_16x16x32_bf16 v[28:31], v[154:157], v[186:189], v[28:31]
	v_mfma_f32_16x16x32_bf16 v[24:27], v[162:165], v[186:189], v[24:27]
	v_mfma_f32_16x16x32_bf16 v[12:15], v[154:157], v[194:197], v[12:15]
	v_mfma_f32_16x16x32_bf16 v[8:11], v[162:165], v[194:197], v[8:11]
	s_setprio 0
	s_barrier
; #define PG8_STAGE(bufoff, gbase, voff) do { _Pragma("unroll") for (int _i = 0; _i < 2; ++_i) \
;         __builtin_amdgcn_global_load_lds((const unsigned*)((const char*)(gbase) + (voff)[_i]), (LAS unsigned*)(lds + (bufoff) + ldsw + _i * 8192), 16, 0, 0); } while (0)
; #define PG8_LDA(dst, b, h) do { _Pragma("unroll") for (int m = 0; m < 4; ++m) _Pragma("unroll") for (int k = 0; k < 2; ++k) dst[m][k] = *(const LAS bf16x8*)(lds + PG8_SA(b, h) + aoff + m * 2048 + k * 1024); } while (0)
; #define PG8_LDB(dst, b, h) do { _Pragma("unroll") for (int n = 0; n < 2; ++n) _Pragma("unroll") for (int k = 0; k < 2; ++k) dst[n][k] = *(const LAS bf16x8*)(lds + PG8_SB(b, h) + boff + n * 2048 + k * 1024); } while (0)
; #define PG8_MMA(ai, bj, At, Bt) do { __builtin_amdgcn_s_setprio(1); _Pragma("unroll") for (int m = 0; m < 4; ++m) _Pragma("unroll") for (int n = 0; n < 2; ++n) _Pragma("unroll") for (int k = 0; k < 2; ++k) \
;         acc[ai][bj][m][n] = __builtin_amdgcn_mfma_f32_16x16x32_bf16(Bt[n][k], At[m][k], acc[ai][bj][m][n], 0, 0, 0); __builtin_amdgcn_s_setprio(0); } while (0)
; #define PG8_WAIT_V(n) asm volatile("s_waitcnt vmcnt(" #n ")" ::: "memory")
; #define PG8_WAIT_L(n) asm volatile("s_waitcnt lgkmcnt(" #n ")" ::: "memory")
; #define PG8_BAR __builtin_amdgcn_s_barrier()
; #define PG8_SCHED __builtin_amdgcn_sched_barrier(0)
; template <class Epi, class Sched>
; __device__ __forceinline__ void gemm_phase(LAS unsigned char* lds, const Gemm g, const Sched& S, const Epi& E) {
;     ...
;             PG8_STAGE(PG8_SB(0, 1), b2 + hstep, voffB);
;             PG8_WAIT_V(6); PG8_BAR; PG8_MMA(1, 1, At, B1); PG8_BAR;
;             PG8_LDB(B0, 1, 0); PG8_SCHED; PG8_LDA(At, 1, 0); PG8_STAGE(PG8_SA(0, 1), a2 + hstep, voffA);
;             PG8_WAIT_L(8); PG8_BAR; PG8_WAIT_L(0); PG8_MMA(0, 0, At, B0); PG8_BAR; PG8_SCHED;
;             PG8_LDB(B1, 1, 1); PG8_STAGE(PG8_SB(1, 0), b3, voffB);
	s_add_u32 s16, s18, 0x40000
	s_addc_u32 s17, s19, 0
	s_add_i32 s20, s41, s25
	v_lshl_add_u64 v[150:151], s[16:17], 0, v[132:133]
	s_mov_b32 m0, s20
	s_nop 0
	global_load_lds_dwordx4 v[150:151], off
	v_lshl_add_u64 v[150:151], s[16:17], 0, v[128:129]
	s_add_i32 m0, s20, 0x2000
	s_nop 0
	global_load_lds_dwordx4 v[150:151], off
	s_waitcnt vmcnt(6)
	s_barrier
	s_setprio 1
	v_mfma_f32_16x16x32_bf16 v[52:55], v[202:205], v[166:169], 0
	v_mfma_f32_16x16x32_bf16 v[48:51], v[210:213], v[166:169], 0
	v_mfma_f32_16x16x32_bf16 v[36:39], v[202:205], v[174:177], 0
	v_mfma_f32_16x16x32_bf16 v[32:35], v[210:213], v[174:177], 0
	v_mfma_f32_16x16x32_bf16 v[20:23], v[202:205], v[182:185], 0
	v_mfma_f32_16x16x32_bf16 v[16:19], v[210:213], v[182:185], 0
	v_mfma_f32_16x16x32_bf16 v[4:7], v[202:205], v[190:193], 0
	v_mfma_f32_16x16x32_bf16 v[0:3], v[210:213], v[190:193], 0
	v_mfma_f32_16x16x32_bf16 v[52:55], v[206:209], v[170:173], v[52:55]
	v_mfma_f32_16x16x32_bf16 v[48:51], v[214:217], v[170:173], v[48:51]
	v_mfma_f32_16x16x32_bf16 v[36:39], v[206:209], v[178:181], v[36:39]
	v_mfma_f32_16x16x32_bf16 v[32:35], v[214:217], v[178:181], v[32:35]
	v_mfma_f32_16x16x32_bf16 v[20:23], v[206:209], v[186:189], v[20:23]
	v_mfma_f32_16x16x32_bf16 v[16:19], v[214:217], v[186:189], v[16:19]
	v_mfma_f32_16x16x32_bf16 v[4:7], v[206:209], v[194:197], v[4:7]
	v_mfma_f32_16x16x32_bf16 v[0:3], v[214:217], v[194:197], v[0:3]
	s_setprio 0
	s_add_i32 s20, 0, 0x18000
	v_add_u32_e32 v162, s20, v146
	s_barrier
	ds_read_b128 v[150:153], v162
	ds_read_b128 v[154:157], v162 offset:1024
	ds_read_b128 v[158:161], v162 offset:2048
	ds_read_b128 v[162:165], v162 offset:3072
	s_add_u32 s16, s22, 0x40000
	s_addc_u32 s17, s23, 0
	s_mov_b32 m0, s29
	v_lshl_add_u64 v[202:203], s[16:17], 0, v[134:135]
	ds_read_b128 v[166:169], v148 offset:32768
	ds_read_b128 v[170:173], v148 offset:33792
	ds_read_b128 v[174:177], v148 offset:34816
	ds_read_b128 v[178:181], v148 offset:35840
	ds_read_b128 v[182:185], v148 offset:36864
	ds_read_b128 v[186:189], v148 offset:37888
	ds_read_b128 v[190:193], v148 offset:38912
	ds_read_b128 v[194:197], v148 offset:39936
	global_load_lds_dwordx4 v[202:203], off
	v_lshl_add_u64 v[202:203], s[16:17], 0, v[130:131]
	s_mov_b32 m0, s33
	s_nop 0
	global_load_lds_dwordx4 v[202:203], off
	s_waitcnt lgkmcnt(8)
	s_barrier
	s_waitcnt lgkmcnt(0)
	s_setprio 1
	s_waitcnt lgkmcnt(0)
	v_mfma_f32_16x16x32_bf16 v[124:127], v[150:153], v[166:169], v[124:127]
	v_mfma_f32_16x16x32_bf16 v[116:119], v[158:161], v[166:169], v[116:119]
	v_mfma_f32_16x16x32_bf16 v[108:111], v[150:153], v[174:177], v[108:111]
	v_mfma_f32_16x16x32_bf16 v[100:103], v[158:161], v[174:177], v[100:103]
	v_mfma_f32_16x16x32_bf16 v[92:95], v[150:153], v[182:185], v[92:95]
	v_mfma_f32_16x16x32_bf16 v[84:87], v[158:161], v[182:185], v[84:87]
	v_mfma_f32_16x16x32_bf16 v[76:79], v[150:153], v[190:193], v[76:79]
	v_mfma_f32_16x16x32_bf16 v[68:71], v[158:161], v[190:193], v[68:71]
	v_mfma_f32_16x16x32_bf16 v[124:127], v[154:157], v[170:173], v[124:127]
	v_mfma_f32_16x16x32_bf16 v[116:119], v[162:165], v[170:173], v[116:119]
	v_mfma_f32_16x16x32_bf16 v[108:111], v[154:157], v[178:181], v[108:111]
	v_mfma_f32_16x16x32_bf16 v[100:103], v[162:165], v[178:181], v[100:103]
	v_mfma_f32_16x16x32_bf16 v[92:95], v[154:157], v[186:189], v[92:95]
	v_mfma_f32_16x16x32_bf16 v[84:87], v[162:165], v[186:189], v[84:87]
	v_mfma_f32_16x16x32_bf16 v[76:79], v[154:157], v[194:197], v[76:79]
	v_mfma_f32_16x16x32_bf16 v[68:71], v[162:165], v[194:197], v[68:71]
	s_setprio 0
	s_barrier
	s_add_i32 s21, 0, 0x1c000
	s_add_i32 s16, s20, s25
	v_add_u32_e32 v214, s21, v146
	v_lshl_add_u64 v[198:199], v[198:199], 0, s[0:1]
	s_mov_b32 m0, s16
	ds_read_b128 v[202:205], v214
	ds_read_b128 v[206:209], v214 offset:1024
	ds_read_b128 v[210:213], v214 offset:2048
	ds_read_b128 v[214:217], v214 offset:3072
	global_load_lds_dwordx4 v[198:199], off
	v_lshl_add_u64 v[198:199], v[218:219], 0, s[0:1]
	s_add_i32 m0, s16, 0x2000
	s_nop 0
	global_load_lds_dwordx4 v[198:199], off
	s_barrier
; #define PG8_STAGE(bufoff, gbase, voff) do { _Pragma("unroll") for (int _i = 0; _i < 2; ++_i) \
;         __builtin_amdgcn_global_load_lds((const unsigned*)((const char*)(gbase) + (voff)[_i]), (LAS unsigned*)(lds + (bufoff) + ldsw + _i * 8192), 16, 0, 0); } while (0)
; #define PG8_LDA(dst, b, h) do { _Pragma("unroll") for (int m = 0; m < 4; ++m) _Pragma("unroll") for (int k = 0; k < 2; ++k) dst[m][k] = *(const LAS bf16x8*)(lds + PG8_SA(b, h) + aoff + m * 2048 + k * 1024); } while (0)
; #define PG8_MMA(ai, bj, At, Bt) do { __builtin_amdgcn_s_setprio(1); _Pragma("unroll") for (int m = 0; m < 4; ++m) _Pragma("unroll") for (int n = 0; n < 2; ++n) _Pragma("unroll") for (int k = 0; k < 2; ++k) \
;         acc[ai][bj][m][n] = __builtin_amdgcn_mfma_f32_16x16x32_bf16(Bt[n][k], At[m][k], acc[ai][bj][m][n], 0, 0, 0); __builtin_amdgcn_s_setprio(0); } while (0)
; #define PG8_WAIT_V(n) asm volatile("s_waitcnt vmcnt(" #n ")" ::: "memory")
; #define PG8_WAIT_L(n) asm volatile("s_waitcnt lgkmcnt(" #n ")" ::: "memory")
; #define PG8_BAR __builtin_amdgcn_s_barrier()
; #define PG8_SCHED __builtin_amdgcn_sched_barrier(0)
; template <class Epi, class Sched>
; __device__ __forceinline__ void gemm_phase(LAS unsigned char* lds, const Gemm g, const Sched& S, const Epi& E) {
;     ...
;             PG8_LDA(At, 1, 1); PG8_STAGE(PG8_SA(1, 0), a3, voffA);
;             PG8_BAR; PG8_WAIT_L(0); PG8_MMA(1, 0, At, B0); PG8_BAR; PG8_SCHED;
;             PG8_STAGE(PG8_SB(1, 1), b3 + hstep, voffB);
;             PG8_WAIT_V(6); PG8_BAR; PG8_MMA(1, 1, At, B1); PG8_BAR;
;         }
	s_waitcnt lgkmcnt(0)
	s_setprio 1
	s_waitcnt lgkmcnt(0)
	v_mfma_f32_16x16x32_bf16 v[120:123], v[202:205], v[166:169], v[120:123]
	v_mfma_f32_16x16x32_bf16 v[112:115], v[210:213], v[166:169], v[112:115]
	v_mfma_f32_16x16x32_bf16 v[104:107], v[202:205], v[174:177], v[104:107]
	v_mfma_f32_16x16x32_bf16 v[96:99], v[210:213], v[174:177], v[96:99]
	v_mfma_f32_16x16x32_bf16 v[88:91], v[202:205], v[182:185], v[88:91]
	v_mfma_f32_16x16x32_bf16 v[80:83], v[210:213], v[182:185], v[80:83]
	v_mfma_f32_16x16x32_bf16 v[72:75], v[202:205], v[190:193], v[72:75]
	v_mfma_f32_16x16x32_bf16 v[64:67], v[210:213], v[190:193], v[64:67]
	v_mfma_f32_16x16x32_bf16 v[120:123], v[206:209], v[170:173], v[120:123]
	v_mfma_f32_16x16x32_bf16 v[112:115], v[214:217], v[170:173], v[112:115]
	v_mfma_f32_16x16x32_bf16 v[104:107], v[206:209], v[178:181], v[104:107]
	v_mfma_f32_16x16x32_bf16 v[96:99], v[214:217], v[178:181], v[96:99]
	v_mfma_f32_16x16x32_bf16 v[88:91], v[206:209], v[186:189], v[88:91]
	v_mfma_f32_16x16x32_bf16 v[80:83], v[214:217], v[186:189], v[80:83]
	v_mfma_f32_16x16x32_bf16 v[72:75], v[206:209], v[194:197], v[72:75]
	v_mfma_f32_16x16x32_bf16 v[64:67], v[214:217], v[194:197], v[64:67]
	s_setprio 0
	s_mov_b32 m0, s36
	v_lshl_add_u64 v[198:199], v[220:221], 0, s[0:1]
	s_barrier
	ds_read_b128 v[166:169], v148 offset:49152
	ds_read_b128 v[170:173], v148 offset:50176
	ds_read_b128 v[174:177], v148 offset:51200
	ds_read_b128 v[178:181], v148 offset:52224
	ds_read_b128 v[182:185], v148 offset:53248
	ds_read_b128 v[186:189], v148 offset:54272
	ds_read_b128 v[190:193], v148 offset:55296
	ds_read_b128 v[194:197], v148 offset:56320
	global_load_lds_dwordx4 v[198:199], off
	v_lshl_add_u64 v[198:199], v[222:223], 0, s[0:1]
	s_mov_b32 m0, s37
	s_nop 0
	global_load_lds_dwordx4 v[198:199], off
	s_barrier
	s_waitcnt lgkmcnt(0)
	s_setprio 1
	s_waitcnt lgkmcnt(0)
	v_mfma_f32_16x16x32_bf16 v[60:63], v[150:153], v[166:169], v[60:63]
	v_mfma_f32_16x16x32_bf16 v[56:59], v[158:161], v[166:169], v[56:59]
	v_mfma_f32_16x16x32_bf16 v[44:47], v[150:153], v[174:177], v[44:47]
	v_mfma_f32_16x16x32_bf16 v[40:43], v[158:161], v[174:177], v[40:43]
	v_mfma_f32_16x16x32_bf16 v[28:31], v[150:153], v[182:185], v[28:31]
	v_mfma_f32_16x16x32_bf16 v[24:27], v[158:161], v[182:185], v[24:27]
	v_mfma_f32_16x16x32_bf16 v[12:15], v[150:153], v[190:193], v[12:15]
	v_mfma_f32_16x16x32_bf16 v[8:11], v[158:161], v[190:193], v[8:11]
	v_mfma_f32_16x16x32_bf16 v[60:63], v[154:157], v[170:173], v[60:63]
	v_mfma_f32_16x16x32_bf16 v[56:59], v[162:165], v[170:173], v[56:59]
	v_mfma_f32_16x16x32_bf16 v[44:47], v[154:157], v[178:181], v[44:47]
	v_mfma_f32_16x16x32_bf16 v[40:43], v[162:165], v[178:181], v[40:43]
	v_mfma_f32_16x16x32_bf16 v[28:31], v[154:157], v[186:189], v[28:31]
	v_mfma_f32_16x16x32_bf16 v[24:27], v[162:165], v[186:189], v[24:27]
	v_mfma_f32_16x16x32_bf16 v[12:15], v[154:157], v[194:197], v[12:15]
	v_mfma_f32_16x16x32_bf16 v[8:11], v[162:165], v[194:197], v[8:11]
	s_setprio 0
	s_barrier
	s_add_u32 s16, s18, 0x40080
	s_addc_u32 s17, s19, 0
	s_add_i32 s18, s21, s25
	v_lshl_add_u64 v[150:151], s[16:17], 0, v[132:133]
	s_mov_b32 m0, s18
	s_nop 0
	global_load_lds_dwordx4 v[150:151], off
	v_lshl_add_u64 v[150:151], s[16:17], 0, v[128:129]
	s_add_i32 m0, s18, 0x2000
	s_nop 0
	global_load_lds_dwordx4 v[150:151], off
	s_waitcnt vmcnt(6)
	s_barrier
	s_setprio 1
	v_mfma_f32_16x16x32_bf16 v[52:55], v[202:205], v[166:169], v[52:55]
	v_mfma_f32_16x16x32_bf16 v[48:51], v[210:213], v[166:169], v[48:51]
	v_mfma_f32_16x16x32_bf16 v[36:39], v[202:205], v[174:177], v[36:39]
	v_mfma_f32_16x16x32_bf16 v[32:35], v[210:213], v[174:177], v[32:35]
	v_mfma_f32_16x16x32_bf16 v[20:23], v[202:205], v[182:185], v[20:23]
	v_mfma_f32_16x16x32_bf16 v[16:19], v[210:213], v[182:185], v[16:19]
	v_mfma_f32_16x16x32_bf16 v[4:7], v[202:205], v[190:193], v[4:7]
	v_mfma_f32_16x16x32_bf16 v[0:3], v[210:213], v[190:193], v[0:3]
	v_mfma_f32_16x16x32_bf16 v[52:55], v[206:209], v[170:173], v[52:55]
	v_mfma_f32_16x16x32_bf16 v[48:51], v[214:217], v[170:173], v[48:51]
	v_mfma_f32_16x16x32_bf16 v[36:39], v[206:209], v[178:181], v[36:39]
	v_mfma_f32_16x16x32_bf16 v[32:35], v[214:217], v[178:181], v[32:35]
	v_mfma_f32_16x16x32_bf16 v[20:23], v[206:209], v[186:189], v[20:23]
	v_mfma_f32_16x16x32_bf16 v[16:19], v[214:217], v[186:189], v[16:19]
	v_mfma_f32_16x16x32_bf16 v[4:7], v[206:209], v[194:197], v[4:7]
	v_mfma_f32_16x16x32_bf16 v[0:3], v[214:217], v[194:197], v[0:3]
	s_setprio 0
	s_add_i32 s48, s48, 2
	s_add_u32 s14, s14, 0x100
	s_addc_u32 s15, s15, 0
	s_add_u32 s46, s46, 0x100
	s_addc_u32 s47, s47, 0
	s_cmp_gt_u32 s48, 13
	s_barrier

; #define PG8_STAGE(bufoff, gbase, voff) do { _Pragma("unroll") for (int _i = 0; _i < 2; ++_i) \
;         __builtin_amdgcn_global_load_lds((const unsigned*)((const char*)(gbase) + (voff)[_i]), (LAS unsigned*)(lds + (bufoff) + ldsw + _i * 8192), 16, 0, 0); } while (0)
; #define PG8_LDA(dst, b, h) do { _Pragma("unroll") for (int m = 0; m < 4; ++m) _Pragma("unroll") for (int k = 0; k < 2; ++k) dst[m][k] = *(const LAS bf16x8*)(lds + PG8_SA(b, h) + aoff + m * 2048 + k * 1024); } while (0)
; #define PG8_LDB(dst, b, h) do { _Pragma("unroll") for (int n = 0; n < 2; ++n) _Pragma("unroll") for (int k = 0; k < 2; ++k) dst[n][k] = *(const LAS bf16x8*)(lds + PG8_SB(b, h) + boff + n * 2048 + k * 1024); } while (0)
; #define PG8_MMA(ai, bj, At, Bt) do { __builtin_amdgcn_s_setprio(1); _Pragma("unroll") for (int m = 0; m < 4; ++m) _Pragma("unroll") for (int n = 0; n < 2; ++n) _Pragma("unroll") for (int k = 0; k < 2; ++k) \
;         acc[ai][bj][m][n] = __builtin_amdgcn_mfma_f32_16x16x32_bf16(Bt[n][k], At[m][k], acc[ai][bj][m][n], 0, 0, 0); __builtin_amdgcn_s_setprio(0); } while (0)
; #define PG8_WAIT_V(n) asm volatile("s_waitcnt vmcnt(" #n ")" ::: "memory")
; #define PG8_WAIT_L(n) asm volatile("s_waitcnt lgkmcnt(" #n ")" ::: "memory")
; template <class Epi, class Sched>
; __device__ __forceinline__ void gemm_phase(LAS unsigned char* lds, const Gemm g, const Sched& S, const Epi& E) {
;     ...
;         for (int t = 0; t < nt; t += 2) {
;             const bool last = (t == nt - 2);
;             const char* a1 = cA + (size_t)(t + 1) * kstep;
;             const char* a2 = last ? nA : cA + (size_t)(t + 2) * kstep; const char* b2 = last ? nB : cB + (size_t)(t + 2) * kstep;
;             const char* a3 = a2 + kstep; const char* b3 = b2 + kstep;
;             PG8_LDB(B0, 0, 0); PG8_SCHED; PG8_LDA(At, 0, 0); PG8_STAGE(PG8_SA(1, 1), a1 + hstep, voffA);
;             PG8_WAIT_L(8); PG8_BAR; PG8_WAIT_L(0); PG8_MMA(0, 0, At, B0); PG8_BAR; PG8_SCHED;
;             PG8_LDB(B1, 0, 1); PG8_STAGE(PG8_SB(0, 0), b2, voffB);
;             PG8_BAR; PG8_WAIT_L(0); PG8_MMA(0, 1, At, B1); PG8_BAR;
;             PG8_LDA(At, 0, 1); PG8_STAGE(PG8_SA(0, 0), a2, voffA);
;             PG8_BAR; PG8_WAIT_L(0); PG8_MMA(1, 0, At, B0); PG8_BAR; PG8_SCHED;
;             PG8_STAGE(PG8_SB(0, 1), b2 + hstep, voffB);
;             PG8_WAIT_V(6); PG8_BAR; PG8_MMA(1, 1, At, B1); PG8_BAR;
.LBB0_304:
	s_add_u32 s0, s28, 0x100
	s_addc_u32 s67, s29, 0
	s_mov_b32 s68, -2
	ds_read_b128 v[144:147], v165
	ds_read_b128 v[148:151], v165 offset:1024
	ds_read_b128 v[152:155], v165 offset:2048
	ds_read_b128 v[156:159], v165 offset:3072
	s_add_u32 s28, s26, 0x100
	s_addc_u32 s29, s27, 0
	s_cmp_eq_u32 s68, 40
	s_cselect_b32 s37, s5, s29
	s_cselect_b32 s36, s4, s28
	s_cselect_b32 s35, s7, s67
	s_cselect_b32 s34, s6, s0
	v_lshl_add_u64 v[160:161], s[26:27], 0, v[136:137]
	s_add_i32 m0, s42, 0xc000
	ds_read_b128 v[168:171], v166
	ds_read_b128 v[172:175], v166 offset:1024
	ds_read_b128 v[176:179], v166 offset:2048
	ds_read_b128 v[180:183], v166 offset:3072
	ds_read_b128 v[184:187], v166 offset:4096
	ds_read_b128 v[188:191], v166 offset:5120
	ds_read_b128 v[192:195], v166 offset:6144
	ds_read_b128 v[196:199], v166 offset:7168
	global_load_lds_dwordx4 v[160:161], off
	v_lshl_add_u64 v[160:161], s[26:27], 0, v[138:139]
	s_add_i32 m0, s42, 0xe000
	s_nop 0
	global_load_lds_dwordx4 v[160:161], off
	s_waitcnt lgkmcnt(8)
	s_barrier
	s_waitcnt lgkmcnt(0)
	s_setprio 1
	s_waitcnt lgkmcnt(0)
	v_mfma_f32_16x16x32_bf16 v[124:127], v[144:147], v[168:171], 0
	v_mfma_f32_16x16x32_bf16 v[120:123], v[152:155], v[168:171], 0
	v_mfma_f32_16x16x32_bf16 v[116:119], v[144:147], v[176:179], 0
	v_mfma_f32_16x16x32_bf16 v[104:107], v[152:155], v[176:179], 0
	v_mfma_f32_16x16x32_bf16 v[96:99], v[144:147], v[184:187], 0
	v_mfma_f32_16x16x32_bf16 v[88:91], v[152:155], v[184:187], 0
	v_mfma_f32_16x16x32_bf16 v[80:83], v[144:147], v[192:195], 0
	v_mfma_f32_16x16x32_bf16 v[72:75], v[152:155], v[192:195], 0
	v_mfma_f32_16x16x32_bf16 v[124:127], v[148:151], v[172:175], v[124:127]
	v_mfma_f32_16x16x32_bf16 v[120:123], v[156:159], v[172:175], v[120:123]
	v_mfma_f32_16x16x32_bf16 v[116:119], v[148:151], v[180:183], v[116:119]
	v_mfma_f32_16x16x32_bf16 v[104:107], v[156:159], v[180:183], v[104:107]
	v_mfma_f32_16x16x32_bf16 v[96:99], v[148:151], v[188:191], v[96:99]
	v_mfma_f32_16x16x32_bf16 v[88:91], v[156:159], v[188:191], v[88:91]
	v_mfma_f32_16x16x32_bf16 v[80:83], v[148:151], v[196:199], v[80:83]
	v_mfma_f32_16x16x32_bf16 v[72:75], v[156:159], v[196:199], v[72:75]
	s_setprio 0
	s_barrier
	s_add_i32 s16, s58, s40
	v_lshl_add_u64 v[160:161], s[34:35], 0, v[132:133]
	s_mov_b32 m0, s16
	ds_read_b128 v[202:205], v167
	ds_read_b128 v[206:209], v167 offset:1024
	ds_read_b128 v[210:213], v167 offset:2048
	ds_read_b128 v[214:217], v167 offset:3072
	global_load_lds_dwordx4 v[160:161], off
	v_lshl_add_u64 v[218:219], s[34:35], 0, v[128:129]
	s_add_i32 m0, s16, 0x2000
	s_nop 0
	global_load_lds_dwordx4 v[218:219], off
	s_barrier
	s_waitcnt lgkmcnt(0)
	s_setprio 1
	s_waitcnt lgkmcnt(0)
	v_mfma_f32_16x16x32_bf16 v[112:115], v[202:205], v[168:171], 0
	v_mfma_f32_16x16x32_bf16 v[108:111], v[210:213], v[168:171], 0
	v_mfma_f32_16x16x32_bf16 v[100:103], v[202:205], v[176:179], 0
	v_mfma_f32_16x16x32_bf16 v[92:95], v[210:213], v[176:179], 0
	v_mfma_f32_16x16x32_bf16 v[84:87], v[202:205], v[184:187], 0
	v_mfma_f32_16x16x32_bf16 v[76:79], v[210:213], v[184:187], 0
	v_mfma_f32_16x16x32_bf16 v[68:71], v[202:205], v[192:195], 0
	v_mfma_f32_16x16x32_bf16 v[64:67], v[210:213], v[192:195], 0
	v_mfma_f32_16x16x32_bf16 v[112:115], v[206:209], v[172:175], v[112:115]
	v_mfma_f32_16x16x32_bf16 v[108:111], v[214:217], v[172:175], v[108:111]
	v_mfma_f32_16x16x32_bf16 v[100:103], v[206:209], v[180:183], v[100:103]
	v_mfma_f32_16x16x32_bf16 v[92:95], v[214:217], v[180:183], v[92:95]
	v_mfma_f32_16x16x32_bf16 v[84:87], v[206:209], v[188:191], v[84:87]
	v_mfma_f32_16x16x32_bf16 v[76:79], v[214:217], v[188:191], v[76:79]
	v_mfma_f32_16x16x32_bf16 v[68:71], v[206:209], v[196:199], v[68:71]
	v_mfma_f32_16x16x32_bf16 v[64:67], v[214:217], v[196:199], v[64:67]
	s_setprio 0
	s_mov_b32 m0, s42
	v_lshl_add_u64 v[220:221], s[36:37], 0, v[134:135]
	s_barrier
	ds_read_b128 v[168:171], v166 offset:16384
	ds_read_b128 v[172:175], v166 offset:17408
	ds_read_b128 v[176:179], v166 offset:18432
	ds_read_b128 v[180:183], v166 offset:19456
	ds_read_b128 v[184:187], v166 offset:20480
	ds_read_b128 v[188:191], v166 offset:21504
	ds_read_b128 v[192:195], v166 offset:22528
	ds_read_b128 v[196:199], v166 offset:23552
	global_load_lds_dwordx4 v[220:221], off
	v_lshl_add_u64 v[222:223], s[36:37], 0, v[130:131]
	s_mov_b32 m0, s43
	s_nop 0
	global_load_lds_dwordx4 v[222:223], off
	s_barrier
	s_waitcnt lgkmcnt(0)
	s_setprio 1
	s_waitcnt lgkmcnt(0)
	v_mfma_f32_16x16x32_bf16 v[60:63], v[144:147], v[168:171], 0
	v_mfma_f32_16x16x32_bf16 v[56:59], v[152:155], v[168:171], 0
	v_mfma_f32_16x16x32_bf16 v[48:51], v[144:147], v[176:179], 0
	v_mfma_f32_16x16x32_bf16 v[40:43], v[152:155], v[176:179], 0
	v_mfma_f32_16x16x32_bf16 v[32:35], v[144:147], v[184:187], 0
	v_mfma_f32_16x16x32_bf16 v[24:27], v[152:155], v[184:187], 0
	v_mfma_f32_16x16x32_bf16 v[16:19], v[144:147], v[192:195], 0
	v_mfma_f32_16x16x32_bf16 v[8:11], v[152:155], v[192:195], 0
	v_mfma_f32_16x16x32_bf16 v[60:63], v[148:151], v[172:175], v[60:63]
	v_mfma_f32_16x16x32_bf16 v[56:59], v[156:159], v[172:175], v[56:59]
	v_mfma_f32_16x16x32_bf16 v[48:51], v[148:151], v[180:183], v[48:51]
	v_mfma_f32_16x16x32_bf16 v[40:43], v[156:159], v[180:183], v[40:43]
	v_mfma_f32_16x16x32_bf16 v[32:35], v[148:151], v[188:191], v[32:35]
	v_mfma_f32_16x16x32_bf16 v[24:27], v[156:159], v[188:191], v[24:27]
	v_mfma_f32_16x16x32_bf16 v[16:19], v[148:151], v[196:199], v[16:19]
	v_mfma_f32_16x16x32_bf16 v[8:11], v[156:159], v[196:199], v[8:11]
	s_setprio 0
	s_barrier
; #define PG8_STAGE(bufoff, gbase, voff) do { _Pragma("unroll") for (int _i = 0; _i < 2; ++_i) \
;         __builtin_amdgcn_global_load_lds((const unsigned*)((const char*)(gbase) + (voff)[_i]), (LAS unsigned*)(lds + (bufoff) + ldsw + _i * 8192), 16, 0, 0); } while (0)
; #define PG8_LDA(dst, b, h) do { _Pragma("unroll") for (int m = 0; m < 4; ++m) _Pragma("unroll") for (int k = 0; k < 2; ++k) dst[m][k] = *(const LAS bf16x8*)(lds + PG8_SA(b, h) + aoff + m * 2048 + k * 1024); } while (0)
; #define PG8_LDB(dst, b, h) do { _Pragma("unroll") for (int n = 0; n < 2; ++n) _Pragma("unroll") for (int k = 0; k < 2; ++k) dst[n][k] = *(const LAS bf16x8*)(lds + PG8_SB(b, h) + boff + n * 2048 + k * 1024); } while (0)
; #define PG8_MMA(ai, bj, At, Bt) do { __builtin_amdgcn_s_setprio(1); _Pragma("unroll") for (int m = 0; m < 4; ++m) _Pragma("unroll") for (int n = 0; n < 2; ++n) _Pragma("unroll") for (int k = 0; k < 2; ++k) \
;         acc[ai][bj][m][n] = __builtin_amdgcn_mfma_f32_16x16x32_bf16(Bt[n][k], At[m][k], acc[ai][bj][m][n], 0, 0, 0); __builtin_amdgcn_s_setprio(0); } while (0)
; #define PG8_WAIT_V(n) asm volatile("s_waitcnt vmcnt(" #n ")" ::: "memory")
; #define PG8_WAIT_L(n) asm volatile("s_waitcnt lgkmcnt(" #n ")" ::: "memory")
; #define PG8_BAR __builtin_amdgcn_s_barrier()
; #define PG8_SCHED __builtin_amdgcn_sched_barrier(0)
; template <class Epi, class Sched>
; __device__ __forceinline__ void gemm_phase(LAS unsigned char* lds, const Gemm g, const Sched& S, const Epi& E) {
;     ...
;             PG8_STAGE(PG8_SB(0, 1), b2 + hstep, voffB);
;             PG8_WAIT_V(6); PG8_BAR; PG8_MMA(1, 1, At, B1); PG8_BAR;
;             PG8_LDB(B0, 1, 0); PG8_SCHED; PG8_LDA(At, 1, 0); PG8_STAGE(PG8_SA(0, 1), a2 + hstep, voffA);
;             PG8_WAIT_L(8); PG8_BAR; PG8_WAIT_L(0); PG8_MMA(0, 0, At, B0); PG8_BAR; PG8_SCHED;
;             PG8_LDB(B1, 1, 1); PG8_STAGE(PG8_SB(1, 0), b3, voffB);
	s_add_u32 s16, s34, 0xb0000
	s_addc_u32 s17, s35, 0
	s_add_i32 s20, s59, s40
	v_lshl_add_u64 v[144:145], s[16:17], 0, v[132:133]
	s_mov_b32 m0, s20
	s_nop 0
	global_load_lds_dwordx4 v[144:145], off
	v_lshl_add_u64 v[144:145], s[16:17], 0, v[128:129]
	s_add_i32 m0, s20, 0x2000
	s_nop 0
	global_load_lds_dwordx4 v[144:145], off
	s_waitcnt vmcnt(6)
	s_barrier
	s_setprio 1
	v_mfma_f32_16x16x32_bf16 v[52:55], v[202:205], v[168:171], 0
	v_mfma_f32_16x16x32_bf16 v[44:47], v[210:213], v[168:171], 0
	v_mfma_f32_16x16x32_bf16 v[36:39], v[202:205], v[176:179], 0
	v_mfma_f32_16x16x32_bf16 v[28:31], v[210:213], v[176:179], 0
	v_mfma_f32_16x16x32_bf16 v[20:23], v[202:205], v[184:187], 0
	v_mfma_f32_16x16x32_bf16 v[12:15], v[210:213], v[184:187], 0
	v_mfma_f32_16x16x32_bf16 v[4:7], v[202:205], v[192:195], 0
	v_mfma_f32_16x16x32_bf16 v[0:3], v[210:213], v[192:195], 0
	v_mfma_f32_16x16x32_bf16 v[52:55], v[206:209], v[172:175], v[52:55]
	v_mfma_f32_16x16x32_bf16 v[44:47], v[214:217], v[172:175], v[44:47]
	v_mfma_f32_16x16x32_bf16 v[36:39], v[206:209], v[180:183], v[36:39]
	v_mfma_f32_16x16x32_bf16 v[28:31], v[214:217], v[180:183], v[28:31]
	v_mfma_f32_16x16x32_bf16 v[20:23], v[206:209], v[188:191], v[20:23]
	v_mfma_f32_16x16x32_bf16 v[12:15], v[214:217], v[188:191], v[12:15]
	v_mfma_f32_16x16x32_bf16 v[4:7], v[206:209], v[196:199], v[4:7]
	v_mfma_f32_16x16x32_bf16 v[0:3], v[214:217], v[196:199], v[0:3]
	s_setprio 0
	s_add_i32 s20, 0, 0x18000
	v_add_u32_e32 v156, s20, v164
	s_barrier
	ds_read_b128 v[144:147], v156
	ds_read_b128 v[148:151], v156 offset:1024
	ds_read_b128 v[152:155], v156 offset:2048
	ds_read_b128 v[156:159], v156 offset:3072
	s_add_u32 s16, s36, 0xb0000
	s_addc_u32 s17, s37, 0
	s_mov_b32 m0, s44
	v_lshl_add_u64 v[202:203], s[16:17], 0, v[134:135]
	ds_read_b128 v[168:171], v166 offset:32768
	ds_read_b128 v[172:175], v166 offset:33792
	ds_read_b128 v[176:179], v166 offset:34816
	ds_read_b128 v[180:183], v166 offset:35840
	ds_read_b128 v[184:187], v166 offset:36864
	ds_read_b128 v[188:191], v166 offset:37888
	ds_read_b128 v[192:195], v166 offset:38912
	ds_read_b128 v[196:199], v166 offset:39936
	global_load_lds_dwordx4 v[202:203], off
	v_lshl_add_u64 v[202:203], s[16:17], 0, v[130:131]
	s_mov_b32 m0, s45
	s_nop 0
	global_load_lds_dwordx4 v[202:203], off
	s_waitcnt lgkmcnt(8)
	s_barrier
	s_waitcnt lgkmcnt(0)
	s_setprio 1
	s_waitcnt lgkmcnt(0)
	v_mfma_f32_16x16x32_bf16 v[124:127], v[144:147], v[168:171], v[124:127]
	v_mfma_f32_16x16x32_bf16 v[120:123], v[152:155], v[168:171], v[120:123]
	v_mfma_f32_16x16x32_bf16 v[116:119], v[144:147], v[176:179], v[116:119]
	v_mfma_f32_16x16x32_bf16 v[104:107], v[152:155], v[176:179], v[104:107]
	v_mfma_f32_16x16x32_bf16 v[96:99], v[144:147], v[184:187], v[96:99]
	v_mfma_f32_16x16x32_bf16 v[88:91], v[152:155], v[184:187], v[88:91]
	v_mfma_f32_16x16x32_bf16 v[80:83], v[144:147], v[192:195], v[80:83]
	v_mfma_f32_16x16x32_bf16 v[72:75], v[152:155], v[192:195], v[72:75]
	v_mfma_f32_16x16x32_bf16 v[124:127], v[148:151], v[172:175], v[124:127]
	v_mfma_f32_16x16x32_bf16 v[120:123], v[156:159], v[172:175], v[120:123]
	v_mfma_f32_16x16x32_bf16 v[116:119], v[148:151], v[180:183], v[116:119]
	v_mfma_f32_16x16x32_bf16 v[104:107], v[156:159], v[180:183], v[104:107]
	v_mfma_f32_16x16x32_bf16 v[96:99], v[148:151], v[188:191], v[96:99]
	v_mfma_f32_16x16x32_bf16 v[88:91], v[156:159], v[188:191], v[88:91]
	v_mfma_f32_16x16x32_bf16 v[80:83], v[148:151], v[196:199], v[80:83]
	v_mfma_f32_16x16x32_bf16 v[72:75], v[156:159], v[196:199], v[72:75]
	s_setprio 0
	s_barrier
	s_add_i32 s21, 0, 0x1c000
	s_add_i32 s16, s20, s40
	v_add_u32_e32 v214, s21, v164
	v_lshl_add_u64 v[160:161], v[160:161], 0, s[8:9]
	s_mov_b32 m0, s16
	ds_read_b128 v[202:205], v214
	ds_read_b128 v[206:209], v214 offset:1024
	ds_read_b128 v[210:213], v214 offset:2048
	ds_read_b128 v[214:217], v214 offset:3072
	global_load_lds_dwordx4 v[160:161], off
	v_lshl_add_u64 v[160:161], v[218:219], 0, s[8:9]
	s_add_i32 m0, s16, 0x2000
	s_nop 0
	global_load_lds_dwordx4 v[160:161], off
	s_barrier
; #define PG8_STAGE(bufoff, gbase, voff) do { _Pragma("unroll") for (int _i = 0; _i < 2; ++_i) \
;         __builtin_amdgcn_global_load_lds((const unsigned*)((const char*)(gbase) + (voff)[_i]), (LAS unsigned*)(lds + (bufoff) + ldsw + _i * 8192), 16, 0, 0); } while (0)
; #define PG8_LDA(dst, b, h) do { _Pragma("unroll") for (int m = 0; m < 4; ++m) _Pragma("unroll") for (int k = 0; k < 2; ++k) dst[m][k] = *(const LAS bf16x8*)(lds + PG8_SA(b, h) + aoff + m * 2048 + k * 1024); } while (0)
; #define PG8_MMA(ai, bj, At, Bt) do { __builtin_amdgcn_s_setprio(1); _Pragma("unroll") for (int m = 0; m < 4; ++m) _Pragma("unroll") for (int n = 0; n < 2; ++n) _Pragma("unroll") for (int k = 0; k < 2; ++k) \
;         acc[ai][bj][m][n] = __builtin_amdgcn_mfma_f32_16x16x32_bf16(Bt[n][k], At[m][k], acc[ai][bj][m][n], 0, 0, 0); __builtin_amdgcn_s_setprio(0); } while (0)
; #define PG8_WAIT_V(n) asm volatile("s_waitcnt vmcnt(" #n ")" ::: "memory")
; #define PG8_WAIT_L(n) asm volatile("s_waitcnt lgkmcnt(" #n ")" ::: "memory")
; #define PG8_BAR __builtin_amdgcn_s_barrier()
; #define PG8_SCHED __builtin_amdgcn_sched_barrier(0)
; template <class Epi, class Sched>
; __device__ __forceinline__ void gemm_phase(LAS unsigned char* lds, const Gemm g, const Sched& S, const Epi& E) {
;     ...
;             PG8_LDA(At, 1, 1); PG8_STAGE(PG8_SA(1, 0), a3, voffA);
;             PG8_BAR; PG8_WAIT_L(0); PG8_MMA(1, 0, At, B0); PG8_BAR; PG8_SCHED;
;             PG8_STAGE(PG8_SB(1, 1), b3 + hstep, voffB);
;             PG8_WAIT_V(6); PG8_BAR; PG8_MMA(1, 1, At, B1); PG8_BAR;
;         }
	s_waitcnt lgkmcnt(0)
	s_setprio 1
	s_waitcnt lgkmcnt(0)
	v_mfma_f32_16x16x32_bf16 v[112:115], v[202:205], v[168:171], v[112:115]
	v_mfma_f32_16x16x32_bf16 v[108:111], v[210:213], v[168:171], v[108:111]
	v_mfma_f32_16x16x32_bf16 v[100:103], v[202:205], v[176:179], v[100:103]
	v_mfma_f32_16x16x32_bf16 v[92:95], v[210:213], v[176:179], v[92:95]
	v_mfma_f32_16x16x32_bf16 v[84:87], v[202:205], v[184:187], v[84:87]
	v_mfma_f32_16x16x32_bf16 v[76:79], v[210:213], v[184:187], v[76:79]
	v_mfma_f32_16x16x32_bf16 v[68:71], v[202:205], v[192:195], v[68:71]
	v_mfma_f32_16x16x32_bf16 v[64:67], v[210:213], v[192:195], v[64:67]
	v_mfma_f32_16x16x32_bf16 v[112:115], v[206:209], v[172:175], v[112:115]
	v_mfma_f32_16x16x32_bf16 v[108:111], v[214:217], v[172:175], v[108:111]
	v_mfma_f32_16x16x32_bf16 v[100:103], v[206:209], v[180:183], v[100:103]
	v_mfma_f32_16x16x32_bf16 v[92:95], v[214:217], v[180:183], v[92:95]
	v_mfma_f32_16x16x32_bf16 v[84:87], v[206:209], v[188:191], v[84:87]
	v_mfma_f32_16x16x32_bf16 v[76:79], v[214:217], v[188:191], v[76:79]
	v_mfma_f32_16x16x32_bf16 v[68:71], v[206:209], v[196:199], v[68:71]
	v_mfma_f32_16x16x32_bf16 v[64:67], v[214:217], v[196:199], v[64:67]
	s_setprio 0
	s_mov_b32 m0, s52
	v_lshl_add_u64 v[160:161], v[220:221], 0, s[8:9]
	s_barrier
	ds_read_b128 v[168:171], v166 offset:49152
	ds_read_b128 v[172:175], v166 offset:50176
	ds_read_b128 v[176:179], v166 offset:51200
	ds_read_b128 v[180:183], v166 offset:52224
	ds_read_b128 v[184:187], v166 offset:53248
	ds_read_b128 v[188:191], v166 offset:54272
	ds_read_b128 v[192:195], v166 offset:55296
	ds_read_b128 v[196:199], v166 offset:56320
	global_load_lds_dwordx4 v[160:161], off
	v_lshl_add_u64 v[160:161], v[222:223], 0, s[8:9]
	s_mov_b32 m0, s53
	s_nop 0
	global_load_lds_dwordx4 v[160:161], off
	s_barrier
	s_waitcnt lgkmcnt(0)
	s_setprio 1
	s_waitcnt lgkmcnt(0)
	v_mfma_f32_16x16x32_bf16 v[60:63], v[144:147], v[168:171], v[60:63]
	v_mfma_f32_16x16x32_bf16 v[56:59], v[152:155], v[168:171], v[56:59]
	v_mfma_f32_16x16x32_bf16 v[48:51], v[144:147], v[176:179], v[48:51]
	v_mfma_f32_16x16x32_bf16 v[40:43], v[152:155], v[176:179], v[40:43]
	v_mfma_f32_16x16x32_bf16 v[32:35], v[144:147], v[184:187], v[32:35]
	v_mfma_f32_16x16x32_bf16 v[24:27], v[152:155], v[184:187], v[24:27]
	v_mfma_f32_16x16x32_bf16 v[16:19], v[144:147], v[192:195], v[16:19]
	v_mfma_f32_16x16x32_bf16 v[8:11], v[152:155], v[192:195], v[8:11]
	v_mfma_f32_16x16x32_bf16 v[60:63], v[148:151], v[172:175], v[60:63]
	v_mfma_f32_16x16x32_bf16 v[56:59], v[156:159], v[172:175], v[56:59]
	v_mfma_f32_16x16x32_bf16 v[48:51], v[148:151], v[180:183], v[48:51]
	v_mfma_f32_16x16x32_bf16 v[40:43], v[156:159], v[180:183], v[40:43]
	v_mfma_f32_16x16x32_bf16 v[32:35], v[148:151], v[188:191], v[32:35]
	v_mfma_f32_16x16x32_bf16 v[24:27], v[156:159], v[188:191], v[24:27]
	v_mfma_f32_16x16x32_bf16 v[16:19], v[148:151], v[196:199], v[16:19]
	v_mfma_f32_16x16x32_bf16 v[8:11], v[156:159], v[196:199], v[8:11]
	s_setprio 0
	s_barrier
	s_add_u32 s16, s34, 0xb0080
	s_addc_u32 s17, s35, 0
	s_add_i32 s20, s21, s40
	v_lshl_add_u64 v[144:145], s[16:17], 0, v[132:133]
	s_mov_b32 m0, s20
	s_nop 0
	global_load_lds_dwordx4 v[144:145], off
	v_lshl_add_u64 v[144:145], s[16:17], 0, v[128:129]
	s_add_i32 m0, s20, 0x2000
	s_nop 0
	global_load_lds_dwordx4 v[144:145], off
	s_waitcnt vmcnt(6)
	s_barrier
	s_setprio 1
	v_mfma_f32_16x16x32_bf16 v[52:55], v[202:205], v[168:171], v[52:55]
	v_mfma_f32_16x16x32_bf16 v[44:47], v[210:213], v[168:171], v[44:47]
	v_mfma_f32_16x16x32_bf16 v[36:39], v[202:205], v[176:179], v[36:39]
	v_mfma_f32_16x16x32_bf16 v[28:31], v[210:213], v[176:179], v[28:31]
	v_mfma_f32_16x16x32_bf16 v[20:23], v[202:205], v[184:187], v[20:23]
	v_mfma_f32_16x16x32_bf16 v[12:15], v[210:213], v[184:187], v[12:15]
	v_mfma_f32_16x16x32_bf16 v[4:7], v[202:205], v[192:195], v[4:7]
	v_mfma_f32_16x16x32_bf16 v[0:3], v[210:213], v[192:195], v[0:3]
	v_mfma_f32_16x16x32_bf16 v[52:55], v[206:209], v[172:175], v[52:55]
	v_mfma_f32_16x16x32_bf16 v[44:47], v[214:217], v[172:175], v[44:47]
	v_mfma_f32_16x16x32_bf16 v[36:39], v[206:209], v[180:183], v[36:39]
	v_mfma_f32_16x16x32_bf16 v[28:31], v[214:217], v[180:183], v[28:31]
	v_mfma_f32_16x16x32_bf16 v[20:23], v[206:209], v[188:191], v[20:23]
	v_mfma_f32_16x16x32_bf16 v[12:15], v[214:217], v[188:191], v[12:15]
	v_mfma_f32_16x16x32_bf16 v[4:7], v[206:209], v[196:199], v[4:7]
	v_mfma_f32_16x16x32_bf16 v[0:3], v[214:217], v[196:199], v[0:3]
	s_setprio 0
	s_add_i32 s68, s68, 2
	s_add_u32 s0, s0, 0x100
	s_addc_u32 s67, s67, 0
	s_cmp_gt_u32 s68, 41
	s_mov_b64 s[26:27], s[28:29]
	s_barrier

; #define PG8_STAGE(bufoff, gbase, voff) do { _Pragma("unroll") for (int _i = 0; _i < 2; ++_i) \
;         __builtin_amdgcn_global_load_lds((const unsigned*)((const char*)(gbase) + (voff)[_i]), (LAS unsigned*)(lds + (bufoff) + ldsw + _i * 8192), 16, 0, 0); } while (0)
; #define PG8_LDA(dst, b, h) do { _Pragma("unroll") for (int m = 0; m < 4; ++m) _Pragma("unroll") for (int k = 0; k < 2; ++k) dst[m][k] = *(const LAS bf16x8*)(lds + PG8_SA(b, h) + aoff + m * 2048 + k * 1024); } while (0)
; #define PG8_LDB(dst, b, h) do { _Pragma("unroll") for (int n = 0; n < 2; ++n) _Pragma("unroll") for (int k = 0; k < 2; ++k) dst[n][k] = *(const LAS bf16x8*)(lds + PG8_SB(b, h) + boff + n * 2048 + k * 1024); } while (0)
; #define PG8_WAIT_V(n) asm volatile("s_waitcnt vmcnt(" #n ")" ::: "memory")
; #define PG8_WAIT_L(n) asm volatile("s_waitcnt lgkmcnt(" #n ")" ::: "memory")
; #define PG8_BAR __builtin_amdgcn_s_barrier()
; #define PG8_SCHED __builtin_amdgcn_sched_barrier(0)
; template <class Epi, class Sched>
; __device__ __forceinline__ void gemm_phase(LAS unsigned char* lds, const Gemm g, const Sched& S, const Epi& E) {
;     ...
;         const bool has_next = S.next(ui + 1, nxt);
;         const char* nA = has_next ? (const char*)g.A + (size_t)nxt.pm * tstep : cA; const char* nB = has_next ? (const char*)g.Bt + (size_t)nxt.pn * tstep : cB;
;         for (int t = 0; t < nt; t += 2) {
;             const bool last = (t == nt - 2);
;             const char* a1 = cA + (size_t)(t + 1) * kstep;
;             const char* a2 = last ? nA : cA + (size_t)(t + 2) * kstep; const char* b2 = last ? nB : cB + (size_t)(t + 2) * kstep;
;             const char* a3 = a2 + kstep; const char* b3 = b2 + kstep;
;             PG8_LDB(B0, 0, 0); PG8_SCHED; PG8_LDA(At, 0, 0); PG8_STAGE(PG8_SA(1, 1), a1 + hstep, voffA);
;             PG8_WAIT_L(8); PG8_BAR; PG8_WAIT_L(0); PG8_MMA(0, 0, At, B0); PG8_BAR; PG8_SCHED;
;             PG8_LDB(B1, 0, 1); PG8_STAGE(PG8_SB(0, 0), b2, voffB);
;             PG8_BAR; PG8_WAIT_L(0); PG8_MMA(0, 1, At, B1); PG8_BAR;
;             PG8_LDA(At, 0, 1); PG8_STAGE(PG8_SA(0, 0), a2, voffA);
;             PG8_BAR; PG8_WAIT_L(0); PG8_MMA(1, 0, At, B0); PG8_BAR; PG8_SCHED;
;             PG8_STAGE(PG8_SB(0, 1), b2 + hstep, voffB);
;             PG8_WAIT_V(6); PG8_BAR; PG8_MMA(1, 1, At, B1); PG8_BAR;
.LBB0_577:
	s_ashr_i32 s21, s20, 31
	v_cmp_lt_i64_e32 vcc, s[22:23], v[156:157]
	s_lshl_b64 s[22:23], s[20:21], 19
	s_add_u32 s22, s96, s22
	s_addc_u32 s23, s97, s23
	s_and_b64 s[24:25], vcc, exec
	s_cselect_b32 s5, s23, s7
	s_cselect_b32 s21, s22, s6
	s_ashr_i32 s19, s18, 31
	s_lshl_b64 s[24:25], s[18:19], 19
	s_add_u32 s24, s31, s24
	s_addc_u32 s25, s33, s25
	s_and_b64 s[28:29], vcc, exec
	s_cselect_b32 s19, s25, s27
	s_cselect_b32 s53, s24, s26
	s_add_u32 s6, s6, 0x40080
	s_addc_u32 s7, s7, 0
	s_add_u32 s54, s26, 0x100
	s_addc_u32 s55, s27, 0
	s_mov_b32 s56, -2
	s_waitcnt lgkmcnt(0)
	ds_read_b128 v[128:131], v167
	ds_read_b128 v[132:135], v167 offset:1024
	ds_read_b128 v[136:139], v167 offset:2048
	ds_read_b128 v[160:163], v167 offset:3072
	s_add_u32 s26, s6, 0xfffc0080
	s_addc_u32 s27, s7, -1
	s_cmp_eq_u32 s56, 12
	s_cselect_b32 s29, s5, s27
	s_cselect_b32 s28, s21, s26
	s_cselect_b32 s27, s19, s55
	s_cselect_b32 s26, s53, s54
	v_lshl_add_u64 v[140:141], s[6:7], 0, v[152:153]
	s_add_i32 m0, s37, 0xc000
	ds_read_b128 v[170:173], v168
	ds_read_b128 v[174:177], v168 offset:1024
	ds_read_b128 v[178:181], v168 offset:2048
	ds_read_b128 v[182:185], v168 offset:3072
	ds_read_b128 v[186:189], v168 offset:4096
	ds_read_b128 v[190:193], v168 offset:5120
	ds_read_b128 v[194:197], v168 offset:6144
	ds_read_b128 v[202:205], v168 offset:7168
	global_load_lds_dwordx4 v[140:141], off
	v_lshl_add_u64 v[140:141], s[6:7], 0, v[154:155]
	s_add_i32 m0, s37, 0xe000
	s_nop 0
	global_load_lds_dwordx4 v[140:141], off
	s_waitcnt lgkmcnt(8)
	s_barrier
	s_waitcnt lgkmcnt(0)
	s_setprio 1
	s_waitcnt lgkmcnt(0)
	v_mfma_f32_16x16x32_bf16 v[124:127], v[128:131], v[170:173], 0
	v_mfma_f32_16x16x32_bf16 v[120:123], v[136:139], v[170:173], 0
	v_mfma_f32_16x16x32_bf16 v[108:111], v[128:131], v[178:181], 0
	v_mfma_f32_16x16x32_bf16 v[104:107], v[136:139], v[178:181], 0
	v_mfma_f32_16x16x32_bf16 v[92:95], v[128:131], v[186:189], 0
	v_mfma_f32_16x16x32_bf16 v[88:91], v[136:139], v[186:189], 0
	v_mfma_f32_16x16x32_bf16 v[76:79], v[128:131], v[194:197], 0
	v_mfma_f32_16x16x32_bf16 v[72:75], v[136:139], v[194:197], 0
	v_mfma_f32_16x16x32_bf16 v[124:127], v[132:135], v[174:177], v[124:127]
	v_mfma_f32_16x16x32_bf16 v[120:123], v[160:163], v[174:177], v[120:123]
	v_mfma_f32_16x16x32_bf16 v[108:111], v[132:135], v[182:185], v[108:111]
	v_mfma_f32_16x16x32_bf16 v[104:107], v[160:163], v[182:185], v[104:107]
	v_mfma_f32_16x16x32_bf16 v[92:95], v[132:135], v[190:193], v[92:95]
	v_mfma_f32_16x16x32_bf16 v[88:91], v[160:163], v[190:193], v[88:91]
	v_mfma_f32_16x16x32_bf16 v[76:79], v[132:135], v[202:205], v[76:79]
	v_mfma_f32_16x16x32_bf16 v[72:75], v[160:163], v[202:205], v[72:75]
	s_setprio 0
	s_barrier
	s_add_i32 s57, s48, s34
	v_lshl_add_u64 v[140:141], s[26:27], 0, v[146:147]
	s_mov_b32 m0, s57
	ds_read_b128 v[206:209], v169
	ds_read_b128 v[210:213], v169 offset:1024
	ds_read_b128 v[214:217], v169 offset:2048
	ds_read_b128 v[218:221], v169 offset:3072
	global_load_lds_dwordx4 v[140:141], off
	v_lshl_add_u64 v[198:199], s[26:27], 0, v[142:143]
	s_add_i32 m0, s57, 0x2000
	s_nop 0
	global_load_lds_dwordx4 v[198:199], off
	s_barrier
	s_waitcnt lgkmcnt(0)
	s_setprio 1
	s_waitcnt lgkmcnt(0)
	v_mfma_f32_16x16x32_bf16 v[116:119], v[206:209], v[170:173], 0
	v_mfma_f32_16x16x32_bf16 v[112:115], v[214:217], v[170:173], 0
	v_mfma_f32_16x16x32_bf16 v[100:103], v[206:209], v[178:181], 0
	v_mfma_f32_16x16x32_bf16 v[96:99], v[214:217], v[178:181], 0
	v_mfma_f32_16x16x32_bf16 v[84:87], v[206:209], v[186:189], 0
	v_mfma_f32_16x16x32_bf16 v[80:83], v[214:217], v[186:189], 0
	v_mfma_f32_16x16x32_bf16 v[68:71], v[206:209], v[194:197], 0
	v_mfma_f32_16x16x32_bf16 v[64:67], v[214:217], v[194:197], 0
	v_mfma_f32_16x16x32_bf16 v[116:119], v[210:213], v[174:177], v[116:119]
	v_mfma_f32_16x16x32_bf16 v[112:115], v[218:221], v[174:177], v[112:115]
	v_mfma_f32_16x16x32_bf16 v[100:103], v[210:213], v[182:185], v[100:103]
	v_mfma_f32_16x16x32_bf16 v[96:99], v[218:221], v[182:185], v[96:99]
	v_mfma_f32_16x16x32_bf16 v[84:87], v[210:213], v[190:193], v[84:87]
	v_mfma_f32_16x16x32_bf16 v[80:83], v[218:221], v[190:193], v[80:83]
	v_mfma_f32_16x16x32_bf16 v[68:71], v[210:213], v[202:205], v[68:71]
	v_mfma_f32_16x16x32_bf16 v[64:67], v[218:221], v[202:205], v[64:67]
	s_setprio 0
	s_mov_b32 m0, s37
	v_lshl_add_u64 v[222:223], s[28:29], 0, v[148:149]
	s_barrier
	ds_read_b128 v[170:173], v168 offset:16384
	ds_read_b128 v[174:177], v168 offset:17408
	ds_read_b128 v[178:181], v168 offset:18432
	ds_read_b128 v[182:185], v168 offset:19456
	ds_read_b128 v[186:189], v168 offset:20480
	ds_read_b128 v[190:193], v168 offset:21504
	ds_read_b128 v[194:197], v168 offset:22528
	ds_read_b128 v[202:205], v168 offset:23552
	global_load_lds_dwordx4 v[222:223], off
	v_lshl_add_u64 v[224:225], s[28:29], 0, v[144:145]
	s_mov_b32 m0, s38
	s_nop 0
	global_load_lds_dwordx4 v[224:225], off
	s_barrier
	s_waitcnt lgkmcnt(0)
	s_setprio 1
	s_waitcnt lgkmcnt(0)
	v_mfma_f32_16x16x32_bf16 v[60:63], v[128:131], v[170:173], 0
	v_mfma_f32_16x16x32_bf16 v[56:59], v[136:139], v[170:173], 0
	v_mfma_f32_16x16x32_bf16 v[44:47], v[128:131], v[178:181], 0
	v_mfma_f32_16x16x32_bf16 v[40:43], v[136:139], v[178:181], 0
	v_mfma_f32_16x16x32_bf16 v[28:31], v[128:131], v[186:189], 0
	v_mfma_f32_16x16x32_bf16 v[24:27], v[136:139], v[186:189], 0
	v_mfma_f32_16x16x32_bf16 v[12:15], v[128:131], v[194:197], 0
	v_mfma_f32_16x16x32_bf16 v[8:11], v[136:139], v[194:197], 0
	v_mfma_f32_16x16x32_bf16 v[60:63], v[132:135], v[174:177], v[60:63]
	v_mfma_f32_16x16x32_bf16 v[56:59], v[160:163], v[174:177], v[56:59]
	v_mfma_f32_16x16x32_bf16 v[44:47], v[132:135], v[182:185], v[44:47]
	v_mfma_f32_16x16x32_bf16 v[40:43], v[160:163], v[182:185], v[40:43]
	v_mfma_f32_16x16x32_bf16 v[28:31], v[132:135], v[190:193], v[28:31]
	v_mfma_f32_16x16x32_bf16 v[24:27], v[160:163], v[190:193], v[24:27]
	v_mfma_f32_16x16x32_bf16 v[12:15], v[132:135], v[202:205], v[12:15]
	v_mfma_f32_16x16x32_bf16 v[8:11], v[160:163], v[202:205], v[8:11]
	s_setprio 0
	s_barrier
; #define PG8_STAGE(bufoff, gbase, voff) do { _Pragma("unroll") for (int _i = 0; _i < 2; ++_i) \
;         __builtin_amdgcn_global_load_lds((const unsigned*)((const char*)(gbase) + (voff)[_i]), (LAS unsigned*)(lds + (bufoff) + ldsw + _i * 8192), 16, 0, 0); } while (0)
; #define PG8_LDA(dst, b, h) do { _Pragma("unroll") for (int m = 0; m < 4; ++m) _Pragma("unroll") for (int k = 0; k < 2; ++k) dst[m][k] = *(const LAS bf16x8*)(lds + PG8_SA(b, h) + aoff + m * 2048 + k * 1024); } while (0)
; #define PG8_LDB(dst, b, h) do { _Pragma("unroll") for (int n = 0; n < 2; ++n) _Pragma("unroll") for (int k = 0; k < 2; ++k) dst[n][k] = *(const LAS bf16x8*)(lds + PG8_SB(b, h) + boff + n * 2048 + k * 1024); } while (0)
; #define PG8_MMA(ai, bj, At, Bt) do { __builtin_amdgcn_s_setprio(1); _Pragma("unroll") for (int m = 0; m < 4; ++m) _Pragma("unroll") for (int n = 0; n < 2; ++n) _Pragma("unroll") for (int k = 0; k < 2; ++k) \
;         acc[ai][bj][m][n] = __builtin_amdgcn_mfma_f32_16x16x32_bf16(Bt[n][k], At[m][k], acc[ai][bj][m][n], 0, 0, 0); __builtin_amdgcn_s_setprio(0); } while (0)
; #define PG8_WAIT_V(n) asm volatile("s_waitcnt vmcnt(" #n ")" ::: "memory")
; #define PG8_WAIT_L(n) asm volatile("s_waitcnt lgkmcnt(" #n ")" ::: "memory")
; #define PG8_BAR __builtin_amdgcn_s_barrier()
; #define PG8_SCHED __builtin_amdgcn_sched_barrier(0)
; template <class Epi, class Sched>
; __device__ __forceinline__ void gemm_phase(LAS unsigned char* lds, const Gemm g, const Sched& S, const Epi& E) {
;     ...
;             PG8_STAGE(PG8_SB(0, 1), b2 + hstep, voffB);
;             PG8_WAIT_V(6); PG8_BAR; PG8_MMA(1, 1, At, B1); PG8_BAR;
;             PG8_LDB(B0, 1, 0); PG8_SCHED; PG8_LDA(At, 1, 0); PG8_STAGE(PG8_SA(0, 1), a2 + hstep, voffA);
;             PG8_WAIT_L(8); PG8_BAR; PG8_WAIT_L(0); PG8_MMA(0, 0, At, B0); PG8_BAR; PG8_SCHED;
;             PG8_LDB(B1, 1, 1); PG8_STAGE(PG8_SB(1, 0), b3, voffB);
	s_add_u32 s58, s26, 0x40000
	s_addc_u32 s59, s27, 0
	s_add_i32 s57, s49, s34
	v_lshl_add_u64 v[128:129], s[58:59], 0, v[146:147]
	s_mov_b32 m0, s57
	s_nop 0
	global_load_lds_dwordx4 v[128:129], off
	v_lshl_add_u64 v[128:129], s[58:59], 0, v[142:143]
	s_add_i32 m0, s57, 0x2000
	s_nop 0
	global_load_lds_dwordx4 v[128:129], off
	s_waitcnt vmcnt(6)
	s_barrier
	s_setprio 1
	v_mfma_f32_16x16x32_bf16 v[52:55], v[206:209], v[170:173], 0
	v_mfma_f32_16x16x32_bf16 v[48:51], v[214:217], v[170:173], 0
	v_mfma_f32_16x16x32_bf16 v[36:39], v[206:209], v[178:181], 0
	v_mfma_f32_16x16x32_bf16 v[32:35], v[214:217], v[178:181], 0
	v_mfma_f32_16x16x32_bf16 v[20:23], v[206:209], v[186:189], 0
	v_mfma_f32_16x16x32_bf16 v[16:19], v[214:217], v[186:189], 0
	v_mfma_f32_16x16x32_bf16 v[4:7], v[206:209], v[194:197], 0
	v_mfma_f32_16x16x32_bf16 v[0:3], v[214:217], v[194:197], 0
	v_mfma_f32_16x16x32_bf16 v[52:55], v[210:213], v[174:177], v[52:55]
	v_mfma_f32_16x16x32_bf16 v[48:51], v[218:221], v[174:177], v[48:51]
	v_mfma_f32_16x16x32_bf16 v[36:39], v[210:213], v[182:185], v[36:39]
	v_mfma_f32_16x16x32_bf16 v[32:35], v[218:221], v[182:185], v[32:35]
	v_mfma_f32_16x16x32_bf16 v[20:23], v[210:213], v[190:193], v[20:23]
	v_mfma_f32_16x16x32_bf16 v[16:19], v[218:221], v[190:193], v[16:19]
	v_mfma_f32_16x16x32_bf16 v[4:7], v[210:213], v[202:205], v[4:7]
	v_mfma_f32_16x16x32_bf16 v[0:3], v[218:221], v[202:205], v[0:3]
	s_setprio 0
	s_add_i32 s57, 0, 0x18000
	v_add_u32_e32 v150, s57, v166
	s_barrier
	ds_read_b128 v[128:131], v150
	ds_read_b128 v[132:135], v150 offset:1024
	ds_read_b128 v[136:139], v150 offset:2048
	ds_read_b128 v[160:163], v150 offset:3072
	s_add_u32 s28, s28, 0x40000
	s_addc_u32 s29, s29, 0
	s_mov_b32 m0, s39
	v_lshl_add_u64 v[206:207], s[28:29], 0, v[148:149]
	ds_read_b128 v[170:173], v168 offset:32768
	ds_read_b128 v[174:177], v168 offset:33792
	ds_read_b128 v[178:181], v168 offset:34816
	ds_read_b128 v[182:185], v168 offset:35840
	ds_read_b128 v[186:189], v168 offset:36864
	ds_read_b128 v[190:193], v168 offset:37888
	ds_read_b128 v[194:197], v168 offset:38912
	ds_read_b128 v[202:205], v168 offset:39936
	global_load_lds_dwordx4 v[206:207], off
	v_lshl_add_u64 v[206:207], s[28:29], 0, v[144:145]
	s_mov_b32 m0, s40
	s_nop 0
	global_load_lds_dwordx4 v[206:207], off
	s_waitcnt lgkmcnt(8)
	s_barrier
	s_waitcnt lgkmcnt(0)
	s_setprio 1
	s_waitcnt lgkmcnt(0)
	v_mfma_f32_16x16x32_bf16 v[124:127], v[128:131], v[170:173], v[124:127]
	v_mfma_f32_16x16x32_bf16 v[120:123], v[136:139], v[170:173], v[120:123]
	v_mfma_f32_16x16x32_bf16 v[108:111], v[128:131], v[178:181], v[108:111]
	v_mfma_f32_16x16x32_bf16 v[104:107], v[136:139], v[178:181], v[104:107]
	v_mfma_f32_16x16x32_bf16 v[92:95], v[128:131], v[186:189], v[92:95]
	v_mfma_f32_16x16x32_bf16 v[88:91], v[136:139], v[186:189], v[88:91]
	v_mfma_f32_16x16x32_bf16 v[76:79], v[128:131], v[194:197], v[76:79]
	v_mfma_f32_16x16x32_bf16 v[72:75], v[136:139], v[194:197], v[72:75]
	v_mfma_f32_16x16x32_bf16 v[124:127], v[132:135], v[174:177], v[124:127]
	v_mfma_f32_16x16x32_bf16 v[120:123], v[160:163], v[174:177], v[120:123]
	v_mfma_f32_16x16x32_bf16 v[108:111], v[132:135], v[182:185], v[108:111]
	v_mfma_f32_16x16x32_bf16 v[104:107], v[160:163], v[182:185], v[104:107]
	v_mfma_f32_16x16x32_bf16 v[92:95], v[132:135], v[190:193], v[92:95]
	v_mfma_f32_16x16x32_bf16 v[88:91], v[160:163], v[190:193], v[88:91]
	v_mfma_f32_16x16x32_bf16 v[76:79], v[132:135], v[202:205], v[76:79]
	v_mfma_f32_16x16x32_bf16 v[72:75], v[160:163], v[202:205], v[72:75]
	s_setprio 0
	s_barrier
	s_add_i32 s28, 0, 0x1c000
	s_add_i32 s29, s57, s34
	v_add_u32_e32 v150, s28, v166
	v_lshl_add_u64 v[140:141], v[140:141], 0, s[0:1]
	s_mov_b32 m0, s29
	ds_read_b128 v[206:209], v150
	ds_read_b128 v[210:213], v150 offset:1024
	ds_read_b128 v[214:217], v150 offset:2048
	ds_read_b128 v[218:221], v150 offset:3072
	global_load_lds_dwordx4 v[140:141], off
	v_lshl_add_u64 v[140:141], v[198:199], 0, s[0:1]
	s_add_i32 m0, s29, 0x2000
	s_nop 0
	global_load_lds_dwordx4 v[140:141], off
	s_barrier
; #define PG8_STAGE(bufoff, gbase, voff) do { _Pragma("unroll") for (int _i = 0; _i < 2; ++_i) \
;         __builtin_amdgcn_global_load_lds((const unsigned*)((const char*)(gbase) + (voff)[_i]), (LAS unsigned*)(lds + (bufoff) + ldsw + _i * 8192), 16, 0, 0); } while (0)
; #define PG8_LDA(dst, b, h) do { _Pragma("unroll") for (int m = 0; m < 4; ++m) _Pragma("unroll") for (int k = 0; k < 2; ++k) dst[m][k] = *(const LAS bf16x8*)(lds + PG8_SA(b, h) + aoff + m * 2048 + k * 1024); } while (0)
; #define PG8_MMA(ai, bj, At, Bt) do { __builtin_amdgcn_s_setprio(1); _Pragma("unroll") for (int m = 0; m < 4; ++m) _Pragma("unroll") for (int n = 0; n < 2; ++n) _Pragma("unroll") for (int k = 0; k < 2; ++k) \
;         acc[ai][bj][m][n] = __builtin_amdgcn_mfma_f32_16x16x32_bf16(Bt[n][k], At[m][k], acc[ai][bj][m][n], 0, 0, 0); __builtin_amdgcn_s_setprio(0); } while (0)
; #define PG8_WAIT_V(n) asm volatile("s_waitcnt vmcnt(" #n ")" ::: "memory")
; #define PG8_WAIT_L(n) asm volatile("s_waitcnt lgkmcnt(" #n ")" ::: "memory")
; #define PG8_BAR __builtin_amdgcn_s_barrier()
; #define PG8_SCHED __builtin_amdgcn_sched_barrier(0)
; template <class Epi, class Sched>
; __device__ __forceinline__ void gemm_phase(LAS unsigned char* lds, const Gemm g, const Sched& S, const Epi& E) {
;     ...
;             PG8_LDA(At, 1, 1); PG8_STAGE(PG8_SA(1, 0), a3, voffA);
;             PG8_BAR; PG8_WAIT_L(0); PG8_MMA(1, 0, At, B0); PG8_BAR; PG8_SCHED;
;             PG8_STAGE(PG8_SB(1, 1), b3 + hstep, voffB);
;             PG8_WAIT_V(6); PG8_BAR; PG8_MMA(1, 1, At, B1); PG8_BAR;
;         }
	s_waitcnt lgkmcnt(0)
	s_setprio 1
	s_waitcnt lgkmcnt(0)
	v_mfma_f32_16x16x32_bf16 v[116:119], v[206:209], v[170:173], v[116:119]
	v_mfma_f32_16x16x32_bf16 v[112:115], v[214:217], v[170:173], v[112:115]
	v_mfma_f32_16x16x32_bf16 v[100:103], v[206:209], v[178:181], v[100:103]
	v_mfma_f32_16x16x32_bf16 v[96:99], v[214:217], v[178:181], v[96:99]
	v_mfma_f32_16x16x32_bf16 v[84:87], v[206:209], v[186:189], v[84:87]
	v_mfma_f32_16x16x32_bf16 v[80:83], v[214:217], v[186:189], v[80:83]
	v_mfma_f32_16x16x32_bf16 v[68:71], v[206:209], v[194:197], v[68:71]
	v_mfma_f32_16x16x32_bf16 v[64:67], v[214:217], v[194:197], v[64:67]
	v_mfma_f32_16x16x32_bf16 v[116:119], v[210:213], v[174:177], v[116:119]
	v_mfma_f32_16x16x32_bf16 v[112:115], v[218:221], v[174:177], v[112:115]
	v_mfma_f32_16x16x32_bf16 v[100:103], v[210:213], v[182:185], v[100:103]
	v_mfma_f32_16x16x32_bf16 v[96:99], v[218:221], v[182:185], v[96:99]
	v_mfma_f32_16x16x32_bf16 v[84:87], v[210:213], v[190:193], v[84:87]
	v_mfma_f32_16x16x32_bf16 v[80:83], v[218:221], v[190:193], v[80:83]
	v_mfma_f32_16x16x32_bf16 v[68:71], v[210:213], v[202:205], v[68:71]
	v_mfma_f32_16x16x32_bf16 v[64:67], v[218:221], v[202:205], v[64:67]
	s_setprio 0
	s_mov_b32 m0, s44
	v_lshl_add_u64 v[140:141], v[222:223], 0, s[0:1]
	s_barrier
	ds_read_b128 v[170:173], v168 offset:49152
	ds_read_b128 v[174:177], v168 offset:50176
	ds_read_b128 v[178:181], v168 offset:51200
	ds_read_b128 v[182:185], v168 offset:52224
	ds_read_b128 v[186:189], v168 offset:53248
	ds_read_b128 v[190:193], v168 offset:54272
	ds_read_b128 v[194:197], v168 offset:55296
	ds_read_b128 v[202:205], v168 offset:56320
	global_load_lds_dwordx4 v[140:141], off
	v_lshl_add_u64 v[140:141], v[224:225], 0, s[0:1]
	s_mov_b32 m0, s45
	s_nop 0
	global_load_lds_dwordx4 v[140:141], off
	s_barrier
	s_waitcnt lgkmcnt(0)
	s_setprio 1
	s_waitcnt lgkmcnt(0)
	v_mfma_f32_16x16x32_bf16 v[60:63], v[128:131], v[170:173], v[60:63]
	v_mfma_f32_16x16x32_bf16 v[56:59], v[136:139], v[170:173], v[56:59]
	v_mfma_f32_16x16x32_bf16 v[44:47], v[128:131], v[178:181], v[44:47]
	v_mfma_f32_16x16x32_bf16 v[40:43], v[136:139], v[178:181], v[40:43]
	v_mfma_f32_16x16x32_bf16 v[28:31], v[128:131], v[186:189], v[28:31]
	v_mfma_f32_16x16x32_bf16 v[24:27], v[136:139], v[186:189], v[24:27]
	v_mfma_f32_16x16x32_bf16 v[12:15], v[128:131], v[194:197], v[12:15]
	v_mfma_f32_16x16x32_bf16 v[8:11], v[136:139], v[194:197], v[8:11]
	v_mfma_f32_16x16x32_bf16 v[60:63], v[132:135], v[174:177], v[60:63]
	v_mfma_f32_16x16x32_bf16 v[56:59], v[160:163], v[174:177], v[56:59]
	v_mfma_f32_16x16x32_bf16 v[44:47], v[132:135], v[182:185], v[44:47]
	v_mfma_f32_16x16x32_bf16 v[40:43], v[160:163], v[182:185], v[40:43]
	v_mfma_f32_16x16x32_bf16 v[28:31], v[132:135], v[190:193], v[28:31]
	v_mfma_f32_16x16x32_bf16 v[24:27], v[160:163], v[190:193], v[24:27]
	v_mfma_f32_16x16x32_bf16 v[12:15], v[132:135], v[202:205], v[12:15]
	v_mfma_f32_16x16x32_bf16 v[8:11], v[160:163], v[202:205], v[8:11]
	s_setprio 0
	s_barrier
	s_add_u32 s26, s26, 0x40080
	s_addc_u32 s27, s27, 0
	s_add_i32 s28, s28, s34
	v_lshl_add_u64 v[128:129], s[26:27], 0, v[146:147]
	s_mov_b32 m0, s28
	s_nop 0
	global_load_lds_dwordx4 v[128:129], off
	v_lshl_add_u64 v[128:129], s[26:27], 0, v[142:143]
	s_add_i32 m0, s28, 0x2000
	s_nop 0
	global_load_lds_dwordx4 v[128:129], off
	s_waitcnt vmcnt(6)
	s_barrier
	s_setprio 1
	v_mfma_f32_16x16x32_bf16 v[52:55], v[206:209], v[170:173], v[52:55]
	v_mfma_f32_16x16x32_bf16 v[48:51], v[214:217], v[170:173], v[48:51]
	v_mfma_f32_16x16x32_bf16 v[36:39], v[206:209], v[178:181], v[36:39]
	v_mfma_f32_16x16x32_bf16 v[32:35], v[214:217], v[178:181], v[32:35]
	v_mfma_f32_16x16x32_bf16 v[20:23], v[206:209], v[186:189], v[20:23]
	v_mfma_f32_16x16x32_bf16 v[16:19], v[214:217], v[186:189], v[16:19]
	v_mfma_f32_16x16x32_bf16 v[4:7], v[206:209], v[194:197], v[4:7]
	v_mfma_f32_16x16x32_bf16 v[0:3], v[214:217], v[194:197], v[0:3]
	v_mfma_f32_16x16x32_bf16 v[52:55], v[210:213], v[174:177], v[52:55]
	v_mfma_f32_16x16x32_bf16 v[48:51], v[218:221], v[174:177], v[48:51]
	v_mfma_f32_16x16x32_bf16 v[36:39], v[210:213], v[182:185], v[36:39]
	v_mfma_f32_16x16x32_bf16 v[32:35], v[218:221], v[182:185], v[32:35]
	v_mfma_f32_16x16x32_bf16 v[20:23], v[210:213], v[190:193], v[20:23]
	v_mfma_f32_16x16x32_bf16 v[16:19], v[218:221], v[190:193], v[16:19]
	v_mfma_f32_16x16x32_bf16 v[4:7], v[210:213], v[202:205], v[4:7]
	v_mfma_f32_16x16x32_bf16 v[0:3], v[218:221], v[202:205], v[0:3]
	s_setprio 0
	s_add_i32 s56, s56, 2
	s_add_u32 s6, s6, 0x100
	s_addc_u32 s7, s7, 0
	s_add_u32 s54, s54, 0x100
	s_addc_u32 s55, s55, 0
	s_cmp_gt_u32 s56, 13
	s_barrier

; #define PG8_STAGE(bufoff, gbase, voff) do { _Pragma("unroll") for (int _i = 0; _i < 2; ++_i) \
;         __builtin_amdgcn_global_load_lds((const unsigned*)((const char*)(gbase) + (voff)[_i]), (LAS unsigned*)(lds + (bufoff) + ldsw + _i * 8192), 16, 0, 0); } while (0)
; #define PG8_LDA(dst, b, h) do { _Pragma("unroll") for (int m = 0; m < 4; ++m) _Pragma("unroll") for (int k = 0; k < 2; ++k) dst[m][k] = *(const LAS bf16x8*)(lds + PG8_SA(b, h) + aoff + m * 2048 + k * 1024); } while (0)
; #define PG8_LDB(dst, b, h) do { _Pragma("unroll") for (int n = 0; n < 2; ++n) _Pragma("unroll") for (int k = 0; k < 2; ++k) dst[n][k] = *(const LAS bf16x8*)(lds + PG8_SB(b, h) + boff + n * 2048 + k * 1024); } while (0)
; #define PG8_WAIT_V(n) asm volatile("s_waitcnt vmcnt(" #n ")" ::: "memory")
; #define PG8_WAIT_L(n) asm volatile("s_waitcnt lgkmcnt(" #n ")" ::: "memory")
; #define PG8_BAR __builtin_amdgcn_s_barrier()
; #define PG8_SCHED __builtin_amdgcn_sched_barrier(0)
; template <class Epi, class Sched>
; __device__ __forceinline__ void gemm_phase(LAS unsigned char* lds, const Gemm g, const Sched& S, const Epi& E) {
;     ...
;         const bool has_next = S.next(ui + 1, nxt);
;         const char* nA = has_next ? (const char*)g.A + (size_t)nxt.pm * tstep : cA; const char* nB = has_next ? (const char*)g.Bt + (size_t)nxt.pn * tstep : cB;
;         for (int t = 0; t < nt; t += 2) {
;             const bool last = (t == nt - 2);
;             const char* a1 = cA + (size_t)(t + 1) * kstep;
;             const char* a2 = last ? nA : cA + (size_t)(t + 2) * kstep; const char* b2 = last ? nB : cB + (size_t)(t + 2) * kstep;
;             const char* a3 = a2 + kstep; const char* b3 = b2 + kstep;
;             PG8_LDB(B0, 0, 0); PG8_SCHED; PG8_LDA(At, 0, 0); PG8_STAGE(PG8_SA(1, 1), a1 + hstep, voffA);
;             PG8_WAIT_L(8); PG8_BAR; PG8_WAIT_L(0); PG8_MMA(0, 0, At, B0); PG8_BAR; PG8_SCHED;
;             PG8_LDB(B1, 0, 1); PG8_STAGE(PG8_SB(0, 0), b2, voffB);
;             PG8_BAR; PG8_WAIT_L(0); PG8_MMA(0, 1, At, B1); PG8_BAR;
;             PG8_LDA(At, 0, 1); PG8_STAGE(PG8_SA(0, 0), a2, voffA);
;             PG8_BAR; PG8_WAIT_L(0); PG8_MMA(1, 0, At, B0); PG8_BAR; PG8_SCHED;
;             PG8_STAGE(PG8_SB(0, 1), b2 + hstep, voffB);
;             PG8_WAIT_V(6); PG8_BAR; PG8_MMA(1, 1, At, B1); PG8_BAR;
.LBB0_612:
	s_ashr_i32 s35, s34, 31
	v_cmp_lt_i64_e32 vcc, s[6:7], v[142:143]
	s_lshl_b64 s[6:7], s[34:35], 19
	s_add_u32 s36, s40, s6
	s_addc_u32 s37, s41, s7
	s_and_b64 s[6:7], vcc, exec
	s_cselect_b32 s8, s37, s1
	s_cselect_b32 s9, s36, s0
	s_ashr_i32 s31, s30, 31
	s_lshl_b64 s[6:7], s[30:31], 19
	s_add_u32 s38, s96, s6
	s_addc_u32 s39, s97, s7
	s_and_b64 s[6:7], vcc, exec
	s_cselect_b32 s31, s39, s5
	s_cselect_b32 s35, s38, s4
	s_add_u32 s0, s0, 0x40080
	s_addc_u32 s1, s1, 0
	s_add_u32 s65, s4, 0x100
	s_addc_u32 s66, s5, 0
	s_mov_b32 s67, -2
	s_waitcnt lgkmcnt(0)
	ds_read_b128 v[146:149], v171
	ds_read_b128 v[150:153], v171 offset:1024
	ds_read_b128 v[154:157], v171 offset:2048
	ds_read_b128 v[158:161], v171 offset:3072
	s_add_u32 s4, s0, 0xfffc0080
	s_addc_u32 s5, s1, -1
	s_cmp_eq_u32 s67, 12
	s_cselect_b32 s7, s8, s5
	s_cselect_b32 s6, s9, s4
	s_cselect_b32 s5, s31, s66
	s_cselect_b32 s4, s35, s65
	v_lshl_add_u64 v[166:167], s[0:1], 0, v[138:139]
	s_add_i32 m0, s45, 0xc000
	ds_read_b128 v[162:165], v172
	ds_read_b128 v[178:181], v172 offset:1024
	ds_read_b128 v[182:185], v172 offset:2048
	ds_read_b128 v[186:189], v172 offset:3072
	ds_read_b128 v[190:193], v172 offset:4096
	ds_read_b128 v[194:197], v172 offset:5120
	ds_read_b128 v[202:205], v172 offset:6144
	ds_read_b128 v[206:209], v172 offset:7168
	global_load_lds_dwordx4 v[166:167], off
	v_lshl_add_u64 v[166:167], s[0:1], 0, v[140:141]
	s_add_i32 m0, s45, 0xe000
	s_nop 0
	global_load_lds_dwordx4 v[166:167], off
	s_waitcnt lgkmcnt(8)
	s_barrier
	s_waitcnt lgkmcnt(0)
	s_setprio 1
	s_waitcnt lgkmcnt(0)
	v_mfma_f32_16x16x32_bf16 v[124:127], v[146:149], v[162:165], 0
	v_mfma_f32_16x16x32_bf16 v[120:123], v[154:157], v[162:165], 0
	v_mfma_f32_16x16x32_bf16 v[108:111], v[146:149], v[182:185], 0
	v_mfma_f32_16x16x32_bf16 v[104:107], v[154:157], v[182:185], 0
	v_mfma_f32_16x16x32_bf16 v[92:95], v[146:149], v[190:193], 0
	v_mfma_f32_16x16x32_bf16 v[88:91], v[154:157], v[190:193], 0
	v_mfma_f32_16x16x32_bf16 v[76:79], v[146:149], v[202:205], 0
	v_mfma_f32_16x16x32_bf16 v[72:75], v[154:157], v[202:205], 0
	v_mfma_f32_16x16x32_bf16 v[124:127], v[150:153], v[178:181], v[124:127]
	v_mfma_f32_16x16x32_bf16 v[120:123], v[158:161], v[178:181], v[120:123]
	v_mfma_f32_16x16x32_bf16 v[108:111], v[150:153], v[186:189], v[108:111]
	v_mfma_f32_16x16x32_bf16 v[104:107], v[158:161], v[186:189], v[104:107]
	v_mfma_f32_16x16x32_bf16 v[92:95], v[150:153], v[194:197], v[92:95]
	v_mfma_f32_16x16x32_bf16 v[88:91], v[158:161], v[194:197], v[88:91]
	v_mfma_f32_16x16x32_bf16 v[76:79], v[150:153], v[206:209], v[76:79]
	v_mfma_f32_16x16x32_bf16 v[72:75], v[158:161], v[206:209], v[72:75]
	s_setprio 0
	s_barrier
	s_add_i32 s68, s57, s44
	v_lshl_add_u64 v[166:167], s[4:5], 0, v[130:131]
	s_mov_b32 m0, s68
	ds_read_b128 v[210:213], v173
	ds_read_b128 v[214:217], v173 offset:1024
	ds_read_b128 v[218:221], v173 offset:2048
	ds_read_b128 v[222:225], v173 offset:3072
	global_load_lds_dwordx4 v[166:167], off
	v_lshl_add_u64 v[198:199], s[4:5], 0, v[134:135]
	s_add_i32 m0, s68, 0x2000
	s_nop 0
	global_load_lds_dwordx4 v[198:199], off
	s_barrier
	s_waitcnt lgkmcnt(0)
	s_setprio 1
	s_waitcnt lgkmcnt(0)
	v_mfma_f32_16x16x32_bf16 v[116:119], v[210:213], v[162:165], 0
	v_mfma_f32_16x16x32_bf16 v[112:115], v[218:221], v[162:165], 0
	v_mfma_f32_16x16x32_bf16 v[100:103], v[210:213], v[182:185], 0
	v_mfma_f32_16x16x32_bf16 v[96:99], v[218:221], v[182:185], 0
	v_mfma_f32_16x16x32_bf16 v[84:87], v[210:213], v[190:193], 0
	v_mfma_f32_16x16x32_bf16 v[80:83], v[218:221], v[190:193], 0
	v_mfma_f32_16x16x32_bf16 v[68:71], v[210:213], v[202:205], 0
	v_mfma_f32_16x16x32_bf16 v[64:67], v[218:221], v[202:205], 0
	v_mfma_f32_16x16x32_bf16 v[116:119], v[214:217], v[178:181], v[116:119]
	v_mfma_f32_16x16x32_bf16 v[112:115], v[222:225], v[178:181], v[112:115]
	v_mfma_f32_16x16x32_bf16 v[100:103], v[214:217], v[186:189], v[100:103]
	v_mfma_f32_16x16x32_bf16 v[96:99], v[222:225], v[186:189], v[96:99]
	v_mfma_f32_16x16x32_bf16 v[84:87], v[214:217], v[194:197], v[84:87]
	v_mfma_f32_16x16x32_bf16 v[80:83], v[222:225], v[194:197], v[80:83]
	v_mfma_f32_16x16x32_bf16 v[68:71], v[214:217], v[206:209], v[68:71]
	v_mfma_f32_16x16x32_bf16 v[64:67], v[222:225], v[206:209], v[64:67]
	s_setprio 0
	s_mov_b32 m0, s45
	v_lshl_add_u64 v[226:227], s[6:7], 0, v[128:129]
	s_barrier
	ds_read_b128 v[162:165], v172 offset:16384
	ds_read_b128 v[178:181], v172 offset:17408
	ds_read_b128 v[182:185], v172 offset:18432
	ds_read_b128 v[186:189], v172 offset:19456
	ds_read_b128 v[190:193], v172 offset:20480
	ds_read_b128 v[194:197], v172 offset:21504
	ds_read_b128 v[202:205], v172 offset:22528
	ds_read_b128 v[206:209], v172 offset:23552
	global_load_lds_dwordx4 v[226:227], off
	v_lshl_add_u64 v[228:229], s[6:7], 0, v[132:133]
	s_mov_b32 m0, s46
	s_nop 0
	global_load_lds_dwordx4 v[228:229], off
	s_barrier
	s_waitcnt lgkmcnt(0)
	s_setprio 1
	s_waitcnt lgkmcnt(0)
	v_mfma_f32_16x16x32_bf16 v[60:63], v[146:149], v[162:165], 0
	v_mfma_f32_16x16x32_bf16 v[56:59], v[154:157], v[162:165], 0
	v_mfma_f32_16x16x32_bf16 v[44:47], v[146:149], v[182:185], 0
	v_mfma_f32_16x16x32_bf16 v[40:43], v[154:157], v[182:185], 0
	v_mfma_f32_16x16x32_bf16 v[28:31], v[146:149], v[190:193], 0
	v_mfma_f32_16x16x32_bf16 v[24:27], v[154:157], v[190:193], 0
	v_mfma_f32_16x16x32_bf16 v[12:15], v[146:149], v[202:205], 0
	v_mfma_f32_16x16x32_bf16 v[8:11], v[154:157], v[202:205], 0
	v_mfma_f32_16x16x32_bf16 v[60:63], v[150:153], v[178:181], v[60:63]
	v_mfma_f32_16x16x32_bf16 v[56:59], v[158:161], v[178:181], v[56:59]
	v_mfma_f32_16x16x32_bf16 v[44:47], v[150:153], v[186:189], v[44:47]
	v_mfma_f32_16x16x32_bf16 v[40:43], v[158:161], v[186:189], v[40:43]
	v_mfma_f32_16x16x32_bf16 v[28:31], v[150:153], v[194:197], v[28:31]
	v_mfma_f32_16x16x32_bf16 v[24:27], v[158:161], v[194:197], v[24:27]
	v_mfma_f32_16x16x32_bf16 v[12:15], v[150:153], v[206:209], v[12:15]
	v_mfma_f32_16x16x32_bf16 v[8:11], v[158:161], v[206:209], v[8:11]
	s_setprio 0
	s_barrier
; #define PG8_STAGE(bufoff, gbase, voff) do { _Pragma("unroll") for (int _i = 0; _i < 2; ++_i) \
;         __builtin_amdgcn_global_load_lds((const unsigned*)((const char*)(gbase) + (voff)[_i]), (LAS unsigned*)(lds + (bufoff) + ldsw + _i * 8192), 16, 0, 0); } while (0)
; #define PG8_LDA(dst, b, h) do { _Pragma("unroll") for (int m = 0; m < 4; ++m) _Pragma("unroll") for (int k = 0; k < 2; ++k) dst[m][k] = *(const LAS bf16x8*)(lds + PG8_SA(b, h) + aoff + m * 2048 + k * 1024); } while (0)
; #define PG8_LDB(dst, b, h) do { _Pragma("unroll") for (int n = 0; n < 2; ++n) _Pragma("unroll") for (int k = 0; k < 2; ++k) dst[n][k] = *(const LAS bf16x8*)(lds + PG8_SB(b, h) + boff + n * 2048 + k * 1024); } while (0)
; #define PG8_MMA(ai, bj, At, Bt) do { __builtin_amdgcn_s_setprio(1); _Pragma("unroll") for (int m = 0; m < 4; ++m) _Pragma("unroll") for (int n = 0; n < 2; ++n) _Pragma("unroll") for (int k = 0; k < 2; ++k) \
;         acc[ai][bj][m][n] = __builtin_amdgcn_mfma_f32_16x16x32_bf16(Bt[n][k], At[m][k], acc[ai][bj][m][n], 0, 0, 0); __builtin_amdgcn_s_setprio(0); } while (0)
; #define PG8_WAIT_V(n) asm volatile("s_waitcnt vmcnt(" #n ")" ::: "memory")
; #define PG8_WAIT_L(n) asm volatile("s_waitcnt lgkmcnt(" #n ")" ::: "memory")
; #define PG8_BAR __builtin_amdgcn_s_barrier()
; #define PG8_SCHED __builtin_amdgcn_sched_barrier(0)
; template <class Epi, class Sched>
; __device__ __forceinline__ void gemm_phase(LAS unsigned char* lds, const Gemm g, const Sched& S, const Epi& E) {
;     ...
;             PG8_STAGE(PG8_SB(0, 1), b2 + hstep, voffB);
;             PG8_WAIT_V(6); PG8_BAR; PG8_MMA(1, 1, At, B1); PG8_BAR;
;             PG8_LDB(B0, 1, 0); PG8_SCHED; PG8_LDA(At, 1, 0); PG8_STAGE(PG8_SA(0, 1), a2 + hstep, voffA);
;             PG8_WAIT_L(8); PG8_BAR; PG8_WAIT_L(0); PG8_MMA(0, 0, At, B0); PG8_BAR; PG8_SCHED;
;             PG8_LDB(B1, 1, 1); PG8_STAGE(PG8_SB(1, 0), b3, voffB);
	s_add_u32 s68, s4, 0x40000
	s_addc_u32 s69, s5, 0
	s_add_i32 s70, s58, s44
	v_lshl_add_u64 v[146:147], s[68:69], 0, v[130:131]
	s_mov_b32 m0, s70
	s_nop 0
	global_load_lds_dwordx4 v[146:147], off
	v_lshl_add_u64 v[146:147], s[68:69], 0, v[134:135]
	s_add_i32 m0, s70, 0x2000
	s_nop 0
	global_load_lds_dwordx4 v[146:147], off
	s_waitcnt vmcnt(6)
	s_barrier
	s_setprio 1
	v_mfma_f32_16x16x32_bf16 v[52:55], v[210:213], v[162:165], 0
	v_mfma_f32_16x16x32_bf16 v[48:51], v[218:221], v[162:165], 0
	v_mfma_f32_16x16x32_bf16 v[36:39], v[210:213], v[182:185], 0
	v_mfma_f32_16x16x32_bf16 v[32:35], v[218:221], v[182:185], 0
	v_mfma_f32_16x16x32_bf16 v[20:23], v[210:213], v[190:193], 0
	v_mfma_f32_16x16x32_bf16 v[16:19], v[218:221], v[190:193], 0
	v_mfma_f32_16x16x32_bf16 v[4:7], v[210:213], v[202:205], 0
	v_mfma_f32_16x16x32_bf16 v[0:3], v[218:221], v[202:205], 0
	v_mfma_f32_16x16x32_bf16 v[52:55], v[214:217], v[178:181], v[52:55]
	v_mfma_f32_16x16x32_bf16 v[48:51], v[222:225], v[178:181], v[48:51]
	v_mfma_f32_16x16x32_bf16 v[36:39], v[214:217], v[186:189], v[36:39]
	v_mfma_f32_16x16x32_bf16 v[32:35], v[222:225], v[186:189], v[32:35]
	v_mfma_f32_16x16x32_bf16 v[20:23], v[214:217], v[194:197], v[20:23]
	v_mfma_f32_16x16x32_bf16 v[16:19], v[222:225], v[194:197], v[16:19]
	v_mfma_f32_16x16x32_bf16 v[4:7], v[214:217], v[206:209], v[4:7]
	v_mfma_f32_16x16x32_bf16 v[0:3], v[222:225], v[206:209], v[0:3]
	s_setprio 0
	s_add_i32 s68, 0, 0x18000
	v_add_u32_e32 v136, s68, v170
	s_barrier
	ds_read_b128 v[146:149], v136
	ds_read_b128 v[150:153], v136 offset:1024
	ds_read_b128 v[154:157], v136 offset:2048
	ds_read_b128 v[158:161], v136 offset:3072
	s_add_u32 s6, s6, 0x40000
	s_addc_u32 s7, s7, 0
	s_mov_b32 m0, s47
	v_lshl_add_u64 v[210:211], s[6:7], 0, v[128:129]
	ds_read_b128 v[162:165], v172 offset:32768
	ds_read_b128 v[178:181], v172 offset:33792
	ds_read_b128 v[182:185], v172 offset:34816
	ds_read_b128 v[186:189], v172 offset:35840
	ds_read_b128 v[190:193], v172 offset:36864
	ds_read_b128 v[194:197], v172 offset:37888
	ds_read_b128 v[202:205], v172 offset:38912
	ds_read_b128 v[206:209], v172 offset:39936
	global_load_lds_dwordx4 v[210:211], off
	v_lshl_add_u64 v[210:211], s[6:7], 0, v[132:133]
	s_mov_b32 m0, s48
	s_nop 0
	global_load_lds_dwordx4 v[210:211], off
	s_waitcnt lgkmcnt(8)
	s_barrier
	s_waitcnt lgkmcnt(0)
	s_setprio 1
	s_waitcnt lgkmcnt(0)
	v_mfma_f32_16x16x32_bf16 v[124:127], v[146:149], v[162:165], v[124:127]
	v_mfma_f32_16x16x32_bf16 v[120:123], v[154:157], v[162:165], v[120:123]
	v_mfma_f32_16x16x32_bf16 v[108:111], v[146:149], v[182:185], v[108:111]
	v_mfma_f32_16x16x32_bf16 v[104:107], v[154:157], v[182:185], v[104:107]
	v_mfma_f32_16x16x32_bf16 v[92:95], v[146:149], v[190:193], v[92:95]
	v_mfma_f32_16x16x32_bf16 v[88:91], v[154:157], v[190:193], v[88:91]
	v_mfma_f32_16x16x32_bf16 v[76:79], v[146:149], v[202:205], v[76:79]
	v_mfma_f32_16x16x32_bf16 v[72:75], v[154:157], v[202:205], v[72:75]
	v_mfma_f32_16x16x32_bf16 v[124:127], v[150:153], v[178:181], v[124:127]
	v_mfma_f32_16x16x32_bf16 v[120:123], v[158:161], v[178:181], v[120:123]
	v_mfma_f32_16x16x32_bf16 v[108:111], v[150:153], v[186:189], v[108:111]
	v_mfma_f32_16x16x32_bf16 v[104:107], v[158:161], v[186:189], v[104:107]
	v_mfma_f32_16x16x32_bf16 v[92:95], v[150:153], v[194:197], v[92:95]
	v_mfma_f32_16x16x32_bf16 v[88:91], v[158:161], v[194:197], v[88:91]
	v_mfma_f32_16x16x32_bf16 v[76:79], v[150:153], v[206:209], v[76:79]
	v_mfma_f32_16x16x32_bf16 v[72:75], v[158:161], v[206:209], v[72:75]
	s_setprio 0
	s_barrier
	s_add_i32 s6, 0, 0x1c000
	s_add_i32 s7, s68, s44
	v_add_u32_e32 v136, s6, v170
	v_lshl_add_u64 v[166:167], v[166:167], 0, s[20:21]
	s_mov_b32 m0, s7
	ds_read_b128 v[210:213], v136
	ds_read_b128 v[214:217], v136 offset:1024
	ds_read_b128 v[218:221], v136 offset:2048
	ds_read_b128 v[222:225], v136 offset:3072
	global_load_lds_dwordx4 v[166:167], off
	v_lshl_add_u64 v[166:167], v[198:199], 0, s[20:21]
	s_add_i32 m0, s7, 0x2000
	s_nop 0
	global_load_lds_dwordx4 v[166:167], off
	s_barrier
; #define PG8_STAGE(bufoff, gbase, voff) do { _Pragma("unroll") for (int _i = 0; _i < 2; ++_i) \
;         __builtin_amdgcn_global_load_lds((const unsigned*)((const char*)(gbase) + (voff)[_i]), (LAS unsigned*)(lds + (bufoff) + ldsw + _i * 8192), 16, 0, 0); } while (0)
; #define PG8_LDA(dst, b, h) do { _Pragma("unroll") for (int m = 0; m < 4; ++m) _Pragma("unroll") for (int k = 0; k < 2; ++k) dst[m][k] = *(const LAS bf16x8*)(lds + PG8_SA(b, h) + aoff + m * 2048 + k * 1024); } while (0)
; #define PG8_MMA(ai, bj, At, Bt) do { __builtin_amdgcn_s_setprio(1); _Pragma("unroll") for (int m = 0; m < 4; ++m) _Pragma("unroll") for (int n = 0; n < 2; ++n) _Pragma("unroll") for (int k = 0; k < 2; ++k) \
;         acc[ai][bj][m][n] = __builtin_amdgcn_mfma_f32_16x16x32_bf16(Bt[n][k], At[m][k], acc[ai][bj][m][n], 0, 0, 0); __builtin_amdgcn_s_setprio(0); } while (0)
; #define PG8_WAIT_V(n) asm volatile("s_waitcnt vmcnt(" #n ")" ::: "memory")
; #define PG8_WAIT_L(n) asm volatile("s_waitcnt lgkmcnt(" #n ")" ::: "memory")
; #define PG8_BAR __builtin_amdgcn_s_barrier()
; #define PG8_SCHED __builtin_amdgcn_sched_barrier(0)
; template <class Epi, class Sched>
; __device__ __forceinline__ void gemm_phase(LAS unsigned char* lds, const Gemm g, const Sched& S, const Epi& E) {
;     ...
;             PG8_LDA(At, 1, 1); PG8_STAGE(PG8_SA(1, 0), a3, voffA);
;             PG8_BAR; PG8_WAIT_L(0); PG8_MMA(1, 0, At, B0); PG8_BAR; PG8_SCHED;
;             PG8_STAGE(PG8_SB(1, 1), b3 + hstep, voffB);
;             PG8_WAIT_V(6); PG8_BAR; PG8_MMA(1, 1, At, B1); PG8_BAR;
;         }
	s_waitcnt lgkmcnt(0)
	s_setprio 1
	s_waitcnt lgkmcnt(0)
	v_mfma_f32_16x16x32_bf16 v[116:119], v[210:213], v[162:165], v[116:119]
	v_mfma_f32_16x16x32_bf16 v[112:115], v[218:221], v[162:165], v[112:115]
	v_mfma_f32_16x16x32_bf16 v[100:103], v[210:213], v[182:185], v[100:103]
	v_mfma_f32_16x16x32_bf16 v[96:99], v[218:221], v[182:185], v[96:99]
	v_mfma_f32_16x16x32_bf16 v[84:87], v[210:213], v[190:193], v[84:87]
	v_mfma_f32_16x16x32_bf16 v[80:83], v[218:221], v[190:193], v[80:83]
	v_mfma_f32_16x16x32_bf16 v[68:71], v[210:213], v[202:205], v[68:71]
	v_mfma_f32_16x16x32_bf16 v[64:67], v[218:221], v[202:205], v[64:67]
	v_mfma_f32_16x16x32_bf16 v[116:119], v[214:217], v[178:181], v[116:119]
	v_mfma_f32_16x16x32_bf16 v[112:115], v[222:225], v[178:181], v[112:115]
	v_mfma_f32_16x16x32_bf16 v[100:103], v[214:217], v[186:189], v[100:103]
	v_mfma_f32_16x16x32_bf16 v[96:99], v[222:225], v[186:189], v[96:99]
	v_mfma_f32_16x16x32_bf16 v[84:87], v[214:217], v[194:197], v[84:87]
	v_mfma_f32_16x16x32_bf16 v[80:83], v[222:225], v[194:197], v[80:83]
	v_mfma_f32_16x16x32_bf16 v[68:71], v[214:217], v[206:209], v[68:71]
	v_mfma_f32_16x16x32_bf16 v[64:67], v[222:225], v[206:209], v[64:67]
	s_setprio 0
	s_mov_b32 m0, s54
	v_lshl_add_u64 v[166:167], v[226:227], 0, s[20:21]
	s_barrier
	ds_read_b128 v[162:165], v172 offset:49152
	ds_read_b128 v[178:181], v172 offset:50176
	ds_read_b128 v[182:185], v172 offset:51200
	ds_read_b128 v[186:189], v172 offset:52224
	ds_read_b128 v[190:193], v172 offset:53248
	ds_read_b128 v[194:197], v172 offset:54272
	ds_read_b128 v[202:205], v172 offset:55296
	ds_read_b128 v[206:209], v172 offset:56320
	global_load_lds_dwordx4 v[166:167], off
	v_lshl_add_u64 v[166:167], v[228:229], 0, s[20:21]
	s_mov_b32 m0, s55
	s_nop 0
	global_load_lds_dwordx4 v[166:167], off
	s_barrier
	s_waitcnt lgkmcnt(0)
	s_setprio 1
	s_waitcnt lgkmcnt(0)
	v_mfma_f32_16x16x32_bf16 v[60:63], v[146:149], v[162:165], v[60:63]
	v_mfma_f32_16x16x32_bf16 v[56:59], v[154:157], v[162:165], v[56:59]
	v_mfma_f32_16x16x32_bf16 v[44:47], v[146:149], v[182:185], v[44:47]
	v_mfma_f32_16x16x32_bf16 v[40:43], v[154:157], v[182:185], v[40:43]
	v_mfma_f32_16x16x32_bf16 v[28:31], v[146:149], v[190:193], v[28:31]
	v_mfma_f32_16x16x32_bf16 v[24:27], v[154:157], v[190:193], v[24:27]
	v_mfma_f32_16x16x32_bf16 v[12:15], v[146:149], v[202:205], v[12:15]
	v_mfma_f32_16x16x32_bf16 v[8:11], v[154:157], v[202:205], v[8:11]
	v_mfma_f32_16x16x32_bf16 v[60:63], v[150:153], v[178:181], v[60:63]
	v_mfma_f32_16x16x32_bf16 v[56:59], v[158:161], v[178:181], v[56:59]
	v_mfma_f32_16x16x32_bf16 v[44:47], v[150:153], v[186:189], v[44:47]
	v_mfma_f32_16x16x32_bf16 v[40:43], v[158:161], v[186:189], v[40:43]
	v_mfma_f32_16x16x32_bf16 v[28:31], v[150:153], v[194:197], v[28:31]
	v_mfma_f32_16x16x32_bf16 v[24:27], v[158:161], v[194:197], v[24:27]
	v_mfma_f32_16x16x32_bf16 v[12:15], v[150:153], v[206:209], v[12:15]
	v_mfma_f32_16x16x32_bf16 v[8:11], v[158:161], v[206:209], v[8:11]
	s_setprio 0
	s_barrier
	s_add_u32 s4, s4, 0x40080
	s_addc_u32 s5, s5, 0
	s_add_i32 s6, s6, s44
	v_lshl_add_u64 v[146:147], s[4:5], 0, v[130:131]
	s_mov_b32 m0, s6
	s_nop 0
	global_load_lds_dwordx4 v[146:147], off
	v_lshl_add_u64 v[146:147], s[4:5], 0, v[134:135]
	s_add_i32 m0, s6, 0x2000
	s_nop 0
	global_load_lds_dwordx4 v[146:147], off
	s_waitcnt vmcnt(6)
	s_barrier
	s_setprio 1
	v_mfma_f32_16x16x32_bf16 v[52:55], v[210:213], v[162:165], v[52:55]
	v_mfma_f32_16x16x32_bf16 v[48:51], v[218:221], v[162:165], v[48:51]
	v_mfma_f32_16x16x32_bf16 v[36:39], v[210:213], v[182:185], v[36:39]
	v_mfma_f32_16x16x32_bf16 v[32:35], v[218:221], v[182:185], v[32:35]
	v_mfma_f32_16x16x32_bf16 v[20:23], v[210:213], v[190:193], v[20:23]
	v_mfma_f32_16x16x32_bf16 v[16:19], v[218:221], v[190:193], v[16:19]
	v_mfma_f32_16x16x32_bf16 v[4:7], v[210:213], v[202:205], v[4:7]
	v_mfma_f32_16x16x32_bf16 v[0:3], v[218:221], v[202:205], v[0:3]
	v_mfma_f32_16x16x32_bf16 v[52:55], v[214:217], v[178:181], v[52:55]
	v_mfma_f32_16x16x32_bf16 v[48:51], v[222:225], v[178:181], v[48:51]
	v_mfma_f32_16x16x32_bf16 v[36:39], v[214:217], v[186:189], v[36:39]
	v_mfma_f32_16x16x32_bf16 v[32:35], v[222:225], v[186:189], v[32:35]
	v_mfma_f32_16x16x32_bf16 v[20:23], v[214:217], v[194:197], v[20:23]
	v_mfma_f32_16x16x32_bf16 v[16:19], v[222:225], v[194:197], v[16:19]
	v_mfma_f32_16x16x32_bf16 v[4:7], v[214:217], v[206:209], v[4:7]
	v_mfma_f32_16x16x32_bf16 v[0:3], v[222:225], v[206:209], v[0:3]
	s_setprio 0
	s_add_i32 s67, s67, 2
	s_add_u32 s0, s0, 0x100
	s_addc_u32 s1, s1, 0
	s_add_u32 s65, s65, 0x100
	s_addc_u32 s66, s66, 0
	s_cmp_gt_u32 s67, 13
	s_barrier

; #define PG8_STAGE(bufoff, gbase, voff) do { _Pragma("unroll") for (int _i = 0; _i < 2; ++_i) \
;         __builtin_amdgcn_global_load_lds((const unsigned*)((const char*)(gbase) + (voff)[_i]), (LAS unsigned*)(lds + (bufoff) + ldsw + _i * 8192), 16, 0, 0); } while (0)
; #define PG8_LDA(dst, b, h) do { _Pragma("unroll") for (int m = 0; m < 4; ++m) _Pragma("unroll") for (int k = 0; k < 2; ++k) dst[m][k] = *(const LAS bf16x8*)(lds + PG8_SA(b, h) + aoff + m * 2048 + k * 1024); } while (0)
; #define PG8_LDB(dst, b, h) do { _Pragma("unroll") for (int n = 0; n < 2; ++n) _Pragma("unroll") for (int k = 0; k < 2; ++k) dst[n][k] = *(const LAS bf16x8*)(lds + PG8_SB(b, h) + boff + n * 2048 + k * 1024); } while (0)
; #define PG8_WAIT_V(n) asm volatile("s_waitcnt vmcnt(" #n ")" ::: "memory")
; #define PG8_WAIT_L(n) asm volatile("s_waitcnt lgkmcnt(" #n ")" ::: "memory")
; #define PG8_BAR __builtin_amdgcn_s_barrier()
; #define PG8_SCHED __builtin_amdgcn_sched_barrier(0)
; template <class Epi, class Sched>
; __device__ __forceinline__ void gemm_phase(LAS unsigned char* lds, const Gemm g, const Sched& S, const Epi& E) {
;     ...
;         const bool has_next = S.next(ui + 1, nxt);
;         const char* nA = has_next ? (const char*)g.A + (size_t)nxt.pm * tstep : cA; const char* nB = has_next ? (const char*)g.Bt + (size_t)nxt.pn * tstep : cB;
;         for (int t = 0; t < nt; t += 2) {
;             const bool last = (t == nt - 2);
;             const char* a1 = cA + (size_t)(t + 1) * kstep;
;             const char* a2 = last ? nA : cA + (size_t)(t + 2) * kstep; const char* b2 = last ? nB : cB + (size_t)(t + 2) * kstep;
;             const char* a3 = a2 + kstep; const char* b3 = b2 + kstep;
;             PG8_LDB(B0, 0, 0); PG8_SCHED; PG8_LDA(At, 0, 0); PG8_STAGE(PG8_SA(1, 1), a1 + hstep, voffA);
;             PG8_WAIT_L(8); PG8_BAR; PG8_WAIT_L(0); PG8_MMA(0, 0, At, B0); PG8_BAR; PG8_SCHED;
;             PG8_LDB(B1, 0, 1); PG8_STAGE(PG8_SB(0, 0), b2, voffB);
;             PG8_BAR; PG8_WAIT_L(0); PG8_MMA(0, 1, At, B1); PG8_BAR;
;             PG8_LDA(At, 0, 1); PG8_STAGE(PG8_SA(0, 0), a2, voffA);
;             PG8_BAR; PG8_WAIT_L(0); PG8_MMA(1, 0, At, B0); PG8_BAR; PG8_SCHED;
;             PG8_STAGE(PG8_SB(0, 1), b2 + hstep, voffB);
;             PG8_WAIT_V(6); PG8_BAR; PG8_MMA(1, 1, At, B1); PG8_BAR;
.LBB0_632:
	s_ashr_i32 s23, s22, 31
	v_cmp_lt_i64_e32 vcc, s[24:25], v[140:141]
	s_lshl_b64 s[24:25], s[22:23], 19
	s_add_u32 s24, s38, s24
	s_addc_u32 s25, s39, s25
	s_and_b64 s[26:27], vcc, exec
	s_cselect_b32 s23, s25, s31
	s_cselect_b32 s61, s24, s30
	s_ashr_i32 s21, s20, 31
	s_lshl_b64 s[26:27], s[20:21], 19
	s_add_u32 s26, s96, s26
	s_addc_u32 s27, s97, s27
	s_and_b64 s[36:37], vcc, exec
	s_cselect_b32 s21, s27, s35
	s_cselect_b32 s62, s26, s34
	s_add_u32 s30, s30, 0x40080
	s_addc_u32 s31, s31, 0
	s_add_u32 s63, s34, 0x100
	s_addc_u32 s64, s35, 0
	s_mov_b32 s65, -2
	s_waitcnt lgkmcnt(0)
	ds_read_b128 v[150:153], v147
	ds_read_b128 v[154:157], v147 offset:1024
	ds_read_b128 v[158:161], v147 offset:2048
	ds_read_b128 v[162:165], v147 offset:3072
	s_add_u32 s34, s30, 0xfffc0080
	s_addc_u32 s35, s31, -1
	s_cmp_eq_u32 s65, 12
	s_cselect_b32 s37, s23, s35
	s_cselect_b32 s36, s61, s34
	s_cselect_b32 s35, s21, s64
	s_cselect_b32 s34, s62, s63
	v_lshl_add_u64 v[198:199], s[30:31], 0, v[136:137]
	s_add_i32 m0, s29, 0xc000
	ds_read_b128 v[166:169], v148
	ds_read_b128 v[170:173], v148 offset:1024
	ds_read_b128 v[174:177], v148 offset:2048
	ds_read_b128 v[178:181], v148 offset:3072
	ds_read_b128 v[182:185], v148 offset:4096
	ds_read_b128 v[186:189], v148 offset:5120
	ds_read_b128 v[190:193], v148 offset:6144
	ds_read_b128 v[194:197], v148 offset:7168
	global_load_lds_dwordx4 v[198:199], off
	v_lshl_add_u64 v[198:199], s[30:31], 0, v[138:139]
	s_add_i32 m0, s29, 0xe000
	s_nop 0
	global_load_lds_dwordx4 v[198:199], off
	s_waitcnt lgkmcnt(8)
	s_barrier
	s_waitcnt lgkmcnt(0)
	s_setprio 1
	s_waitcnt lgkmcnt(0)
	v_mfma_f32_16x16x32_bf16 v[124:127], v[150:153], v[166:169], 0
	v_mfma_f32_16x16x32_bf16 v[120:123], v[158:161], v[166:169], 0
	v_mfma_f32_16x16x32_bf16 v[116:119], v[150:153], v[174:177], 0
	v_mfma_f32_16x16x32_bf16 v[108:111], v[158:161], v[174:177], 0
	v_mfma_f32_16x16x32_bf16 v[100:103], v[150:153], v[182:185], 0
	v_mfma_f32_16x16x32_bf16 v[92:95], v[158:161], v[182:185], 0
	v_mfma_f32_16x16x32_bf16 v[84:87], v[150:153], v[190:193], 0
	v_mfma_f32_16x16x32_bf16 v[76:79], v[158:161], v[190:193], 0
	v_mfma_f32_16x16x32_bf16 v[124:127], v[154:157], v[170:173], v[124:127]
	v_mfma_f32_16x16x32_bf16 v[120:123], v[162:165], v[170:173], v[120:123]
	v_mfma_f32_16x16x32_bf16 v[116:119], v[154:157], v[178:181], v[116:119]
	v_mfma_f32_16x16x32_bf16 v[108:111], v[162:165], v[178:181], v[108:111]
	v_mfma_f32_16x16x32_bf16 v[100:103], v[154:157], v[186:189], v[100:103]
	v_mfma_f32_16x16x32_bf16 v[92:95], v[162:165], v[186:189], v[92:95]
	v_mfma_f32_16x16x32_bf16 v[84:87], v[154:157], v[194:197], v[84:87]
	v_mfma_f32_16x16x32_bf16 v[76:79], v[162:165], v[194:197], v[76:79]
	s_setprio 0
	s_barrier
	s_add_i32 s66, s54, s43
	v_lshl_add_u64 v[198:199], s[34:35], 0, v[130:131]
	s_mov_b32 m0, s66
	ds_read_b128 v[202:205], v149
	ds_read_b128 v[206:209], v149 offset:1024
	ds_read_b128 v[210:213], v149 offset:2048
	ds_read_b128 v[214:217], v149 offset:3072
	global_load_lds_dwordx4 v[198:199], off
	v_lshl_add_u64 v[218:219], s[34:35], 0, v[134:135]
	s_add_i32 m0, s66, 0x2000
	s_nop 0
	global_load_lds_dwordx4 v[218:219], off
	s_barrier
	s_waitcnt lgkmcnt(0)
	s_setprio 1
	s_waitcnt lgkmcnt(0)
	v_mfma_f32_16x16x32_bf16 v[112:115], v[202:205], v[166:169], 0
	v_mfma_f32_16x16x32_bf16 v[104:107], v[210:213], v[166:169], 0
	v_mfma_f32_16x16x32_bf16 v[96:99], v[202:205], v[174:177], 0
	v_mfma_f32_16x16x32_bf16 v[88:91], v[210:213], v[174:177], 0
	v_mfma_f32_16x16x32_bf16 v[80:83], v[202:205], v[182:185], 0
	v_mfma_f32_16x16x32_bf16 v[72:75], v[210:213], v[182:185], 0
	v_mfma_f32_16x16x32_bf16 v[68:71], v[202:205], v[190:193], 0
	v_mfma_f32_16x16x32_bf16 v[64:67], v[210:213], v[190:193], 0
	v_mfma_f32_16x16x32_bf16 v[112:115], v[206:209], v[170:173], v[112:115]
	v_mfma_f32_16x16x32_bf16 v[104:107], v[214:217], v[170:173], v[104:107]
	v_mfma_f32_16x16x32_bf16 v[96:99], v[206:209], v[178:181], v[96:99]
	v_mfma_f32_16x16x32_bf16 v[88:91], v[214:217], v[178:181], v[88:91]
	v_mfma_f32_16x16x32_bf16 v[80:83], v[206:209], v[186:189], v[80:83]
	v_mfma_f32_16x16x32_bf16 v[72:75], v[214:217], v[186:189], v[72:75]
	v_mfma_f32_16x16x32_bf16 v[68:71], v[206:209], v[194:197], v[68:71]
	v_mfma_f32_16x16x32_bf16 v[64:67], v[214:217], v[194:197], v[64:67]
	s_setprio 0
	s_mov_b32 m0, s29
	v_lshl_add_u64 v[220:221], s[36:37], 0, v[128:129]
	s_barrier
	ds_read_b128 v[166:169], v148 offset:16384
	ds_read_b128 v[170:173], v148 offset:17408
	ds_read_b128 v[174:177], v148 offset:18432
	ds_read_b128 v[178:181], v148 offset:19456
	ds_read_b128 v[182:185], v148 offset:20480
	ds_read_b128 v[186:189], v148 offset:21504
	ds_read_b128 v[190:193], v148 offset:22528
	ds_read_b128 v[194:197], v148 offset:23552
	global_load_lds_dwordx4 v[220:221], off
	v_lshl_add_u64 v[222:223], s[36:37], 0, v[132:133]
	s_mov_b32 m0, s44
	s_nop 0
	global_load_lds_dwordx4 v[222:223], off
	s_barrier
	s_waitcnt lgkmcnt(0)
	s_setprio 1
	s_waitcnt lgkmcnt(0)
	v_mfma_f32_16x16x32_bf16 v[60:63], v[150:153], v[166:169], 0
	v_mfma_f32_16x16x32_bf16 v[56:59], v[158:161], v[166:169], 0
	v_mfma_f32_16x16x32_bf16 v[52:55], v[150:153], v[174:177], 0
	v_mfma_f32_16x16x32_bf16 v[44:47], v[158:161], v[174:177], 0
	v_mfma_f32_16x16x32_bf16 v[36:39], v[150:153], v[182:185], 0
	v_mfma_f32_16x16x32_bf16 v[28:31], v[158:161], v[182:185], 0
	v_mfma_f32_16x16x32_bf16 v[20:23], v[150:153], v[190:193], 0
	v_mfma_f32_16x16x32_bf16 v[12:15], v[158:161], v[190:193], 0
	v_mfma_f32_16x16x32_bf16 v[60:63], v[154:157], v[170:173], v[60:63]
	v_mfma_f32_16x16x32_bf16 v[56:59], v[162:165], v[170:173], v[56:59]
	v_mfma_f32_16x16x32_bf16 v[52:55], v[154:157], v[178:181], v[52:55]
	v_mfma_f32_16x16x32_bf16 v[44:47], v[162:165], v[178:181], v[44:47]
	v_mfma_f32_16x16x32_bf16 v[36:39], v[154:157], v[186:189], v[36:39]
	v_mfma_f32_16x16x32_bf16 v[28:31], v[162:165], v[186:189], v[28:31]
	v_mfma_f32_16x16x32_bf16 v[20:23], v[154:157], v[194:197], v[20:23]
	v_mfma_f32_16x16x32_bf16 v[12:15], v[162:165], v[194:197], v[12:15]
	s_setprio 0
	s_barrier
; #define PG8_STAGE(bufoff, gbase, voff) do { _Pragma("unroll") for (int _i = 0; _i < 2; ++_i) \
;         __builtin_amdgcn_global_load_lds((const unsigned*)((const char*)(gbase) + (voff)[_i]), (LAS unsigned*)(lds + (bufoff) + ldsw + _i * 8192), 16, 0, 0); } while (0)
; #define PG8_LDA(dst, b, h) do { _Pragma("unroll") for (int m = 0; m < 4; ++m) _Pragma("unroll") for (int k = 0; k < 2; ++k) dst[m][k] = *(const LAS bf16x8*)(lds + PG8_SA(b, h) + aoff + m * 2048 + k * 1024); } while (0)
; #define PG8_LDB(dst, b, h) do { _Pragma("unroll") for (int n = 0; n < 2; ++n) _Pragma("unroll") for (int k = 0; k < 2; ++k) dst[n][k] = *(const LAS bf16x8*)(lds + PG8_SB(b, h) + boff + n * 2048 + k * 1024); } while (0)
; #define PG8_MMA(ai, bj, At, Bt) do { __builtin_amdgcn_s_setprio(1); _Pragma("unroll") for (int m = 0; m < 4; ++m) _Pragma("unroll") for (int n = 0; n < 2; ++n) _Pragma("unroll") for (int k = 0; k < 2; ++k) \
;         acc[ai][bj][m][n] = __builtin_amdgcn_mfma_f32_16x16x32_bf16(Bt[n][k], At[m][k], acc[ai][bj][m][n], 0, 0, 0); __builtin_amdgcn_s_setprio(0); } while (0)
; #define PG8_WAIT_V(n) asm volatile("s_waitcnt vmcnt(" #n ")" ::: "memory")
; #define PG8_WAIT_L(n) asm volatile("s_waitcnt lgkmcnt(" #n ")" ::: "memory")
; #define PG8_BAR __builtin_amdgcn_s_barrier()
; #define PG8_SCHED __builtin_amdgcn_sched_barrier(0)
; template <class Epi, class Sched>
; __device__ __forceinline__ void gemm_phase(LAS unsigned char* lds, const Gemm g, const Sched& S, const Epi& E) {
;     ...
;             PG8_STAGE(PG8_SB(0, 1), b2 + hstep, voffB);
;             PG8_WAIT_V(6); PG8_BAR; PG8_MMA(1, 1, At, B1); PG8_BAR;
;             PG8_LDB(B0, 1, 0); PG8_SCHED; PG8_LDA(At, 1, 0); PG8_STAGE(PG8_SA(0, 1), a2 + hstep, voffA);
;             PG8_WAIT_L(8); PG8_BAR; PG8_WAIT_L(0); PG8_MMA(0, 0, At, B0); PG8_BAR; PG8_SCHED;
;             PG8_LDB(B1, 1, 1); PG8_STAGE(PG8_SB(1, 0), b3, voffB);
	s_add_u32 s66, s34, 0x40000
	s_addc_u32 s67, s35, 0
	s_add_i32 s68, s55, s43
	v_lshl_add_u64 v[150:151], s[66:67], 0, v[130:131]
	s_mov_b32 m0, s68
	s_nop 0
	global_load_lds_dwordx4 v[150:151], off
	v_lshl_add_u64 v[150:151], s[66:67], 0, v[134:135]
	s_add_i32 m0, s68, 0x2000
	s_nop 0
	global_load_lds_dwordx4 v[150:151], off
	s_waitcnt vmcnt(6)
	s_barrier
	s_setprio 1
	v_mfma_f32_16x16x32_bf16 v[48:51], v[202:205], v[166:169], 0
	v_mfma_f32_16x16x32_bf16 v[40:43], v[210:213], v[166:169], 0
	v_mfma_f32_16x16x32_bf16 v[32:35], v[202:205], v[174:177], 0
	v_mfma_f32_16x16x32_bf16 v[24:27], v[210:213], v[174:177], 0
	v_mfma_f32_16x16x32_bf16 v[16:19], v[202:205], v[182:185], 0
	v_mfma_f32_16x16x32_bf16 v[8:11], v[210:213], v[182:185], 0
	v_mfma_f32_16x16x32_bf16 v[4:7], v[202:205], v[190:193], 0
	v_mfma_f32_16x16x32_bf16 v[0:3], v[210:213], v[190:193], 0
	v_mfma_f32_16x16x32_bf16 v[48:51], v[206:209], v[170:173], v[48:51]
	v_mfma_f32_16x16x32_bf16 v[40:43], v[214:217], v[170:173], v[40:43]
	v_mfma_f32_16x16x32_bf16 v[32:35], v[206:209], v[178:181], v[32:35]
	v_mfma_f32_16x16x32_bf16 v[24:27], v[214:217], v[178:181], v[24:27]
	v_mfma_f32_16x16x32_bf16 v[16:19], v[206:209], v[186:189], v[16:19]
	v_mfma_f32_16x16x32_bf16 v[8:11], v[214:217], v[186:189], v[8:11]
	v_mfma_f32_16x16x32_bf16 v[4:7], v[206:209], v[194:197], v[4:7]
	v_mfma_f32_16x16x32_bf16 v[0:3], v[214:217], v[194:197], v[0:3]
	s_setprio 0
	s_add_i32 s66, 0, 0x18000
	v_add_u32_e32 v162, s66, v146
	s_barrier
	ds_read_b128 v[150:153], v162
	ds_read_b128 v[154:157], v162 offset:1024
	ds_read_b128 v[158:161], v162 offset:2048
	ds_read_b128 v[162:165], v162 offset:3072
	s_add_u32 s36, s36, 0x40000
	s_addc_u32 s37, s37, 0
	s_mov_b32 m0, s45
	v_lshl_add_u64 v[202:203], s[36:37], 0, v[128:129]
	ds_read_b128 v[166:169], v148 offset:32768
	ds_read_b128 v[170:173], v148 offset:33792
	ds_read_b128 v[174:177], v148 offset:34816
	ds_read_b128 v[178:181], v148 offset:35840
	ds_read_b128 v[182:185], v148 offset:36864
	ds_read_b128 v[186:189], v148 offset:37888
	ds_read_b128 v[190:193], v148 offset:38912
	ds_read_b128 v[194:197], v148 offset:39936
	global_load_lds_dwordx4 v[202:203], off
	v_lshl_add_u64 v[202:203], s[36:37], 0, v[132:133]
	s_mov_b32 m0, s46
	s_nop 0
	global_load_lds_dwordx4 v[202:203], off
	s_waitcnt lgkmcnt(8)
	s_barrier
	s_waitcnt lgkmcnt(0)
	s_setprio 1
	s_waitcnt lgkmcnt(0)
	v_mfma_f32_16x16x32_bf16 v[124:127], v[150:153], v[166:169], v[124:127]
	v_mfma_f32_16x16x32_bf16 v[120:123], v[158:161], v[166:169], v[120:123]
	v_mfma_f32_16x16x32_bf16 v[116:119], v[150:153], v[174:177], v[116:119]
	v_mfma_f32_16x16x32_bf16 v[108:111], v[158:161], v[174:177], v[108:111]
	v_mfma_f32_16x16x32_bf16 v[100:103], v[150:153], v[182:185], v[100:103]
	v_mfma_f32_16x16x32_bf16 v[92:95], v[158:161], v[182:185], v[92:95]
	v_mfma_f32_16x16x32_bf16 v[84:87], v[150:153], v[190:193], v[84:87]
	v_mfma_f32_16x16x32_bf16 v[76:79], v[158:161], v[190:193], v[76:79]
	v_mfma_f32_16x16x32_bf16 v[124:127], v[154:157], v[170:173], v[124:127]
	v_mfma_f32_16x16x32_bf16 v[120:123], v[162:165], v[170:173], v[120:123]
	v_mfma_f32_16x16x32_bf16 v[116:119], v[154:157], v[178:181], v[116:119]
	v_mfma_f32_16x16x32_bf16 v[108:111], v[162:165], v[178:181], v[108:111]
	v_mfma_f32_16x16x32_bf16 v[100:103], v[154:157], v[186:189], v[100:103]
	v_mfma_f32_16x16x32_bf16 v[92:95], v[162:165], v[186:189], v[92:95]
	v_mfma_f32_16x16x32_bf16 v[84:87], v[154:157], v[194:197], v[84:87]
	v_mfma_f32_16x16x32_bf16 v[76:79], v[162:165], v[194:197], v[76:79]
	s_setprio 0
	s_barrier
	s_add_i32 s36, 0, 0x1c000
	s_add_i32 s37, s66, s43
	v_add_u32_e32 v214, s36, v146
	v_lshl_add_u64 v[198:199], v[198:199], 0, s[4:5]
	s_mov_b32 m0, s37
	ds_read_b128 v[202:205], v214
	ds_read_b128 v[206:209], v214 offset:1024
	ds_read_b128 v[210:213], v214 offset:2048
	ds_read_b128 v[214:217], v214 offset:3072
	global_load_lds_dwordx4 v[198:199], off
	v_lshl_add_u64 v[198:199], v[218:219], 0, s[4:5]
	s_add_i32 m0, s37, 0x2000
	s_nop 0
	global_load_lds_dwordx4 v[198:199], off
	s_barrier
; #define PG8_STAGE(bufoff, gbase, voff) do { _Pragma("unroll") for (int _i = 0; _i < 2; ++_i) \
;         __builtin_amdgcn_global_load_lds((const unsigned*)((const char*)(gbase) + (voff)[_i]), (LAS unsigned*)(lds + (bufoff) + ldsw + _i * 8192), 16, 0, 0); } while (0)
; #define PG8_LDA(dst, b, h) do { _Pragma("unroll") for (int m = 0; m < 4; ++m) _Pragma("unroll") for (int k = 0; k < 2; ++k) dst[m][k] = *(const LAS bf16x8*)(lds + PG8_SA(b, h) + aoff + m * 2048 + k * 1024); } while (0)
; #define PG8_MMA(ai, bj, At, Bt) do { __builtin_amdgcn_s_setprio(1); _Pragma("unroll") for (int m = 0; m < 4; ++m) _Pragma("unroll") for (int n = 0; n < 2; ++n) _Pragma("unroll") for (int k = 0; k < 2; ++k) \
;         acc[ai][bj][m][n] = __builtin_amdgcn_mfma_f32_16x16x32_bf16(Bt[n][k], At[m][k], acc[ai][bj][m][n], 0, 0, 0); __builtin_amdgcn_s_setprio(0); } while (0)
; #define PG8_WAIT_V(n) asm volatile("s_waitcnt vmcnt(" #n ")" ::: "memory")
; #define PG8_WAIT_L(n) asm volatile("s_waitcnt lgkmcnt(" #n ")" ::: "memory")
; #define PG8_BAR __builtin_amdgcn_s_barrier()
; #define PG8_SCHED __builtin_amdgcn_sched_barrier(0)
; template <class Epi, class Sched>
; __device__ __forceinline__ void gemm_phase(LAS unsigned char* lds, const Gemm g, const Sched& S, const Epi& E) {
;     ...
;             PG8_LDA(At, 1, 1); PG8_STAGE(PG8_SA(1, 0), a3, voffA);
;             PG8_BAR; PG8_WAIT_L(0); PG8_MMA(1, 0, At, B0); PG8_BAR; PG8_SCHED;
;             PG8_STAGE(PG8_SB(1, 1), b3 + hstep, voffB);
;             PG8_WAIT_V(6); PG8_BAR; PG8_MMA(1, 1, At, B1); PG8_BAR;
;         }
	s_waitcnt lgkmcnt(0)
	s_setprio 1
	s_waitcnt lgkmcnt(0)
	v_mfma_f32_16x16x32_bf16 v[112:115], v[202:205], v[166:169], v[112:115]
	v_mfma_f32_16x16x32_bf16 v[104:107], v[210:213], v[166:169], v[104:107]
	v_mfma_f32_16x16x32_bf16 v[96:99], v[202:205], v[174:177], v[96:99]
	v_mfma_f32_16x16x32_bf16 v[88:91], v[210:213], v[174:177], v[88:91]
	v_mfma_f32_16x16x32_bf16 v[80:83], v[202:205], v[182:185], v[80:83]
	v_mfma_f32_16x16x32_bf16 v[72:75], v[210:213], v[182:185], v[72:75]
	v_mfma_f32_16x16x32_bf16 v[68:71], v[202:205], v[190:193], v[68:71]
	v_mfma_f32_16x16x32_bf16 v[64:67], v[210:213], v[190:193], v[64:67]
	v_mfma_f32_16x16x32_bf16 v[112:115], v[206:209], v[170:173], v[112:115]
	v_mfma_f32_16x16x32_bf16 v[104:107], v[214:217], v[170:173], v[104:107]
	v_mfma_f32_16x16x32_bf16 v[96:99], v[206:209], v[178:181], v[96:99]
	v_mfma_f32_16x16x32_bf16 v[88:91], v[214:217], v[178:181], v[88:91]
	v_mfma_f32_16x16x32_bf16 v[80:83], v[206:209], v[186:189], v[80:83]
	v_mfma_f32_16x16x32_bf16 v[72:75], v[214:217], v[186:189], v[72:75]
	v_mfma_f32_16x16x32_bf16 v[68:71], v[206:209], v[194:197], v[68:71]
	v_mfma_f32_16x16x32_bf16 v[64:67], v[214:217], v[194:197], v[64:67]
	s_setprio 0
	s_mov_b32 m0, s51
	v_lshl_add_u64 v[198:199], v[220:221], 0, s[4:5]
	s_barrier
	ds_read_b128 v[166:169], v148 offset:49152
	ds_read_b128 v[170:173], v148 offset:50176
	ds_read_b128 v[174:177], v148 offset:51200
	ds_read_b128 v[178:181], v148 offset:52224
	ds_read_b128 v[182:185], v148 offset:53248
	ds_read_b128 v[186:189], v148 offset:54272
	ds_read_b128 v[190:193], v148 offset:55296
	ds_read_b128 v[194:197], v148 offset:56320
	global_load_lds_dwordx4 v[198:199], off
	v_lshl_add_u64 v[198:199], v[222:223], 0, s[4:5]
	s_mov_b32 m0, s52
	s_nop 0
	global_load_lds_dwordx4 v[198:199], off
	s_barrier
	s_waitcnt lgkmcnt(0)
	s_setprio 1
	s_waitcnt lgkmcnt(0)
	v_mfma_f32_16x16x32_bf16 v[60:63], v[150:153], v[166:169], v[60:63]
	v_mfma_f32_16x16x32_bf16 v[56:59], v[158:161], v[166:169], v[56:59]
	v_mfma_f32_16x16x32_bf16 v[52:55], v[150:153], v[174:177], v[52:55]
	v_mfma_f32_16x16x32_bf16 v[44:47], v[158:161], v[174:177], v[44:47]
	v_mfma_f32_16x16x32_bf16 v[36:39], v[150:153], v[182:185], v[36:39]
	v_mfma_f32_16x16x32_bf16 v[28:31], v[158:161], v[182:185], v[28:31]
	v_mfma_f32_16x16x32_bf16 v[20:23], v[150:153], v[190:193], v[20:23]
	v_mfma_f32_16x16x32_bf16 v[12:15], v[158:161], v[190:193], v[12:15]
	v_mfma_f32_16x16x32_bf16 v[60:63], v[154:157], v[170:173], v[60:63]
	v_mfma_f32_16x16x32_bf16 v[56:59], v[162:165], v[170:173], v[56:59]
	v_mfma_f32_16x16x32_bf16 v[52:55], v[154:157], v[178:181], v[52:55]
	v_mfma_f32_16x16x32_bf16 v[44:47], v[162:165], v[178:181], v[44:47]
	v_mfma_f32_16x16x32_bf16 v[36:39], v[154:157], v[186:189], v[36:39]
	v_mfma_f32_16x16x32_bf16 v[28:31], v[162:165], v[186:189], v[28:31]
	v_mfma_f32_16x16x32_bf16 v[20:23], v[154:157], v[194:197], v[20:23]
	v_mfma_f32_16x16x32_bf16 v[12:15], v[162:165], v[194:197], v[12:15]
	s_setprio 0
	s_barrier
	s_add_u32 s34, s34, 0x40080
	s_addc_u32 s35, s35, 0
	s_add_i32 s36, s36, s43
	v_lshl_add_u64 v[150:151], s[34:35], 0, v[130:131]
	s_mov_b32 m0, s36
	s_nop 0
	global_load_lds_dwordx4 v[150:151], off
	v_lshl_add_u64 v[150:151], s[34:35], 0, v[134:135]
	s_add_i32 m0, s36, 0x2000
	s_nop 0
	global_load_lds_dwordx4 v[150:151], off
	s_waitcnt vmcnt(6)
	s_barrier
	s_setprio 1
	v_mfma_f32_16x16x32_bf16 v[48:51], v[202:205], v[166:169], v[48:51]
	v_mfma_f32_16x16x32_bf16 v[40:43], v[210:213], v[166:169], v[40:43]
	v_mfma_f32_16x16x32_bf16 v[32:35], v[202:205], v[174:177], v[32:35]
	v_mfma_f32_16x16x32_bf16 v[24:27], v[210:213], v[174:177], v[24:27]
	v_mfma_f32_16x16x32_bf16 v[16:19], v[202:205], v[182:185], v[16:19]
	v_mfma_f32_16x16x32_bf16 v[8:11], v[210:213], v[182:185], v[8:11]
	v_mfma_f32_16x16x32_bf16 v[4:7], v[202:205], v[190:193], v[4:7]
	v_mfma_f32_16x16x32_bf16 v[0:3], v[210:213], v[190:193], v[0:3]
	v_mfma_f32_16x16x32_bf16 v[48:51], v[206:209], v[170:173], v[48:51]
	v_mfma_f32_16x16x32_bf16 v[40:43], v[214:217], v[170:173], v[40:43]
	v_mfma_f32_16x16x32_bf16 v[32:35], v[206:209], v[178:181], v[32:35]
	v_mfma_f32_16x16x32_bf16 v[24:27], v[214:217], v[178:181], v[24:27]
	v_mfma_f32_16x16x32_bf16 v[16:19], v[206:209], v[186:189], v[16:19]
	v_mfma_f32_16x16x32_bf16 v[8:11], v[214:217], v[186:189], v[8:11]
	v_mfma_f32_16x16x32_bf16 v[4:7], v[206:209], v[194:197], v[4:7]
	v_mfma_f32_16x16x32_bf16 v[0:3], v[214:217], v[194:197], v[0:3]
	s_setprio 0
	s_add_i32 s65, s65, 2
	s_add_u32 s30, s30, 0x100
	s_addc_u32 s31, s31, 0
	s_add_u32 s63, s63, 0x100
	s_addc_u32 s64, s64, 0
	s_cmp_gt_u32 s65, 13
	s_barrier

; #define PG8_STAGE(bufoff, gbase, voff) do { _Pragma("unroll") for (int _i = 0; _i < 2; ++_i) \
;         __builtin_amdgcn_global_load_lds((const unsigned*)((const char*)(gbase) + (voff)[_i]), (LAS unsigned*)(lds + (bufoff) + ldsw + _i * 8192), 16, 0, 0); } while (0)
; #define PG8_LDA(dst, b, h) do { _Pragma("unroll") for (int m = 0; m < 4; ++m) _Pragma("unroll") for (int k = 0; k < 2; ++k) dst[m][k] = *(const LAS bf16x8*)(lds + PG8_SA(b, h) + aoff + m * 2048 + k * 1024); } while (0)
; #define PG8_LDB(dst, b, h) do { _Pragma("unroll") for (int n = 0; n < 2; ++n) _Pragma("unroll") for (int k = 0; k < 2; ++k) dst[n][k] = *(const LAS bf16x8*)(lds + PG8_SB(b, h) + boff + n * 2048 + k * 1024); } while (0)
; #define PG8_WAIT_V(n) asm volatile("s_waitcnt vmcnt(" #n ")" ::: "memory")
; #define PG8_WAIT_L(n) asm volatile("s_waitcnt lgkmcnt(" #n ")" ::: "memory")
; #define PG8_BAR __builtin_amdgcn_s_barrier()
; #define PG8_SCHED __builtin_amdgcn_sched_barrier(0)
; template <class Epi, class Sched>
; __device__ __forceinline__ void gemm_phase(LAS unsigned char* lds, const Gemm g, const Sched& S, const Epi& E) {
;     ...
;         const bool has_next = S.next(ui + 1, nxt);
;         const char* nA = has_next ? (const char*)g.A + (size_t)nxt.pm * tstep : cA; const char* nB = has_next ? (const char*)g.Bt + (size_t)nxt.pn * tstep : cB;
;         for (int t = 0; t < nt; t += 2) {
;             const bool last = (t == nt - 2);
;             const char* a1 = cA + (size_t)(t + 1) * kstep;
;             const char* a2 = last ? nA : cA + (size_t)(t + 2) * kstep; const char* b2 = last ? nB : cB + (size_t)(t + 2) * kstep;
;             const char* a3 = a2 + kstep; const char* b3 = b2 + kstep;
;             PG8_LDB(B0, 0, 0); PG8_SCHED; PG8_LDA(At, 0, 0); PG8_STAGE(PG8_SA(1, 1), a1 + hstep, voffA);
;             PG8_WAIT_L(8); PG8_BAR; PG8_WAIT_L(0); PG8_MMA(0, 0, At, B0); PG8_BAR; PG8_SCHED;
;             PG8_LDB(B1, 0, 1); PG8_STAGE(PG8_SB(0, 0), b2, voffB);
;             PG8_BAR; PG8_WAIT_L(0); PG8_MMA(0, 1, At, B1); PG8_BAR;
;             PG8_LDA(At, 0, 1); PG8_STAGE(PG8_SA(0, 0), a2, voffA);
;             PG8_BAR; PG8_WAIT_L(0); PG8_MMA(1, 0, At, B0); PG8_BAR; PG8_SCHED;
;             PG8_STAGE(PG8_SB(0, 1), b2 + hstep, voffB);
;             PG8_WAIT_V(6); PG8_BAR; PG8_MMA(1, 1, At, B1); PG8_BAR;
.LBB0_652:
	s_ashr_i32 s9, s8, 31
	v_cmp_lt_i64_e32 vcc, s[16:17], v[142:143]
	s_lshl_b64 s[16:17], s[8:9], 19
	s_add_u32 s16, s14, s16
	s_addc_u32 s17, s15, s17
	s_and_b64 s[18:19], vcc, exec
	s_cselect_b32 s9, s17, s23
	s_cselect_b32 s48, s16, s22
	s_ashr_i32 s7, s6, 31
	s_lshl_b64 s[18:19], s[6:7], 19
	s_add_u32 s18, s12, s18
	s_addc_u32 s19, s13, s19
	s_and_b64 s[26:27], vcc, exec
	s_cselect_b32 s7, s19, s25
	s_cselect_b32 s49, s18, s24
	s_add_u32 s22, s22, 0x40080
	s_addc_u32 s23, s23, 0
	s_add_u32 s51, s24, 0x100
	s_addc_u32 s52, s25, 0
	s_mov_b32 s53, -2
	s_waitcnt lgkmcnt(0)
	ds_read_b128 v[152:155], v149
	ds_read_b128 v[156:159], v149 offset:1024
	ds_read_b128 v[160:163], v149 offset:2048
	ds_read_b128 v[164:167], v149 offset:3072
	s_add_u32 s24, s22, 0xfffc0080
	s_addc_u32 s25, s23, -1
	s_cmp_eq_u32 s53, 12
	s_cselect_b32 s27, s9, s25
	s_cselect_b32 s26, s48, s24
	s_cselect_b32 s25, s7, s52
	s_cselect_b32 s24, s49, s51
	v_lshl_add_u64 v[202:203], s[22:23], 0, v[138:139]
	s_add_i32 m0, s21, 0xc000
	ds_read_b128 v[168:171], v150
	ds_read_b128 v[172:175], v150 offset:1024
	ds_read_b128 v[176:179], v150 offset:2048
	ds_read_b128 v[180:183], v150 offset:3072
	ds_read_b128 v[184:187], v150 offset:4096
	ds_read_b128 v[188:191], v150 offset:5120
	ds_read_b128 v[192:195], v150 offset:6144
	ds_read_b128 v[196:199], v150 offset:7168
	global_load_lds_dwordx4 v[202:203], off
	v_lshl_add_u64 v[202:203], s[22:23], 0, v[140:141]
	s_add_i32 m0, s21, 0xe000
	s_nop 0
	global_load_lds_dwordx4 v[202:203], off
	s_waitcnt lgkmcnt(8)
	s_barrier
	s_waitcnt lgkmcnt(0)
	s_setprio 1
	s_waitcnt lgkmcnt(0)
	v_mfma_f32_16x16x32_bf16 v[124:127], v[152:155], v[168:171], 0
	v_mfma_f32_16x16x32_bf16 v[120:123], v[160:163], v[168:171], 0
	v_mfma_f32_16x16x32_bf16 v[112:115], v[152:155], v[176:179], 0
	v_mfma_f32_16x16x32_bf16 v[104:107], v[160:163], v[176:179], 0
	v_mfma_f32_16x16x32_bf16 v[96:99], v[152:155], v[184:187], 0
	v_mfma_f32_16x16x32_bf16 v[88:91], v[160:163], v[184:187], 0
	v_mfma_f32_16x16x32_bf16 v[80:83], v[152:155], v[192:195], 0
	v_mfma_f32_16x16x32_bf16 v[72:75], v[160:163], v[192:195], 0
	v_mfma_f32_16x16x32_bf16 v[124:127], v[156:159], v[172:175], v[124:127]
	v_mfma_f32_16x16x32_bf16 v[120:123], v[164:167], v[172:175], v[120:123]
	v_mfma_f32_16x16x32_bf16 v[112:115], v[156:159], v[180:183], v[112:115]
	v_mfma_f32_16x16x32_bf16 v[104:107], v[164:167], v[180:183], v[104:107]
	v_mfma_f32_16x16x32_bf16 v[96:99], v[156:159], v[188:191], v[96:99]
	v_mfma_f32_16x16x32_bf16 v[88:91], v[164:167], v[188:191], v[88:91]
	v_mfma_f32_16x16x32_bf16 v[80:83], v[156:159], v[196:199], v[80:83]
	v_mfma_f32_16x16x32_bf16 v[72:75], v[164:167], v[196:199], v[72:75]
	s_setprio 0
	s_barrier
	s_add_i32 s54, s45, s30
	v_lshl_add_u64 v[218:219], s[24:25], 0, v[130:131]
	s_mov_b32 m0, s54
	ds_read_b128 v[202:205], v151
	ds_read_b128 v[206:209], v151 offset:1024
	ds_read_b128 v[210:213], v151 offset:2048
	ds_read_b128 v[214:217], v151 offset:3072
	global_load_lds_dwordx4 v[218:219], off
	v_lshl_add_u64 v[220:221], s[24:25], 0, v[134:135]
	s_add_i32 m0, s54, 0x2000
	s_nop 0
	global_load_lds_dwordx4 v[220:221], off
	s_barrier
	s_waitcnt lgkmcnt(0)
	s_setprio 1
	s_waitcnt lgkmcnt(0)
	v_mfma_f32_16x16x32_bf16 v[116:119], v[202:205], v[168:171], 0
	v_mfma_f32_16x16x32_bf16 v[108:111], v[210:213], v[168:171], 0
	v_mfma_f32_16x16x32_bf16 v[100:103], v[202:205], v[176:179], 0
	v_mfma_f32_16x16x32_bf16 v[92:95], v[210:213], v[176:179], 0
	v_mfma_f32_16x16x32_bf16 v[84:87], v[202:205], v[184:187], 0
	v_mfma_f32_16x16x32_bf16 v[76:79], v[210:213], v[184:187], 0
	v_mfma_f32_16x16x32_bf16 v[68:71], v[202:205], v[192:195], 0
	v_mfma_f32_16x16x32_bf16 v[64:67], v[210:213], v[192:195], 0
	v_mfma_f32_16x16x32_bf16 v[116:119], v[206:209], v[172:175], v[116:119]
	v_mfma_f32_16x16x32_bf16 v[108:111], v[214:217], v[172:175], v[108:111]
	v_mfma_f32_16x16x32_bf16 v[100:103], v[206:209], v[180:183], v[100:103]
	v_mfma_f32_16x16x32_bf16 v[92:95], v[214:217], v[180:183], v[92:95]
	v_mfma_f32_16x16x32_bf16 v[84:87], v[206:209], v[188:191], v[84:87]
	v_mfma_f32_16x16x32_bf16 v[76:79], v[214:217], v[188:191], v[76:79]
	v_mfma_f32_16x16x32_bf16 v[68:71], v[206:209], v[196:199], v[68:71]
	v_mfma_f32_16x16x32_bf16 v[64:67], v[214:217], v[196:199], v[64:67]
	s_setprio 0
	s_mov_b32 m0, s21
	v_lshl_add_u64 v[222:223], s[26:27], 0, v[128:129]
	s_barrier
	ds_read_b128 v[168:171], v150 offset:16384
	ds_read_b128 v[172:175], v150 offset:17408
	ds_read_b128 v[176:179], v150 offset:18432
	ds_read_b128 v[180:183], v150 offset:19456
	ds_read_b128 v[184:187], v150 offset:20480
	ds_read_b128 v[188:191], v150 offset:21504
	ds_read_b128 v[192:195], v150 offset:22528
	ds_read_b128 v[196:199], v150 offset:23552
	global_load_lds_dwordx4 v[222:223], off
	v_lshl_add_u64 v[224:225], s[26:27], 0, v[132:133]
	s_mov_b32 m0, s31
	s_nop 0
	global_load_lds_dwordx4 v[224:225], off
	s_barrier
	s_waitcnt lgkmcnt(0)
	s_setprio 1
	s_waitcnt lgkmcnt(0)
	v_mfma_f32_16x16x32_bf16 v[60:63], v[152:155], v[168:171], 0
	v_mfma_f32_16x16x32_bf16 v[56:59], v[160:163], v[168:171], 0
	v_mfma_f32_16x16x32_bf16 v[48:51], v[152:155], v[176:179], 0
	v_mfma_f32_16x16x32_bf16 v[40:43], v[160:163], v[176:179], 0
	v_mfma_f32_16x16x32_bf16 v[32:35], v[152:155], v[184:187], 0
	v_mfma_f32_16x16x32_bf16 v[24:27], v[160:163], v[184:187], 0
	v_mfma_f32_16x16x32_bf16 v[16:19], v[152:155], v[192:195], 0
	v_mfma_f32_16x16x32_bf16 v[8:11], v[160:163], v[192:195], 0
	v_mfma_f32_16x16x32_bf16 v[60:63], v[156:159], v[172:175], v[60:63]
	v_mfma_f32_16x16x32_bf16 v[56:59], v[164:167], v[172:175], v[56:59]
	v_mfma_f32_16x16x32_bf16 v[48:51], v[156:159], v[180:183], v[48:51]
	v_mfma_f32_16x16x32_bf16 v[40:43], v[164:167], v[180:183], v[40:43]
	v_mfma_f32_16x16x32_bf16 v[32:35], v[156:159], v[188:191], v[32:35]
	v_mfma_f32_16x16x32_bf16 v[24:27], v[164:167], v[188:191], v[24:27]
	v_mfma_f32_16x16x32_bf16 v[16:19], v[156:159], v[196:199], v[16:19]
	v_mfma_f32_16x16x32_bf16 v[8:11], v[164:167], v[196:199], v[8:11]
	s_setprio 0
	s_barrier
; #define PG8_STAGE(bufoff, gbase, voff) do { _Pragma("unroll") for (int _i = 0; _i < 2; ++_i) \
;         __builtin_amdgcn_global_load_lds((const unsigned*)((const char*)(gbase) + (voff)[_i]), (LAS unsigned*)(lds + (bufoff) + ldsw + _i * 8192), 16, 0, 0); } while (0)
; #define PG8_LDA(dst, b, h) do { _Pragma("unroll") for (int m = 0; m < 4; ++m) _Pragma("unroll") for (int k = 0; k < 2; ++k) dst[m][k] = *(const LAS bf16x8*)(lds + PG8_SA(b, h) + aoff + m * 2048 + k * 1024); } while (0)
; #define PG8_LDB(dst, b, h) do { _Pragma("unroll") for (int n = 0; n < 2; ++n) _Pragma("unroll") for (int k = 0; k < 2; ++k) dst[n][k] = *(const LAS bf16x8*)(lds + PG8_SB(b, h) + boff + n * 2048 + k * 1024); } while (0)
; #define PG8_MMA(ai, bj, At, Bt) do { __builtin_amdgcn_s_setprio(1); _Pragma("unroll") for (int m = 0; m < 4; ++m) _Pragma("unroll") for (int n = 0; n < 2; ++n) _Pragma("unroll") for (int k = 0; k < 2; ++k) \
;         acc[ai][bj][m][n] = __builtin_amdgcn_mfma_f32_16x16x32_bf16(Bt[n][k], At[m][k], acc[ai][bj][m][n], 0, 0, 0); __builtin_amdgcn_s_setprio(0); } while (0)
; #define PG8_WAIT_V(n) asm volatile("s_waitcnt vmcnt(" #n ")" ::: "memory")
; #define PG8_WAIT_L(n) asm volatile("s_waitcnt lgkmcnt(" #n ")" ::: "memory")
; #define PG8_BAR __builtin_amdgcn_s_barrier()
; #define PG8_SCHED __builtin_amdgcn_sched_barrier(0)
; template <class Epi, class Sched>
; __device__ __forceinline__ void gemm_phase(LAS unsigned char* lds, const Gemm g, const Sched& S, const Epi& E) {
;     ...
;             PG8_STAGE(PG8_SB(0, 1), b2 + hstep, voffB);
;             PG8_WAIT_V(6); PG8_BAR; PG8_MMA(1, 1, At, B1); PG8_BAR;
;             PG8_LDB(B0, 1, 0); PG8_SCHED; PG8_LDA(At, 1, 0); PG8_STAGE(PG8_SA(0, 1), a2 + hstep, voffA);
;             PG8_WAIT_L(8); PG8_BAR; PG8_WAIT_L(0); PG8_MMA(0, 0, At, B0); PG8_BAR; PG8_SCHED;
;             PG8_LDB(B1, 1, 1); PG8_STAGE(PG8_SB(1, 0), b3, voffB);
	s_add_u32 s54, s24, 0x40000
	s_addc_u32 s55, s25, 0
	s_add_i32 s56, s46, s30
	v_lshl_add_u64 v[152:153], s[54:55], 0, v[130:131]
	s_mov_b32 m0, s56
	s_nop 0
	global_load_lds_dwordx4 v[152:153], off
	v_lshl_add_u64 v[152:153], s[54:55], 0, v[134:135]
	s_add_i32 m0, s56, 0x2000
	s_nop 0
	global_load_lds_dwordx4 v[152:153], off
	s_waitcnt vmcnt(6)
	s_barrier
	s_setprio 1
	v_mfma_f32_16x16x32_bf16 v[52:55], v[202:205], v[168:171], 0
	v_mfma_f32_16x16x32_bf16 v[44:47], v[210:213], v[168:171], 0
	v_mfma_f32_16x16x32_bf16 v[36:39], v[202:205], v[176:179], 0
	v_mfma_f32_16x16x32_bf16 v[28:31], v[210:213], v[176:179], 0
	v_mfma_f32_16x16x32_bf16 v[20:23], v[202:205], v[184:187], 0
	v_mfma_f32_16x16x32_bf16 v[12:15], v[210:213], v[184:187], 0
	v_mfma_f32_16x16x32_bf16 v[4:7], v[202:205], v[192:195], 0
	v_mfma_f32_16x16x32_bf16 v[0:3], v[210:213], v[192:195], 0
	v_mfma_f32_16x16x32_bf16 v[52:55], v[206:209], v[172:175], v[52:55]
	v_mfma_f32_16x16x32_bf16 v[44:47], v[214:217], v[172:175], v[44:47]
	v_mfma_f32_16x16x32_bf16 v[36:39], v[206:209], v[180:183], v[36:39]
	v_mfma_f32_16x16x32_bf16 v[28:31], v[214:217], v[180:183], v[28:31]
	v_mfma_f32_16x16x32_bf16 v[20:23], v[206:209], v[188:191], v[20:23]
	v_mfma_f32_16x16x32_bf16 v[12:15], v[214:217], v[188:191], v[12:15]
	v_mfma_f32_16x16x32_bf16 v[4:7], v[206:209], v[196:199], v[4:7]
	v_mfma_f32_16x16x32_bf16 v[0:3], v[214:217], v[196:199], v[0:3]
	s_setprio 0
	s_add_i32 s54, 0, 0x18000
	v_add_u32_e32 v136, s54, v148
	s_barrier
	ds_read_b128 v[152:155], v136
	ds_read_b128 v[156:159], v136 offset:1024
	ds_read_b128 v[160:163], v136 offset:2048
	ds_read_b128 v[164:167], v136 offset:3072
	s_add_u32 s26, s26, 0x40000
	s_addc_u32 s27, s27, 0
	s_mov_b32 m0, s33
	v_lshl_add_u64 v[202:203], s[26:27], 0, v[128:129]
	ds_read_b128 v[168:171], v150 offset:32768
	ds_read_b128 v[172:175], v150 offset:33792
	ds_read_b128 v[176:179], v150 offset:34816
	ds_read_b128 v[180:183], v150 offset:35840
	ds_read_b128 v[184:187], v150 offset:36864
	ds_read_b128 v[188:191], v150 offset:37888
	ds_read_b128 v[192:195], v150 offset:38912
	ds_read_b128 v[196:199], v150 offset:39936
	global_load_lds_dwordx4 v[202:203], off
	v_lshl_add_u64 v[202:203], s[26:27], 0, v[132:133]
	s_mov_b32 m0, s34
	s_nop 0
	global_load_lds_dwordx4 v[202:203], off
	s_waitcnt lgkmcnt(8)
	s_barrier
	s_waitcnt lgkmcnt(0)
	s_setprio 1
	s_waitcnt lgkmcnt(0)
	v_mfma_f32_16x16x32_bf16 v[124:127], v[152:155], v[168:171], v[124:127]
	v_mfma_f32_16x16x32_bf16 v[120:123], v[160:163], v[168:171], v[120:123]
	v_mfma_f32_16x16x32_bf16 v[112:115], v[152:155], v[176:179], v[112:115]
	v_mfma_f32_16x16x32_bf16 v[104:107], v[160:163], v[176:179], v[104:107]
	v_mfma_f32_16x16x32_bf16 v[96:99], v[152:155], v[184:187], v[96:99]
	v_mfma_f32_16x16x32_bf16 v[88:91], v[160:163], v[184:187], v[88:91]
	v_mfma_f32_16x16x32_bf16 v[80:83], v[152:155], v[192:195], v[80:83]
	v_mfma_f32_16x16x32_bf16 v[72:75], v[160:163], v[192:195], v[72:75]
	v_mfma_f32_16x16x32_bf16 v[124:127], v[156:159], v[172:175], v[124:127]
	v_mfma_f32_16x16x32_bf16 v[120:123], v[164:167], v[172:175], v[120:123]
	v_mfma_f32_16x16x32_bf16 v[112:115], v[156:159], v[180:183], v[112:115]
	v_mfma_f32_16x16x32_bf16 v[104:107], v[164:167], v[180:183], v[104:107]
	v_mfma_f32_16x16x32_bf16 v[96:99], v[156:159], v[188:191], v[96:99]
	v_mfma_f32_16x16x32_bf16 v[88:91], v[164:167], v[188:191], v[88:91]
	v_mfma_f32_16x16x32_bf16 v[80:83], v[156:159], v[196:199], v[80:83]
	v_mfma_f32_16x16x32_bf16 v[72:75], v[164:167], v[196:199], v[72:75]
	s_setprio 0
	s_barrier
	s_add_i32 s26, 0, 0x1c000
	s_add_i32 s27, s54, s30
	v_add_u32_e32 v136, s26, v148
	v_lshl_add_u64 v[218:219], v[218:219], 0, s[0:1]
	s_mov_b32 m0, s27
	ds_read_b128 v[202:205], v136
	ds_read_b128 v[206:209], v136 offset:1024
	ds_read_b128 v[210:213], v136 offset:2048
	ds_read_b128 v[214:217], v136 offset:3072
	global_load_lds_dwordx4 v[218:219], off
	v_lshl_add_u64 v[218:219], v[220:221], 0, s[0:1]
	s_add_i32 m0, s27, 0x2000
	s_nop 0
	global_load_lds_dwordx4 v[218:219], off
	s_barrier
; #define PG8_STAGE(bufoff, gbase, voff) do { _Pragma("unroll") for (int _i = 0; _i < 2; ++_i) \
;         __builtin_amdgcn_global_load_lds((const unsigned*)((const char*)(gbase) + (voff)[_i]), (LAS unsigned*)(lds + (bufoff) + ldsw + _i * 8192), 16, 0, 0); } while (0)
; #define PG8_LDA(dst, b, h) do { _Pragma("unroll") for (int m = 0; m < 4; ++m) _Pragma("unroll") for (int k = 0; k < 2; ++k) dst[m][k] = *(const LAS bf16x8*)(lds + PG8_SA(b, h) + aoff + m * 2048 + k * 1024); } while (0)
; #define PG8_MMA(ai, bj, At, Bt) do { __builtin_amdgcn_s_setprio(1); _Pragma("unroll") for (int m = 0; m < 4; ++m) _Pragma("unroll") for (int n = 0; n < 2; ++n) _Pragma("unroll") for (int k = 0; k < 2; ++k) \
;         acc[ai][bj][m][n] = __builtin_amdgcn_mfma_f32_16x16x32_bf16(Bt[n][k], At[m][k], acc[ai][bj][m][n], 0, 0, 0); __builtin_amdgcn_s_setprio(0); } while (0)
; #define PG8_WAIT_V(n) asm volatile("s_waitcnt vmcnt(" #n ")" ::: "memory")
; #define PG8_WAIT_L(n) asm volatile("s_waitcnt lgkmcnt(" #n ")" ::: "memory")
; #define PG8_BAR __builtin_amdgcn_s_barrier()
; #define PG8_SCHED __builtin_amdgcn_sched_barrier(0)
; template <class Epi, class Sched>
; __device__ __forceinline__ void gemm_phase(LAS unsigned char* lds, const Gemm g, const Sched& S, const Epi& E) {
;     ...
;             PG8_LDA(At, 1, 1); PG8_STAGE(PG8_SA(1, 0), a3, voffA);
;             PG8_BAR; PG8_WAIT_L(0); PG8_MMA(1, 0, At, B0); PG8_BAR; PG8_SCHED;
;             PG8_STAGE(PG8_SB(1, 1), b3 + hstep, voffB);
;             PG8_WAIT_V(6); PG8_BAR; PG8_MMA(1, 1, At, B1); PG8_BAR;
;         }
	s_waitcnt lgkmcnt(0)
	s_setprio 1
	s_waitcnt lgkmcnt(0)
	v_mfma_f32_16x16x32_bf16 v[116:119], v[202:205], v[168:171], v[116:119]
	v_mfma_f32_16x16x32_bf16 v[108:111], v[210:213], v[168:171], v[108:111]
	v_mfma_f32_16x16x32_bf16 v[100:103], v[202:205], v[176:179], v[100:103]
	v_mfma_f32_16x16x32_bf16 v[92:95], v[210:213], v[176:179], v[92:95]
	v_mfma_f32_16x16x32_bf16 v[84:87], v[202:205], v[184:187], v[84:87]
	v_mfma_f32_16x16x32_bf16 v[76:79], v[210:213], v[184:187], v[76:79]
	v_mfma_f32_16x16x32_bf16 v[68:71], v[202:205], v[192:195], v[68:71]
	v_mfma_f32_16x16x32_bf16 v[64:67], v[210:213], v[192:195], v[64:67]
	v_mfma_f32_16x16x32_bf16 v[116:119], v[206:209], v[172:175], v[116:119]
	v_mfma_f32_16x16x32_bf16 v[108:111], v[214:217], v[172:175], v[108:111]
	v_mfma_f32_16x16x32_bf16 v[100:103], v[206:209], v[180:183], v[100:103]
	v_mfma_f32_16x16x32_bf16 v[92:95], v[214:217], v[180:183], v[92:95]
	v_mfma_f32_16x16x32_bf16 v[84:87], v[206:209], v[188:191], v[84:87]
	v_mfma_f32_16x16x32_bf16 v[76:79], v[214:217], v[188:191], v[76:79]
	v_mfma_f32_16x16x32_bf16 v[68:71], v[206:209], v[196:199], v[68:71]
	v_mfma_f32_16x16x32_bf16 v[64:67], v[214:217], v[196:199], v[64:67]
	s_setprio 0
	s_mov_b32 m0, s42
	v_lshl_add_u64 v[218:219], v[222:223], 0, s[0:1]
	s_barrier
	ds_read_b128 v[168:171], v150 offset:49152
	ds_read_b128 v[172:175], v150 offset:50176
	ds_read_b128 v[176:179], v150 offset:51200
	ds_read_b128 v[180:183], v150 offset:52224
	ds_read_b128 v[184:187], v150 offset:53248
	ds_read_b128 v[188:191], v150 offset:54272
	ds_read_b128 v[192:195], v150 offset:55296
	ds_read_b128 v[196:199], v150 offset:56320
	global_load_lds_dwordx4 v[218:219], off
	v_lshl_add_u64 v[218:219], v[224:225], 0, s[0:1]
	s_mov_b32 m0, s43
	s_nop 0
	global_load_lds_dwordx4 v[218:219], off
	s_barrier
	s_waitcnt lgkmcnt(0)
	s_setprio 1
	s_waitcnt lgkmcnt(0)
	v_mfma_f32_16x16x32_bf16 v[60:63], v[152:155], v[168:171], v[60:63]
	v_mfma_f32_16x16x32_bf16 v[56:59], v[160:163], v[168:171], v[56:59]
	v_mfma_f32_16x16x32_bf16 v[48:51], v[152:155], v[176:179], v[48:51]
	v_mfma_f32_16x16x32_bf16 v[40:43], v[160:163], v[176:179], v[40:43]
	v_mfma_f32_16x16x32_bf16 v[32:35], v[152:155], v[184:187], v[32:35]
	v_mfma_f32_16x16x32_bf16 v[24:27], v[160:163], v[184:187], v[24:27]
	v_mfma_f32_16x16x32_bf16 v[16:19], v[152:155], v[192:195], v[16:19]
	v_mfma_f32_16x16x32_bf16 v[8:11], v[160:163], v[192:195], v[8:11]
	v_mfma_f32_16x16x32_bf16 v[60:63], v[156:159], v[172:175], v[60:63]
	v_mfma_f32_16x16x32_bf16 v[56:59], v[164:167], v[172:175], v[56:59]
	v_mfma_f32_16x16x32_bf16 v[48:51], v[156:159], v[180:183], v[48:51]
	v_mfma_f32_16x16x32_bf16 v[40:43], v[164:167], v[180:183], v[40:43]
	v_mfma_f32_16x16x32_bf16 v[32:35], v[156:159], v[188:191], v[32:35]
	v_mfma_f32_16x16x32_bf16 v[24:27], v[164:167], v[188:191], v[24:27]
	v_mfma_f32_16x16x32_bf16 v[16:19], v[156:159], v[196:199], v[16:19]
	v_mfma_f32_16x16x32_bf16 v[8:11], v[164:167], v[196:199], v[8:11]
	s_setprio 0
	s_barrier
	s_add_u32 s24, s24, 0x40080
	s_addc_u32 s25, s25, 0
	s_add_i32 s26, s26, s30
	v_lshl_add_u64 v[152:153], s[24:25], 0, v[130:131]
	s_mov_b32 m0, s26
	s_nop 0
	global_load_lds_dwordx4 v[152:153], off
	v_lshl_add_u64 v[152:153], s[24:25], 0, v[134:135]
	s_add_i32 m0, s26, 0x2000
	s_nop 0
	global_load_lds_dwordx4 v[152:153], off
	s_waitcnt vmcnt(6)
	s_barrier
	s_setprio 1
	v_mfma_f32_16x16x32_bf16 v[52:55], v[202:205], v[168:171], v[52:55]
	v_mfma_f32_16x16x32_bf16 v[44:47], v[210:213], v[168:171], v[44:47]
	v_mfma_f32_16x16x32_bf16 v[36:39], v[202:205], v[176:179], v[36:39]
	v_mfma_f32_16x16x32_bf16 v[28:31], v[210:213], v[176:179], v[28:31]
	v_mfma_f32_16x16x32_bf16 v[20:23], v[202:205], v[184:187], v[20:23]
	v_mfma_f32_16x16x32_bf16 v[12:15], v[210:213], v[184:187], v[12:15]
	v_mfma_f32_16x16x32_bf16 v[4:7], v[202:205], v[192:195], v[4:7]
	v_mfma_f32_16x16x32_bf16 v[0:3], v[210:213], v[192:195], v[0:3]
	v_mfma_f32_16x16x32_bf16 v[52:55], v[206:209], v[172:175], v[52:55]
	v_mfma_f32_16x16x32_bf16 v[44:47], v[214:217], v[172:175], v[44:47]
	v_mfma_f32_16x16x32_bf16 v[36:39], v[206:209], v[180:183], v[36:39]
	v_mfma_f32_16x16x32_bf16 v[28:31], v[214:217], v[180:183], v[28:31]
	v_mfma_f32_16x16x32_bf16 v[20:23], v[206:209], v[188:191], v[20:23]
	v_mfma_f32_16x16x32_bf16 v[12:15], v[214:217], v[188:191], v[12:15]
	v_mfma_f32_16x16x32_bf16 v[4:7], v[206:209], v[196:199], v[4:7]
	v_mfma_f32_16x16x32_bf16 v[0:3], v[214:217], v[196:199], v[0:3]
	s_setprio 0
	s_add_i32 s53, s53, 2
	s_add_u32 s22, s22, 0x100
	s_addc_u32 s23, s23, 0
	s_add_u32 s51, s51, 0x100
	s_addc_u32 s52, s52, 0
	s_cmp_gt_u32 s53, 13
	s_barrier

; #define PG8_STAGE(bufoff, gbase, voff) do { _Pragma("unroll") for (int _i = 0; _i < 2; ++_i) \
;         __builtin_amdgcn_global_load_lds((const unsigned*)((const char*)(gbase) + (voff)[_i]), (LAS unsigned*)(lds + (bufoff) + ldsw + _i * 8192), 16, 0, 0); } while (0)
; #define PG8_LDA(dst, b, h) do { _Pragma("unroll") for (int m = 0; m < 4; ++m) _Pragma("unroll") for (int k = 0; k < 2; ++k) dst[m][k] = *(const LAS bf16x8*)(lds + PG8_SA(b, h) + aoff + m * 2048 + k * 1024); } while (0)
; #define PG8_LDB(dst, b, h) do { _Pragma("unroll") for (int n = 0; n < 2; ++n) _Pragma("unroll") for (int k = 0; k < 2; ++k) dst[n][k] = *(const LAS bf16x8*)(lds + PG8_SB(b, h) + boff + n * 2048 + k * 1024); } while (0)
; #define PG8_WAIT_V(n) asm volatile("s_waitcnt vmcnt(" #n ")" ::: "memory")
; #define PG8_WAIT_L(n) asm volatile("s_waitcnt lgkmcnt(" #n ")" ::: "memory")
; #define PG8_BAR __builtin_amdgcn_s_barrier()
; #define PG8_SCHED __builtin_amdgcn_sched_barrier(0)
; template <class Epi, class Sched>
; __device__ __forceinline__ void gemm_phase(LAS unsigned char* lds, const Gemm g, const Sched& S, const Epi& E) {
;     ...
;         const bool has_next = S.next(ui + 1, nxt);
;         const char* nA = has_next ? (const char*)g.A + (size_t)nxt.pm * tstep : cA; const char* nB = has_next ? (const char*)g.Bt + (size_t)nxt.pn * tstep : cB;
;         for (int t = 0; t < nt; t += 2) {
;             const bool last = (t == nt - 2);
;             const char* a1 = cA + (size_t)(t + 1) * kstep;
;             const char* a2 = last ? nA : cA + (size_t)(t + 2) * kstep; const char* b2 = last ? nB : cB + (size_t)(t + 2) * kstep;
;             const char* a3 = a2 + kstep; const char* b3 = b2 + kstep;
;             PG8_LDB(B0, 0, 0); PG8_SCHED; PG8_LDA(At, 0, 0); PG8_STAGE(PG8_SA(1, 1), a1 + hstep, voffA);
;             PG8_WAIT_L(8); PG8_BAR; PG8_WAIT_L(0); PG8_MMA(0, 0, At, B0); PG8_BAR; PG8_SCHED;
;             PG8_LDB(B1, 0, 1); PG8_STAGE(PG8_SB(0, 0), b2, voffB);
;             PG8_BAR; PG8_WAIT_L(0); PG8_MMA(0, 1, At, B1); PG8_BAR;
;             PG8_LDA(At, 0, 1); PG8_STAGE(PG8_SA(0, 0), a2, voffA);
;             PG8_BAR; PG8_WAIT_L(0); PG8_MMA(1, 0, At, B0); PG8_BAR; PG8_SCHED;
;             PG8_STAGE(PG8_SB(0, 1), b2 + hstep, voffB);
;             PG8_WAIT_V(6); PG8_BAR; PG8_MMA(1, 1, At, B1); PG8_BAR;
.LBB0_672:
	s_ashr_i32 s9, s8, 31
	v_cmp_lt_i64_e32 vcc, s[12:13], v[142:143]
	s_lshl_b64 s[12:13], s[8:9], 19
	s_add_u32 s12, s26, s12
	s_addc_u32 s13, s27, s13
	s_and_b64 s[14:15], vcc, exec
	s_cselect_b32 s9, s13, s19
	s_cselect_b32 s46, s12, s18
	s_ashr_i32 s7, s6, 31
	s_lshl_b64 s[14:15], s[6:7], 19
	s_add_u32 s14, s10, s14
	s_addc_u32 s15, s11, s15
	s_and_b64 s[22:23], vcc, exec
	s_cselect_b32 s7, s15, s21
	s_cselect_b32 s47, s14, s20
	s_add_u32 s18, s18, 0x40080
	s_addc_u32 s19, s19, 0
	s_add_u32 s48, s20, 0x100
	s_addc_u32 s49, s21, 0
	s_mov_b32 s51, -2
	s_waitcnt lgkmcnt(0)
	ds_read_b128 v[152:155], v149
	ds_read_b128 v[156:159], v149 offset:1024
	ds_read_b128 v[160:163], v149 offset:2048
	ds_read_b128 v[164:167], v149 offset:3072
	s_add_u32 s20, s18, 0xfffc0080
	s_addc_u32 s21, s19, -1
	s_cmp_eq_u32 s51, 12
	s_cselect_b32 s23, s9, s21
	s_cselect_b32 s22, s46, s20
	s_cselect_b32 s21, s7, s49
	s_cselect_b32 s20, s47, s48
	v_lshl_add_u64 v[202:203], s[18:19], 0, v[138:139]
	s_add_i32 m0, s17, 0xc000
	ds_read_b128 v[168:171], v150
	ds_read_b128 v[172:175], v150 offset:1024
	ds_read_b128 v[176:179], v150 offset:2048
	ds_read_b128 v[180:183], v150 offset:3072
	ds_read_b128 v[184:187], v150 offset:4096
	ds_read_b128 v[188:191], v150 offset:5120
	ds_read_b128 v[192:195], v150 offset:6144
	ds_read_b128 v[196:199], v150 offset:7168
	global_load_lds_dwordx4 v[202:203], off
	v_lshl_add_u64 v[202:203], s[18:19], 0, v[140:141]
	s_add_i32 m0, s17, 0xe000
	s_nop 0
	global_load_lds_dwordx4 v[202:203], off
	s_waitcnt lgkmcnt(8)
	s_barrier
	s_waitcnt lgkmcnt(0)
	s_setprio 1
	s_waitcnt lgkmcnt(0)
	v_mfma_f32_16x16x32_bf16 v[124:127], v[152:155], v[168:171], 0
	v_mfma_f32_16x16x32_bf16 v[120:123], v[160:163], v[168:171], 0
	v_mfma_f32_16x16x32_bf16 v[112:115], v[152:155], v[176:179], 0
	v_mfma_f32_16x16x32_bf16 v[104:107], v[160:163], v[176:179], 0
	v_mfma_f32_16x16x32_bf16 v[96:99], v[152:155], v[184:187], 0
	v_mfma_f32_16x16x32_bf16 v[88:91], v[160:163], v[184:187], 0
	v_mfma_f32_16x16x32_bf16 v[80:83], v[152:155], v[192:195], 0
	v_mfma_f32_16x16x32_bf16 v[72:75], v[160:163], v[192:195], 0
	v_mfma_f32_16x16x32_bf16 v[124:127], v[156:159], v[172:175], v[124:127]
	v_mfma_f32_16x16x32_bf16 v[120:123], v[164:167], v[172:175], v[120:123]
	v_mfma_f32_16x16x32_bf16 v[112:115], v[156:159], v[180:183], v[112:115]
	v_mfma_f32_16x16x32_bf16 v[104:107], v[164:167], v[180:183], v[104:107]
	v_mfma_f32_16x16x32_bf16 v[96:99], v[156:159], v[188:191], v[96:99]
	v_mfma_f32_16x16x32_bf16 v[88:91], v[164:167], v[188:191], v[88:91]
	v_mfma_f32_16x16x32_bf16 v[80:83], v[156:159], v[196:199], v[80:83]
	v_mfma_f32_16x16x32_bf16 v[72:75], v[164:167], v[196:199], v[72:75]
	s_setprio 0
	s_barrier
	s_add_i32 s52, s43, s28
	v_lshl_add_u64 v[218:219], s[20:21], 0, v[130:131]
	s_mov_b32 m0, s52
	ds_read_b128 v[202:205], v151
	ds_read_b128 v[206:209], v151 offset:1024
	ds_read_b128 v[210:213], v151 offset:2048
	ds_read_b128 v[214:217], v151 offset:3072
	global_load_lds_dwordx4 v[218:219], off
	v_lshl_add_u64 v[220:221], s[20:21], 0, v[134:135]
	s_add_i32 m0, s52, 0x2000
	s_nop 0
	global_load_lds_dwordx4 v[220:221], off
	s_barrier
	s_waitcnt lgkmcnt(0)
	s_setprio 1
	s_waitcnt lgkmcnt(0)
	v_mfma_f32_16x16x32_bf16 v[116:119], v[202:205], v[168:171], 0
	v_mfma_f32_16x16x32_bf16 v[108:111], v[210:213], v[168:171], 0
	v_mfma_f32_16x16x32_bf16 v[100:103], v[202:205], v[176:179], 0
	v_mfma_f32_16x16x32_bf16 v[92:95], v[210:213], v[176:179], 0
	v_mfma_f32_16x16x32_bf16 v[84:87], v[202:205], v[184:187], 0
	v_mfma_f32_16x16x32_bf16 v[76:79], v[210:213], v[184:187], 0
	v_mfma_f32_16x16x32_bf16 v[68:71], v[202:205], v[192:195], 0
	v_mfma_f32_16x16x32_bf16 v[64:67], v[210:213], v[192:195], 0
	v_mfma_f32_16x16x32_bf16 v[116:119], v[206:209], v[172:175], v[116:119]
	v_mfma_f32_16x16x32_bf16 v[108:111], v[214:217], v[172:175], v[108:111]
	v_mfma_f32_16x16x32_bf16 v[100:103], v[206:209], v[180:183], v[100:103]
	v_mfma_f32_16x16x32_bf16 v[92:95], v[214:217], v[180:183], v[92:95]
	v_mfma_f32_16x16x32_bf16 v[84:87], v[206:209], v[188:191], v[84:87]
	v_mfma_f32_16x16x32_bf16 v[76:79], v[214:217], v[188:191], v[76:79]
	v_mfma_f32_16x16x32_bf16 v[68:71], v[206:209], v[196:199], v[68:71]
	v_mfma_f32_16x16x32_bf16 v[64:67], v[214:217], v[196:199], v[64:67]
	s_setprio 0
	s_mov_b32 m0, s17
	v_lshl_add_u64 v[222:223], s[22:23], 0, v[128:129]
	s_barrier
	ds_read_b128 v[168:171], v150 offset:16384
	ds_read_b128 v[172:175], v150 offset:17408
	ds_read_b128 v[176:179], v150 offset:18432
	ds_read_b128 v[180:183], v150 offset:19456
	ds_read_b128 v[184:187], v150 offset:20480
	ds_read_b128 v[188:191], v150 offset:21504
	ds_read_b128 v[192:195], v150 offset:22528
	ds_read_b128 v[196:199], v150 offset:23552
	global_load_lds_dwordx4 v[222:223], off
	v_lshl_add_u64 v[224:225], s[22:23], 0, v[132:133]
	s_mov_b32 m0, s29
	s_nop 0
	global_load_lds_dwordx4 v[224:225], off
	s_barrier
	s_waitcnt lgkmcnt(0)
	s_setprio 1
	s_waitcnt lgkmcnt(0)
	v_mfma_f32_16x16x32_bf16 v[60:63], v[152:155], v[168:171], 0
	v_mfma_f32_16x16x32_bf16 v[56:59], v[160:163], v[168:171], 0
	v_mfma_f32_16x16x32_bf16 v[48:51], v[152:155], v[176:179], 0
	v_mfma_f32_16x16x32_bf16 v[40:43], v[160:163], v[176:179], 0
	v_mfma_f32_16x16x32_bf16 v[32:35], v[152:155], v[184:187], 0
	v_mfma_f32_16x16x32_bf16 v[24:27], v[160:163], v[184:187], 0
	v_mfma_f32_16x16x32_bf16 v[16:19], v[152:155], v[192:195], 0
	v_mfma_f32_16x16x32_bf16 v[8:11], v[160:163], v[192:195], 0
	v_mfma_f32_16x16x32_bf16 v[60:63], v[156:159], v[172:175], v[60:63]
	v_mfma_f32_16x16x32_bf16 v[56:59], v[164:167], v[172:175], v[56:59]
	v_mfma_f32_16x16x32_bf16 v[48:51], v[156:159], v[180:183], v[48:51]
	v_mfma_f32_16x16x32_bf16 v[40:43], v[164:167], v[180:183], v[40:43]
	v_mfma_f32_16x16x32_bf16 v[32:35], v[156:159], v[188:191], v[32:35]
	v_mfma_f32_16x16x32_bf16 v[24:27], v[164:167], v[188:191], v[24:27]
	v_mfma_f32_16x16x32_bf16 v[16:19], v[156:159], v[196:199], v[16:19]
	v_mfma_f32_16x16x32_bf16 v[8:11], v[164:167], v[196:199], v[8:11]
	s_setprio 0
	s_barrier
; #define PG8_STAGE(bufoff, gbase, voff) do { _Pragma("unroll") for (int _i = 0; _i < 2; ++_i) \
;         __builtin_amdgcn_global_load_lds((const unsigned*)((const char*)(gbase) + (voff)[_i]), (LAS unsigned*)(lds + (bufoff) + ldsw + _i * 8192), 16, 0, 0); } while (0)
; #define PG8_LDA(dst, b, h) do { _Pragma("unroll") for (int m = 0; m < 4; ++m) _Pragma("unroll") for (int k = 0; k < 2; ++k) dst[m][k] = *(const LAS bf16x8*)(lds + PG8_SA(b, h) + aoff + m * 2048 + k * 1024); } while (0)
; #define PG8_LDB(dst, b, h) do { _Pragma("unroll") for (int n = 0; n < 2; ++n) _Pragma("unroll") for (int k = 0; k < 2; ++k) dst[n][k] = *(const LAS bf16x8*)(lds + PG8_SB(b, h) + boff + n * 2048 + k * 1024); } while (0)
; #define PG8_MMA(ai, bj, At, Bt) do { __builtin_amdgcn_s_setprio(1); _Pragma("unroll") for (int m = 0; m < 4; ++m) _Pragma("unroll") for (int n = 0; n < 2; ++n) _Pragma("unroll") for (int k = 0; k < 2; ++k) \
;         acc[ai][bj][m][n] = __builtin_amdgcn_mfma_f32_16x16x32_bf16(Bt[n][k], At[m][k], acc[ai][bj][m][n], 0, 0, 0); __builtin_amdgcn_s_setprio(0); } while (0)
; #define PG8_WAIT_V(n) asm volatile("s_waitcnt vmcnt(" #n ")" ::: "memory")
; #define PG8_WAIT_L(n) asm volatile("s_waitcnt lgkmcnt(" #n ")" ::: "memory")
; #define PG8_BAR __builtin_amdgcn_s_barrier()
; #define PG8_SCHED __builtin_amdgcn_sched_barrier(0)
; template <class Epi, class Sched>
; __device__ __forceinline__ void gemm_phase(LAS unsigned char* lds, const Gemm g, const Sched& S, const Epi& E) {
;     ...
;             PG8_STAGE(PG8_SB(0, 1), b2 + hstep, voffB);
;             PG8_WAIT_V(6); PG8_BAR; PG8_MMA(1, 1, At, B1); PG8_BAR;
;             PG8_LDB(B0, 1, 0); PG8_SCHED; PG8_LDA(At, 1, 0); PG8_STAGE(PG8_SA(0, 1), a2 + hstep, voffA);
;             PG8_WAIT_L(8); PG8_BAR; PG8_WAIT_L(0); PG8_MMA(0, 0, At, B0); PG8_BAR; PG8_SCHED;
;             PG8_LDB(B1, 1, 1); PG8_STAGE(PG8_SB(1, 0), b3, voffB);
	s_add_u32 s52, s20, 0x40000
	s_addc_u32 s53, s21, 0
	s_add_i32 s54, s44, s28
	v_lshl_add_u64 v[152:153], s[52:53], 0, v[130:131]
	s_mov_b32 m0, s54
	s_nop 0
	global_load_lds_dwordx4 v[152:153], off
	v_lshl_add_u64 v[152:153], s[52:53], 0, v[134:135]
	s_add_i32 m0, s54, 0x2000
	s_nop 0
	global_load_lds_dwordx4 v[152:153], off
	s_waitcnt vmcnt(6)
	s_barrier
	s_setprio 1
	v_mfma_f32_16x16x32_bf16 v[52:55], v[202:205], v[168:171], 0
	v_mfma_f32_16x16x32_bf16 v[44:47], v[210:213], v[168:171], 0
	v_mfma_f32_16x16x32_bf16 v[36:39], v[202:205], v[176:179], 0
	v_mfma_f32_16x16x32_bf16 v[28:31], v[210:213], v[176:179], 0
	v_mfma_f32_16x16x32_bf16 v[20:23], v[202:205], v[184:187], 0
	v_mfma_f32_16x16x32_bf16 v[12:15], v[210:213], v[184:187], 0
	v_mfma_f32_16x16x32_bf16 v[4:7], v[202:205], v[192:195], 0
	v_mfma_f32_16x16x32_bf16 v[0:3], v[210:213], v[192:195], 0
	v_mfma_f32_16x16x32_bf16 v[52:55], v[206:209], v[172:175], v[52:55]
	v_mfma_f32_16x16x32_bf16 v[44:47], v[214:217], v[172:175], v[44:47]
	v_mfma_f32_16x16x32_bf16 v[36:39], v[206:209], v[180:183], v[36:39]
	v_mfma_f32_16x16x32_bf16 v[28:31], v[214:217], v[180:183], v[28:31]
	v_mfma_f32_16x16x32_bf16 v[20:23], v[206:209], v[188:191], v[20:23]
	v_mfma_f32_16x16x32_bf16 v[12:15], v[214:217], v[188:191], v[12:15]
	v_mfma_f32_16x16x32_bf16 v[4:7], v[206:209], v[196:199], v[4:7]
	v_mfma_f32_16x16x32_bf16 v[0:3], v[214:217], v[196:199], v[0:3]
	s_setprio 0
	s_add_i32 s52, 0, 0x18000
	v_add_u32_e32 v136, s52, v148
	s_barrier
	ds_read_b128 v[152:155], v136
	ds_read_b128 v[156:159], v136 offset:1024
	ds_read_b128 v[160:163], v136 offset:2048
	ds_read_b128 v[164:167], v136 offset:3072
	s_add_u32 s22, s22, 0x40000
	s_addc_u32 s23, s23, 0
	s_mov_b32 m0, s30
	v_lshl_add_u64 v[202:203], s[22:23], 0, v[128:129]
	ds_read_b128 v[168:171], v150 offset:32768
	ds_read_b128 v[172:175], v150 offset:33792
	ds_read_b128 v[176:179], v150 offset:34816
	ds_read_b128 v[180:183], v150 offset:35840
	ds_read_b128 v[184:187], v150 offset:36864
	ds_read_b128 v[188:191], v150 offset:37888
	ds_read_b128 v[192:195], v150 offset:38912
	ds_read_b128 v[196:199], v150 offset:39936
	global_load_lds_dwordx4 v[202:203], off
	v_lshl_add_u64 v[202:203], s[22:23], 0, v[132:133]
	s_mov_b32 m0, s31
	s_nop 0
	global_load_lds_dwordx4 v[202:203], off
	s_waitcnt lgkmcnt(8)
	s_barrier
	s_waitcnt lgkmcnt(0)
	s_setprio 1
	s_waitcnt lgkmcnt(0)
	v_mfma_f32_16x16x32_bf16 v[124:127], v[152:155], v[168:171], v[124:127]
	v_mfma_f32_16x16x32_bf16 v[120:123], v[160:163], v[168:171], v[120:123]
	v_mfma_f32_16x16x32_bf16 v[112:115], v[152:155], v[176:179], v[112:115]
	v_mfma_f32_16x16x32_bf16 v[104:107], v[160:163], v[176:179], v[104:107]
	v_mfma_f32_16x16x32_bf16 v[96:99], v[152:155], v[184:187], v[96:99]
	v_mfma_f32_16x16x32_bf16 v[88:91], v[160:163], v[184:187], v[88:91]
	v_mfma_f32_16x16x32_bf16 v[80:83], v[152:155], v[192:195], v[80:83]
	v_mfma_f32_16x16x32_bf16 v[72:75], v[160:163], v[192:195], v[72:75]
	v_mfma_f32_16x16x32_bf16 v[124:127], v[156:159], v[172:175], v[124:127]
	v_mfma_f32_16x16x32_bf16 v[120:123], v[164:167], v[172:175], v[120:123]
	v_mfma_f32_16x16x32_bf16 v[112:115], v[156:159], v[180:183], v[112:115]
	v_mfma_f32_16x16x32_bf16 v[104:107], v[164:167], v[180:183], v[104:107]
	v_mfma_f32_16x16x32_bf16 v[96:99], v[156:159], v[188:191], v[96:99]
	v_mfma_f32_16x16x32_bf16 v[88:91], v[164:167], v[188:191], v[88:91]
	v_mfma_f32_16x16x32_bf16 v[80:83], v[156:159], v[196:199], v[80:83]
	v_mfma_f32_16x16x32_bf16 v[72:75], v[164:167], v[196:199], v[72:75]
	s_setprio 0
	s_barrier
	s_add_i32 s22, 0, 0x1c000
	s_add_i32 s23, s52, s28
	v_add_u32_e32 v136, s22, v148
	v_lshl_add_u64 v[218:219], v[218:219], 0, s[0:1]
	s_mov_b32 m0, s23
	ds_read_b128 v[202:205], v136
	ds_read_b128 v[206:209], v136 offset:1024
	ds_read_b128 v[210:213], v136 offset:2048
	ds_read_b128 v[214:217], v136 offset:3072
	global_load_lds_dwordx4 v[218:219], off
	v_lshl_add_u64 v[218:219], v[220:221], 0, s[0:1]
	s_add_i32 m0, s23, 0x2000
	s_nop 0
	global_load_lds_dwordx4 v[218:219], off
	s_barrier
; #define PG8_STAGE(bufoff, gbase, voff) do { _Pragma("unroll") for (int _i = 0; _i < 2; ++_i) \
;         __builtin_amdgcn_global_load_lds((const unsigned*)((const char*)(gbase) + (voff)[_i]), (LAS unsigned*)(lds + (bufoff) + ldsw + _i * 8192), 16, 0, 0); } while (0)
; #define PG8_LDA(dst, b, h) do { _Pragma("unroll") for (int m = 0; m < 4; ++m) _Pragma("unroll") for (int k = 0; k < 2; ++k) dst[m][k] = *(const LAS bf16x8*)(lds + PG8_SA(b, h) + aoff + m * 2048 + k * 1024); } while (0)
; #define PG8_MMA(ai, bj, At, Bt) do { __builtin_amdgcn_s_setprio(1); _Pragma("unroll") for (int m = 0; m < 4; ++m) _Pragma("unroll") for (int n = 0; n < 2; ++n) _Pragma("unroll") for (int k = 0; k < 2; ++k) \
;         acc[ai][bj][m][n] = __builtin_amdgcn_mfma_f32_16x16x32_bf16(Bt[n][k], At[m][k], acc[ai][bj][m][n], 0, 0, 0); __builtin_amdgcn_s_setprio(0); } while (0)
; #define PG8_WAIT_V(n) asm volatile("s_waitcnt vmcnt(" #n ")" ::: "memory")
; #define PG8_WAIT_L(n) asm volatile("s_waitcnt lgkmcnt(" #n ")" ::: "memory")
; #define PG8_BAR __builtin_amdgcn_s_barrier()
; #define PG8_SCHED __builtin_amdgcn_sched_barrier(0)
; template <class Epi, class Sched>
; __device__ __forceinline__ void gemm_phase(LAS unsigned char* lds, const Gemm g, const Sched& S, const Epi& E) {
;     ...
;             PG8_LDA(At, 1, 1); PG8_STAGE(PG8_SA(1, 0), a3, voffA);
;             PG8_BAR; PG8_WAIT_L(0); PG8_MMA(1, 0, At, B0); PG8_BAR; PG8_SCHED;
;             PG8_STAGE(PG8_SB(1, 1), b3 + hstep, voffB);
;             PG8_WAIT_V(6); PG8_BAR; PG8_MMA(1, 1, At, B1); PG8_BAR;
;         }
	s_waitcnt lgkmcnt(0)
	s_setprio 1
	s_waitcnt lgkmcnt(0)
	v_mfma_f32_16x16x32_bf16 v[116:119], v[202:205], v[168:171], v[116:119]
	v_mfma_f32_16x16x32_bf16 v[108:111], v[210:213], v[168:171], v[108:111]
	v_mfma_f32_16x16x32_bf16 v[100:103], v[202:205], v[176:179], v[100:103]
	v_mfma_f32_16x16x32_bf16 v[92:95], v[210:213], v[176:179], v[92:95]
	v_mfma_f32_16x16x32_bf16 v[84:87], v[202:205], v[184:187], v[84:87]
	v_mfma_f32_16x16x32_bf16 v[76:79], v[210:213], v[184:187], v[76:79]
	v_mfma_f32_16x16x32_bf16 v[68:71], v[202:205], v[192:195], v[68:71]
	v_mfma_f32_16x16x32_bf16 v[64:67], v[210:213], v[192:195], v[64:67]
	v_mfma_f32_16x16x32_bf16 v[116:119], v[206:209], v[172:175], v[116:119]
	v_mfma_f32_16x16x32_bf16 v[108:111], v[214:217], v[172:175], v[108:111]
	v_mfma_f32_16x16x32_bf16 v[100:103], v[206:209], v[180:183], v[100:103]
	v_mfma_f32_16x16x32_bf16 v[92:95], v[214:217], v[180:183], v[92:95]
	v_mfma_f32_16x16x32_bf16 v[84:87], v[206:209], v[188:191], v[84:87]
	v_mfma_f32_16x16x32_bf16 v[76:79], v[214:217], v[188:191], v[76:79]
	v_mfma_f32_16x16x32_bf16 v[68:71], v[206:209], v[196:199], v[68:71]
	v_mfma_f32_16x16x32_bf16 v[64:67], v[214:217], v[196:199], v[64:67]
	s_setprio 0
	s_mov_b32 m0, s36
	v_lshl_add_u64 v[218:219], v[222:223], 0, s[0:1]
	s_barrier
	ds_read_b128 v[168:171], v150 offset:49152
	ds_read_b128 v[172:175], v150 offset:50176
	ds_read_b128 v[176:179], v150 offset:51200
	ds_read_b128 v[180:183], v150 offset:52224
	ds_read_b128 v[184:187], v150 offset:53248
	ds_read_b128 v[188:191], v150 offset:54272
	ds_read_b128 v[192:195], v150 offset:55296
	ds_read_b128 v[196:199], v150 offset:56320
	global_load_lds_dwordx4 v[218:219], off
	v_lshl_add_u64 v[218:219], v[224:225], 0, s[0:1]
	s_mov_b32 m0, s37
	s_nop 0
	global_load_lds_dwordx4 v[218:219], off
	s_barrier
	s_waitcnt lgkmcnt(0)
	s_setprio 1
	s_waitcnt lgkmcnt(0)
	v_mfma_f32_16x16x32_bf16 v[60:63], v[152:155], v[168:171], v[60:63]
	v_mfma_f32_16x16x32_bf16 v[56:59], v[160:163], v[168:171], v[56:59]
	v_mfma_f32_16x16x32_bf16 v[48:51], v[152:155], v[176:179], v[48:51]
	v_mfma_f32_16x16x32_bf16 v[40:43], v[160:163], v[176:179], v[40:43]
	v_mfma_f32_16x16x32_bf16 v[32:35], v[152:155], v[184:187], v[32:35]
	v_mfma_f32_16x16x32_bf16 v[24:27], v[160:163], v[184:187], v[24:27]
	v_mfma_f32_16x16x32_bf16 v[16:19], v[152:155], v[192:195], v[16:19]
	v_mfma_f32_16x16x32_bf16 v[8:11], v[160:163], v[192:195], v[8:11]
	v_mfma_f32_16x16x32_bf16 v[60:63], v[156:159], v[172:175], v[60:63]
	v_mfma_f32_16x16x32_bf16 v[56:59], v[164:167], v[172:175], v[56:59]
	v_mfma_f32_16x16x32_bf16 v[48:51], v[156:159], v[180:183], v[48:51]
	v_mfma_f32_16x16x32_bf16 v[40:43], v[164:167], v[180:183], v[40:43]
	v_mfma_f32_16x16x32_bf16 v[32:35], v[156:159], v[188:191], v[32:35]
	v_mfma_f32_16x16x32_bf16 v[24:27], v[164:167], v[188:191], v[24:27]
	v_mfma_f32_16x16x32_bf16 v[16:19], v[156:159], v[196:199], v[16:19]
	v_mfma_f32_16x16x32_bf16 v[8:11], v[164:167], v[196:199], v[8:11]
	s_setprio 0
	s_barrier
	s_add_u32 s20, s20, 0x40080
	s_addc_u32 s21, s21, 0
	s_add_i32 s22, s22, s28
	v_lshl_add_u64 v[152:153], s[20:21], 0, v[130:131]
	s_mov_b32 m0, s22
	s_nop 0
	global_load_lds_dwordx4 v[152:153], off
	v_lshl_add_u64 v[152:153], s[20:21], 0, v[134:135]
	s_add_i32 m0, s22, 0x2000
	s_nop 0
	global_load_lds_dwordx4 v[152:153], off
	s_waitcnt vmcnt(6)
	s_barrier
	s_setprio 1
	v_mfma_f32_16x16x32_bf16 v[52:55], v[202:205], v[168:171], v[52:55]
	v_mfma_f32_16x16x32_bf16 v[44:47], v[210:213], v[168:171], v[44:47]
	v_mfma_f32_16x16x32_bf16 v[36:39], v[202:205], v[176:179], v[36:39]
	v_mfma_f32_16x16x32_bf16 v[28:31], v[210:213], v[176:179], v[28:31]
	v_mfma_f32_16x16x32_bf16 v[20:23], v[202:205], v[184:187], v[20:23]
	v_mfma_f32_16x16x32_bf16 v[12:15], v[210:213], v[184:187], v[12:15]
	v_mfma_f32_16x16x32_bf16 v[4:7], v[202:205], v[192:195], v[4:7]
	v_mfma_f32_16x16x32_bf16 v[0:3], v[210:213], v[192:195], v[0:3]
	v_mfma_f32_16x16x32_bf16 v[52:55], v[206:209], v[172:175], v[52:55]
	v_mfma_f32_16x16x32_bf16 v[44:47], v[214:217], v[172:175], v[44:47]
	v_mfma_f32_16x16x32_bf16 v[36:39], v[206:209], v[180:183], v[36:39]
	v_mfma_f32_16x16x32_bf16 v[28:31], v[214:217], v[180:183], v[28:31]
	v_mfma_f32_16x16x32_bf16 v[20:23], v[206:209], v[188:191], v[20:23]
	v_mfma_f32_16x16x32_bf16 v[12:15], v[214:217], v[188:191], v[12:15]
	v_mfma_f32_16x16x32_bf16 v[4:7], v[206:209], v[196:199], v[4:7]
	v_mfma_f32_16x16x32_bf16 v[0:3], v[214:217], v[196:199], v[0:3]
	s_setprio 0
	s_add_i32 s51, s51, 2
	s_add_u32 s18, s18, 0x100
	s_addc_u32 s19, s19, 0
	s_add_u32 s48, s48, 0x100
	s_addc_u32 s49, s49, 0
	s_cmp_gt_u32 s51, 13
	s_barrier

; #define PG8_STAGE(bufoff, gbase, voff) do { _Pragma("unroll") for (int _i = 0; _i < 2; ++_i) \
;         __builtin_amdgcn_global_load_lds((const unsigned*)((const char*)(gbase) + (voff)[_i]), (LAS unsigned*)(lds + (bufoff) + ldsw + _i * 8192), 16, 0, 0); } while (0)
; #define PG8_LDA(dst, b, h) do { _Pragma("unroll") for (int m = 0; m < 4; ++m) _Pragma("unroll") for (int k = 0; k < 2; ++k) dst[m][k] = *(const LAS bf16x8*)(lds + PG8_SA(b, h) + aoff + m * 2048 + k * 1024); } while (0)
; #define PG8_LDB(dst, b, h) do { _Pragma("unroll") for (int n = 0; n < 2; ++n) _Pragma("unroll") for (int k = 0; k < 2; ++k) dst[n][k] = *(const LAS bf16x8*)(lds + PG8_SB(b, h) + boff + n * 2048 + k * 1024); } while (0)
; #define PG8_WAIT_V(n) asm volatile("s_waitcnt vmcnt(" #n ")" ::: "memory")
; #define PG8_WAIT_L(n) asm volatile("s_waitcnt lgkmcnt(" #n ")" ::: "memory")
; #define PG8_BAR __builtin_amdgcn_s_barrier()
; #define PG8_SCHED __builtin_amdgcn_sched_barrier(0)
; template <class Epi, class Sched>
; __device__ __forceinline__ void gemm_phase(LAS unsigned char* lds, const Gemm g, const Sched& S, const Epi& E) {
;     ...
;         const bool has_next = S.next(ui + 1, nxt);
;         const char* nA = has_next ? (const char*)g.A + (size_t)nxt.pm * tstep : cA; const char* nB = has_next ? (const char*)g.Bt + (size_t)nxt.pn * tstep : cB;
;         for (int t = 0; t < nt; t += 2) {
;             const bool last = (t == nt - 2);
;             const char* a1 = cA + (size_t)(t + 1) * kstep;
;             const char* a2 = last ? nA : cA + (size_t)(t + 2) * kstep; const char* b2 = last ? nB : cB + (size_t)(t + 2) * kstep;
;             const char* a3 = a2 + kstep; const char* b3 = b2 + kstep;
;             PG8_LDB(B0, 0, 0); PG8_SCHED; PG8_LDA(At, 0, 0); PG8_STAGE(PG8_SA(1, 1), a1 + hstep, voffA);
;             PG8_WAIT_L(8); PG8_BAR; PG8_WAIT_L(0); PG8_MMA(0, 0, At, B0); PG8_BAR; PG8_SCHED;
;             PG8_LDB(B1, 0, 1); PG8_STAGE(PG8_SB(0, 0), b2, voffB);
;             PG8_BAR; PG8_WAIT_L(0); PG8_MMA(0, 1, At, B1); PG8_BAR;
;             PG8_LDA(At, 0, 1); PG8_STAGE(PG8_SA(0, 0), a2, voffA);
;             PG8_BAR; PG8_WAIT_L(0); PG8_MMA(1, 0, At, B0); PG8_BAR; PG8_SCHED;
;             PG8_STAGE(PG8_SB(0, 1), b2 + hstep, voffB);
;             PG8_WAIT_V(6); PG8_BAR; PG8_MMA(1, 1, At, B1); PG8_BAR;
.LBB0_692:
	s_ashr_i32 s19, s18, 31
	v_cmp_lt_i64_e64 s[24:25], s[20:21], 32
	s_lshl_b64 s[20:21], s[18:19], 19
	s_add_u32 s20, s40, s20
	s_addc_u32 s21, s41, s21
	s_and_b64 s[22:23], s[24:25], exec
	s_cselect_b32 s19, s21, s3
	s_cselect_b32 s57, s20, s2
	s_ashr_i32 s17, s16, 31
	s_lshl_b64 s[22:23], s[16:17], 19
	s_add_u32 s22, s28, s22
	s_addc_u32 s23, s29, s23
	s_and_b64 s[24:25], s[24:25], exec
	s_cselect_b32 s17, s23, s5
	s_cselect_b32 s58, s22, s4
	s_add_u32 s2, s2, 0x40080
	s_addc_u32 s3, s3, 0
	s_add_u32 s59, s4, 0x100
	s_addc_u32 s60, s5, 0
	s_mov_b32 s61, -2
	s_waitcnt lgkmcnt(0)
	ds_read_b128 v[140:143], v149
	ds_read_b128 v[154:157], v149 offset:1024
	ds_read_b128 v[158:161], v149 offset:2048
	ds_read_b128 v[162:165], v149 offset:3072
	s_add_u32 s4, s2, 0xfffc0080
	s_addc_u32 s5, s3, -1
	s_cmp_eq_u32 s61, 12
	s_cselect_b32 s25, s19, s5
	s_cselect_b32 s24, s57, s4
	s_cselect_b32 s5, s17, s60
	s_cselect_b32 s4, s58, s59
	v_lshl_add_u64 v[144:145], s[2:3], 0, v[136:137]
	s_add_i32 m0, s33, 0xc000
	ds_read_b128 v[166:169], v150
	ds_read_b128 v[170:173], v150 offset:1024
	ds_read_b128 v[174:177], v150 offset:2048
	ds_read_b128 v[178:181], v150 offset:3072
	ds_read_b128 v[182:185], v150 offset:4096
	ds_read_b128 v[186:189], v150 offset:5120
	ds_read_b128 v[190:193], v150 offset:6144
	ds_read_b128 v[194:197], v150 offset:7168
	global_load_lds_dwordx4 v[144:145], off
	v_lshl_add_u64 v[144:145], s[2:3], 0, v[138:139]
	s_add_i32 m0, s33, 0xe000
	s_nop 0
	global_load_lds_dwordx4 v[144:145], off
	s_waitcnt lgkmcnt(8)
	s_barrier
	s_waitcnt lgkmcnt(0)
	s_setprio 1
	s_waitcnt lgkmcnt(0)
	v_mfma_f32_16x16x32_bf16 v[124:127], v[140:143], v[166:169], 0
	v_mfma_f32_16x16x32_bf16 v[120:123], v[158:161], v[166:169], 0
	v_mfma_f32_16x16x32_bf16 v[108:111], v[140:143], v[174:177], 0
	v_mfma_f32_16x16x32_bf16 v[104:107], v[158:161], v[174:177], 0
	v_mfma_f32_16x16x32_bf16 v[92:95], v[140:143], v[182:185], 0
	v_mfma_f32_16x16x32_bf16 v[88:91], v[158:161], v[182:185], 0
	v_mfma_f32_16x16x32_bf16 v[76:79], v[140:143], v[190:193], 0
	v_mfma_f32_16x16x32_bf16 v[72:75], v[158:161], v[190:193], 0
	v_mfma_f32_16x16x32_bf16 v[124:127], v[154:157], v[170:173], v[124:127]
	v_mfma_f32_16x16x32_bf16 v[120:123], v[162:165], v[170:173], v[120:123]
	v_mfma_f32_16x16x32_bf16 v[108:111], v[154:157], v[178:181], v[108:111]
	v_mfma_f32_16x16x32_bf16 v[104:107], v[162:165], v[178:181], v[104:107]
	v_mfma_f32_16x16x32_bf16 v[92:95], v[154:157], v[186:189], v[92:95]
	v_mfma_f32_16x16x32_bf16 v[88:91], v[162:165], v[186:189], v[88:91]
	v_mfma_f32_16x16x32_bf16 v[76:79], v[154:157], v[194:197], v[76:79]
	v_mfma_f32_16x16x32_bf16 v[72:75], v[162:165], v[194:197], v[72:75]
	s_setprio 0
	s_barrier
	s_add_i32 s62, s47, s31
	v_lshl_add_u64 v[144:145], s[4:5], 0, v[130:131]
	s_mov_b32 m0, s62
	ds_read_b128 v[202:205], v151
	ds_read_b128 v[206:209], v151 offset:1024
	ds_read_b128 v[210:213], v151 offset:2048
	ds_read_b128 v[214:217], v151 offset:3072
	global_load_lds_dwordx4 v[144:145], off
	v_lshl_add_u64 v[198:199], s[4:5], 0, v[134:135]
	s_add_i32 m0, s62, 0x2000
	s_nop 0
	global_load_lds_dwordx4 v[198:199], off
	s_barrier
	s_waitcnt lgkmcnt(0)
	s_setprio 1
	s_waitcnt lgkmcnt(0)
	v_mfma_f32_16x16x32_bf16 v[116:119], v[202:205], v[166:169], 0
	v_mfma_f32_16x16x32_bf16 v[112:115], v[210:213], v[166:169], 0
	v_mfma_f32_16x16x32_bf16 v[100:103], v[202:205], v[174:177], 0
	v_mfma_f32_16x16x32_bf16 v[96:99], v[210:213], v[174:177], 0
	v_mfma_f32_16x16x32_bf16 v[84:87], v[202:205], v[182:185], 0
	v_mfma_f32_16x16x32_bf16 v[80:83], v[210:213], v[182:185], 0
	v_mfma_f32_16x16x32_bf16 v[68:71], v[202:205], v[190:193], 0
	v_mfma_f32_16x16x32_bf16 v[64:67], v[210:213], v[190:193], 0
	v_mfma_f32_16x16x32_bf16 v[116:119], v[206:209], v[170:173], v[116:119]
	v_mfma_f32_16x16x32_bf16 v[112:115], v[214:217], v[170:173], v[112:115]
	v_mfma_f32_16x16x32_bf16 v[100:103], v[206:209], v[178:181], v[100:103]
	v_mfma_f32_16x16x32_bf16 v[96:99], v[214:217], v[178:181], v[96:99]
	v_mfma_f32_16x16x32_bf16 v[84:87], v[206:209], v[186:189], v[84:87]
	v_mfma_f32_16x16x32_bf16 v[80:83], v[214:217], v[186:189], v[80:83]
	v_mfma_f32_16x16x32_bf16 v[68:71], v[206:209], v[194:197], v[68:71]
	v_mfma_f32_16x16x32_bf16 v[64:67], v[214:217], v[194:197], v[64:67]
	s_setprio 0
	s_mov_b32 m0, s33
	v_lshl_add_u64 v[218:219], s[24:25], 0, v[128:129]
	s_barrier
	ds_read_b128 v[166:169], v150 offset:16384
	ds_read_b128 v[170:173], v150 offset:17408
	ds_read_b128 v[174:177], v150 offset:18432
	ds_read_b128 v[178:181], v150 offset:19456
	ds_read_b128 v[182:185], v150 offset:20480
	ds_read_b128 v[186:189], v150 offset:21504
	ds_read_b128 v[190:193], v150 offset:22528
	ds_read_b128 v[194:197], v150 offset:23552
	global_load_lds_dwordx4 v[218:219], off
	v_lshl_add_u64 v[220:221], s[24:25], 0, v[132:133]
	s_mov_b32 m0, s34
	s_nop 0
	global_load_lds_dwordx4 v[220:221], off
	s_barrier
	s_waitcnt lgkmcnt(0)
	s_setprio 1
	s_waitcnt lgkmcnt(0)
	v_mfma_f32_16x16x32_bf16 v[60:63], v[140:143], v[166:169], 0
	v_mfma_f32_16x16x32_bf16 v[56:59], v[158:161], v[166:169], 0
	v_mfma_f32_16x16x32_bf16 v[44:47], v[140:143], v[174:177], 0
	v_mfma_f32_16x16x32_bf16 v[40:43], v[158:161], v[174:177], 0
	v_mfma_f32_16x16x32_bf16 v[28:31], v[140:143], v[182:185], 0
	v_mfma_f32_16x16x32_bf16 v[24:27], v[158:161], v[182:185], 0
	v_mfma_f32_16x16x32_bf16 v[12:15], v[140:143], v[190:193], 0
	v_mfma_f32_16x16x32_bf16 v[8:11], v[158:161], v[190:193], 0
	v_mfma_f32_16x16x32_bf16 v[60:63], v[154:157], v[170:173], v[60:63]
	v_mfma_f32_16x16x32_bf16 v[56:59], v[162:165], v[170:173], v[56:59]
	v_mfma_f32_16x16x32_bf16 v[44:47], v[154:157], v[178:181], v[44:47]
	v_mfma_f32_16x16x32_bf16 v[40:43], v[162:165], v[178:181], v[40:43]
	v_mfma_f32_16x16x32_bf16 v[28:31], v[154:157], v[186:189], v[28:31]
	v_mfma_f32_16x16x32_bf16 v[24:27], v[162:165], v[186:189], v[24:27]
	v_mfma_f32_16x16x32_bf16 v[12:15], v[154:157], v[194:197], v[12:15]
	v_mfma_f32_16x16x32_bf16 v[8:11], v[162:165], v[194:197], v[8:11]
	s_setprio 0
	s_barrier
; #define PG8_STAGE(bufoff, gbase, voff) do { _Pragma("unroll") for (int _i = 0; _i < 2; ++_i) \
;         __builtin_amdgcn_global_load_lds((const unsigned*)((const char*)(gbase) + (voff)[_i]), (LAS unsigned*)(lds + (bufoff) + ldsw + _i * 8192), 16, 0, 0); } while (0)
; #define PG8_LDA(dst, b, h) do { _Pragma("unroll") for (int m = 0; m < 4; ++m) _Pragma("unroll") for (int k = 0; k < 2; ++k) dst[m][k] = *(const LAS bf16x8*)(lds + PG8_SA(b, h) + aoff + m * 2048 + k * 1024); } while (0)
; #define PG8_LDB(dst, b, h) do { _Pragma("unroll") for (int n = 0; n < 2; ++n) _Pragma("unroll") for (int k = 0; k < 2; ++k) dst[n][k] = *(const LAS bf16x8*)(lds + PG8_SB(b, h) + boff + n * 2048 + k * 1024); } while (0)
; #define PG8_MMA(ai, bj, At, Bt) do { __builtin_amdgcn_s_setprio(1); _Pragma("unroll") for (int m = 0; m < 4; ++m) _Pragma("unroll") for (int n = 0; n < 2; ++n) _Pragma("unroll") for (int k = 0; k < 2; ++k) \
;         acc[ai][bj][m][n] = __builtin_amdgcn_mfma_f32_16x16x32_bf16(Bt[n][k], At[m][k], acc[ai][bj][m][n], 0, 0, 0); __builtin_amdgcn_s_setprio(0); } while (0)
; #define PG8_WAIT_V(n) asm volatile("s_waitcnt vmcnt(" #n ")" ::: "memory")
; #define PG8_WAIT_L(n) asm volatile("s_waitcnt lgkmcnt(" #n ")" ::: "memory")
; #define PG8_BAR __builtin_amdgcn_s_barrier()
; #define PG8_SCHED __builtin_amdgcn_sched_barrier(0)
; template <class Epi, class Sched>
; __device__ __forceinline__ void gemm_phase(LAS unsigned char* lds, const Gemm g, const Sched& S, const Epi& E) {
;     ...
;             PG8_STAGE(PG8_SB(0, 1), b2 + hstep, voffB);
;             PG8_WAIT_V(6); PG8_BAR; PG8_MMA(1, 1, At, B1); PG8_BAR;
;             PG8_LDB(B0, 1, 0); PG8_SCHED; PG8_LDA(At, 1, 0); PG8_STAGE(PG8_SA(0, 1), a2 + hstep, voffA);
;             PG8_WAIT_L(8); PG8_BAR; PG8_WAIT_L(0); PG8_MMA(0, 0, At, B0); PG8_BAR; PG8_SCHED;
;             PG8_LDB(B1, 1, 1); PG8_STAGE(PG8_SB(1, 0), b3, voffB);
	s_add_u32 s62, s4, 0x40000
	s_addc_u32 s63, s5, 0
	s_add_i32 s64, s48, s31
	v_lshl_add_u64 v[140:141], s[62:63], 0, v[130:131]
	s_mov_b32 m0, s64
	s_nop 0
	global_load_lds_dwordx4 v[140:141], off
	v_lshl_add_u64 v[140:141], s[62:63], 0, v[134:135]
	s_add_i32 m0, s64, 0x2000
	s_nop 0
	global_load_lds_dwordx4 v[140:141], off
	s_waitcnt vmcnt(6)
	s_barrier
	s_setprio 1
	v_mfma_f32_16x16x32_bf16 v[52:55], v[202:205], v[166:169], 0
	v_mfma_f32_16x16x32_bf16 v[48:51], v[210:213], v[166:169], 0
	v_mfma_f32_16x16x32_bf16 v[36:39], v[202:205], v[174:177], 0
	v_mfma_f32_16x16x32_bf16 v[32:35], v[210:213], v[174:177], 0
	v_mfma_f32_16x16x32_bf16 v[20:23], v[202:205], v[182:185], 0
	v_mfma_f32_16x16x32_bf16 v[16:19], v[210:213], v[182:185], 0
	v_mfma_f32_16x16x32_bf16 v[4:7], v[202:205], v[190:193], 0
	v_mfma_f32_16x16x32_bf16 v[0:3], v[210:213], v[190:193], 0
	v_mfma_f32_16x16x32_bf16 v[52:55], v[206:209], v[170:173], v[52:55]
	v_mfma_f32_16x16x32_bf16 v[48:51], v[214:217], v[170:173], v[48:51]
	v_mfma_f32_16x16x32_bf16 v[36:39], v[206:209], v[178:181], v[36:39]
	v_mfma_f32_16x16x32_bf16 v[32:35], v[214:217], v[178:181], v[32:35]
	v_mfma_f32_16x16x32_bf16 v[20:23], v[206:209], v[186:189], v[20:23]
	v_mfma_f32_16x16x32_bf16 v[16:19], v[214:217], v[186:189], v[16:19]
	v_mfma_f32_16x16x32_bf16 v[4:7], v[206:209], v[194:197], v[4:7]
	v_mfma_f32_16x16x32_bf16 v[0:3], v[214:217], v[194:197], v[0:3]
	s_setprio 0
	s_add_i32 s62, 0, 0x18000
	v_add_u32_e32 v162, s62, v148
	s_barrier
	ds_read_b128 v[140:143], v162
	ds_read_b128 v[154:157], v162 offset:1024
	ds_read_b128 v[158:161], v162 offset:2048
	ds_read_b128 v[162:165], v162 offset:3072
	s_add_u32 s24, s24, 0x40000
	s_addc_u32 s25, s25, 0
	s_mov_b32 m0, s35
	v_lshl_add_u64 v[202:203], s[24:25], 0, v[128:129]
	ds_read_b128 v[166:169], v150 offset:32768
	ds_read_b128 v[170:173], v150 offset:33792
	ds_read_b128 v[174:177], v150 offset:34816
	ds_read_b128 v[178:181], v150 offset:35840
	ds_read_b128 v[182:185], v150 offset:36864
	ds_read_b128 v[186:189], v150 offset:37888
	ds_read_b128 v[190:193], v150 offset:38912
	ds_read_b128 v[194:197], v150 offset:39936
	global_load_lds_dwordx4 v[202:203], off
	v_lshl_add_u64 v[202:203], s[24:25], 0, v[132:133]
	s_mov_b32 m0, s36
	s_nop 0
	global_load_lds_dwordx4 v[202:203], off
	s_waitcnt lgkmcnt(8)
	s_barrier
	s_waitcnt lgkmcnt(0)
	s_setprio 1
	s_waitcnt lgkmcnt(0)
	v_mfma_f32_16x16x32_bf16 v[124:127], v[140:143], v[166:169], v[124:127]
	v_mfma_f32_16x16x32_bf16 v[120:123], v[158:161], v[166:169], v[120:123]
	v_mfma_f32_16x16x32_bf16 v[108:111], v[140:143], v[174:177], v[108:111]
	v_mfma_f32_16x16x32_bf16 v[104:107], v[158:161], v[174:177], v[104:107]
	v_mfma_f32_16x16x32_bf16 v[92:95], v[140:143], v[182:185], v[92:95]
	v_mfma_f32_16x16x32_bf16 v[88:91], v[158:161], v[182:185], v[88:91]
	v_mfma_f32_16x16x32_bf16 v[76:79], v[140:143], v[190:193], v[76:79]
	v_mfma_f32_16x16x32_bf16 v[72:75], v[158:161], v[190:193], v[72:75]
	v_mfma_f32_16x16x32_bf16 v[124:127], v[154:157], v[170:173], v[124:127]
	v_mfma_f32_16x16x32_bf16 v[120:123], v[162:165], v[170:173], v[120:123]
	v_mfma_f32_16x16x32_bf16 v[108:111], v[154:157], v[178:181], v[108:111]
	v_mfma_f32_16x16x32_bf16 v[104:107], v[162:165], v[178:181], v[104:107]
	v_mfma_f32_16x16x32_bf16 v[92:95], v[154:157], v[186:189], v[92:95]
	v_mfma_f32_16x16x32_bf16 v[88:91], v[162:165], v[186:189], v[88:91]
	v_mfma_f32_16x16x32_bf16 v[76:79], v[154:157], v[194:197], v[76:79]
	v_mfma_f32_16x16x32_bf16 v[72:75], v[162:165], v[194:197], v[72:75]
	s_setprio 0
	s_barrier
	s_add_i32 s24, 0, 0x1c000
	s_add_i32 s25, s62, s31
	v_add_u32_e32 v214, s24, v148
	v_lshl_add_u64 v[144:145], v[144:145], 0, s[0:1]
	s_mov_b32 m0, s25
	ds_read_b128 v[202:205], v214
	ds_read_b128 v[206:209], v214 offset:1024
	ds_read_b128 v[210:213], v214 offset:2048
	ds_read_b128 v[214:217], v214 offset:3072
	global_load_lds_dwordx4 v[144:145], off
	v_lshl_add_u64 v[144:145], v[198:199], 0, s[0:1]
	s_add_i32 m0, s25, 0x2000
	s_nop 0
	global_load_lds_dwordx4 v[144:145], off
	s_barrier
; #define PG8_STAGE(bufoff, gbase, voff) do { _Pragma("unroll") for (int _i = 0; _i < 2; ++_i) \
;         __builtin_amdgcn_global_load_lds((const unsigned*)((const char*)(gbase) + (voff)[_i]), (LAS unsigned*)(lds + (bufoff) + ldsw + _i * 8192), 16, 0, 0); } while (0)
; #define PG8_LDA(dst, b, h) do { _Pragma("unroll") for (int m = 0; m < 4; ++m) _Pragma("unroll") for (int k = 0; k < 2; ++k) dst[m][k] = *(const LAS bf16x8*)(lds + PG8_SA(b, h) + aoff + m * 2048 + k * 1024); } while (0)
; #define PG8_LDB(dst, b, h) do { _Pragma("unroll") for (int n = 0; n < 2; ++n) _Pragma("unroll") for (int k = 0; k < 2; ++k) dst[n][k] = *(const LAS bf16x8*)(lds + PG8_SB(b, h) + boff + n * 2048 + k * 1024); } while (0)
; #define PG8_MMA(ai, bj, At, Bt) do { __builtin_amdgcn_s_setprio(1); _Pragma("unroll") for (int m = 0; m < 4; ++m) _Pragma("unroll") for (int n = 0; n < 2; ++n) _Pragma("unroll") for (int k = 0; k < 2; ++k) \
;         acc[ai][bj][m][n] = __builtin_amdgcn_mfma_f32_16x16x32_bf16(Bt[n][k], At[m][k], acc[ai][bj][m][n], 0, 0, 0); __builtin_amdgcn_s_setprio(0); } while (0)
; #define PG8_WAIT_V(n) asm volatile("s_waitcnt vmcnt(" #n ")" ::: "memory")
; #define PG8_WAIT_L(n) asm volatile("s_waitcnt lgkmcnt(" #n ")" ::: "memory")
; #define PG8_BAR __builtin_amdgcn_s_barrier()
; #define PG8_SCHED __builtin_amdgcn_sched_barrier(0)
; template <class Epi, class Sched>
; __device__ __forceinline__ void gemm_phase(LAS unsigned char* lds, const Gemm g, const Sched& S, const Epi& E) {
;     ...
;             PG8_LDB(B1, 1, 1); PG8_STAGE(PG8_SB(1, 0), b3, voffB);
;             PG8_BAR; PG8_WAIT_L(0); PG8_MMA(0, 1, At, B1); PG8_BAR;
;             PG8_LDA(At, 1, 1); PG8_STAGE(PG8_SA(1, 0), a3, voffA);
;             PG8_BAR; PG8_WAIT_L(0); PG8_MMA(1, 0, At, B0); PG8_BAR; PG8_SCHED;
;             PG8_STAGE(PG8_SB(1, 1), b3 + hstep, voffB);
;             PG8_WAIT_V(6); PG8_BAR; PG8_MMA(1, 1, At, B1); PG8_BAR;
	s_waitcnt lgkmcnt(0)
	s_setprio 1
	s_waitcnt lgkmcnt(0)
	v_mfma_f32_16x16x32_bf16 v[116:119], v[202:205], v[166:169], v[116:119]
	v_mfma_f32_16x16x32_bf16 v[112:115], v[210:213], v[166:169], v[112:115]
	v_mfma_f32_16x16x32_bf16 v[100:103], v[202:205], v[174:177], v[100:103]
	v_mfma_f32_16x16x32_bf16 v[96:99], v[210:213], v[174:177], v[96:99]
	v_mfma_f32_16x16x32_bf16 v[84:87], v[202:205], v[182:185], v[84:87]
	v_mfma_f32_16x16x32_bf16 v[80:83], v[210:213], v[182:185], v[80:83]
	v_mfma_f32_16x16x32_bf16 v[68:71], v[202:205], v[190:193], v[68:71]
	v_mfma_f32_16x16x32_bf16 v[64:67], v[210:213], v[190:193], v[64:67]
	v_mfma_f32_16x16x32_bf16 v[116:119], v[206:209], v[170:173], v[116:119]
	v_mfma_f32_16x16x32_bf16 v[112:115], v[214:217], v[170:173], v[112:115]
	v_mfma_f32_16x16x32_bf16 v[100:103], v[206:209], v[178:181], v[100:103]
	v_mfma_f32_16x16x32_bf16 v[96:99], v[214:217], v[178:181], v[96:99]
	v_mfma_f32_16x16x32_bf16 v[84:87], v[206:209], v[186:189], v[84:87]
	v_mfma_f32_16x16x32_bf16 v[80:83], v[214:217], v[186:189], v[80:83]
	v_mfma_f32_16x16x32_bf16 v[68:71], v[206:209], v[194:197], v[68:71]
	v_mfma_f32_16x16x32_bf16 v[64:67], v[214:217], v[194:197], v[64:67]
	s_setprio 0
	s_mov_b32 m0, s44
	v_lshl_add_u64 v[144:145], v[218:219], 0, s[0:1]
	s_barrier
	ds_read_b128 v[166:169], v150 offset:49152
	ds_read_b128 v[170:173], v150 offset:50176
	ds_read_b128 v[174:177], v150 offset:51200
	ds_read_b128 v[178:181], v150 offset:52224
	ds_read_b128 v[182:185], v150 offset:53248
	ds_read_b128 v[186:189], v150 offset:54272
	ds_read_b128 v[190:193], v150 offset:55296
	ds_read_b128 v[194:197], v150 offset:56320
	global_load_lds_dwordx4 v[144:145], off
	v_lshl_add_u64 v[144:145], v[220:221], 0, s[0:1]
	s_mov_b32 m0, s45
	s_nop 0
	global_load_lds_dwordx4 v[144:145], off
	s_barrier
	s_waitcnt lgkmcnt(0)
	s_setprio 1
	s_waitcnt lgkmcnt(0)
	v_mfma_f32_16x16x32_bf16 v[60:63], v[140:143], v[166:169], v[60:63]
	v_mfma_f32_16x16x32_bf16 v[56:59], v[158:161], v[166:169], v[56:59]
	v_mfma_f32_16x16x32_bf16 v[44:47], v[140:143], v[174:177], v[44:47]
	v_mfma_f32_16x16x32_bf16 v[40:43], v[158:161], v[174:177], v[40:43]
	v_mfma_f32_16x16x32_bf16 v[28:31], v[140:143], v[182:185], v[28:31]
	v_mfma_f32_16x16x32_bf16 v[24:27], v[158:161], v[182:185], v[24:27]
	v_mfma_f32_16x16x32_bf16 v[12:15], v[140:143], v[190:193], v[12:15]
	v_mfma_f32_16x16x32_bf16 v[8:11], v[158:161], v[190:193], v[8:11]
	v_mfma_f32_16x16x32_bf16 v[60:63], v[154:157], v[170:173], v[60:63]
	v_mfma_f32_16x16x32_bf16 v[56:59], v[162:165], v[170:173], v[56:59]
	v_mfma_f32_16x16x32_bf16 v[44:47], v[154:157], v[178:181], v[44:47]
	v_mfma_f32_16x16x32_bf16 v[40:43], v[162:165], v[178:181], v[40:43]
	v_mfma_f32_16x16x32_bf16 v[28:31], v[154:157], v[186:189], v[28:31]
	v_mfma_f32_16x16x32_bf16 v[24:27], v[162:165], v[186:189], v[24:27]
	v_mfma_f32_16x16x32_bf16 v[12:15], v[154:157], v[194:197], v[12:15]
	v_mfma_f32_16x16x32_bf16 v[8:11], v[162:165], v[194:197], v[8:11]
	s_setprio 0
	s_barrier
	s_add_u32 s4, s4, 0x40080
	s_addc_u32 s5, s5, 0
	s_add_i32 s24, s24, s31
	v_lshl_add_u64 v[140:141], s[4:5], 0, v[130:131]
	s_mov_b32 m0, s24
	s_nop 0
	global_load_lds_dwordx4 v[140:141], off
	v_lshl_add_u64 v[140:141], s[4:5], 0, v[134:135]
	s_add_i32 m0, s24, 0x2000
	s_nop 0
	global_load_lds_dwordx4 v[140:141], off
	s_waitcnt vmcnt(6)
	s_barrier
	s_setprio 1
	v_mfma_f32_16x16x32_bf16 v[52:55], v[202:205], v[166:169], v[52:55]
	v_mfma_f32_16x16x32_bf16 v[48:51], v[210:213], v[166:169], v[48:51]
	v_mfma_f32_16x16x32_bf16 v[36:39], v[202:205], v[174:177], v[36:39]
	v_mfma_f32_16x16x32_bf16 v[32:35], v[210:213], v[174:177], v[32:35]
	v_mfma_f32_16x16x32_bf16 v[20:23], v[202:205], v[182:185], v[20:23]
	v_mfma_f32_16x16x32_bf16 v[16:19], v[210:213], v[182:185], v[16:19]
	v_mfma_f32_16x16x32_bf16 v[4:7], v[202:205], v[190:193], v[4:7]
	v_mfma_f32_16x16x32_bf16 v[0:3], v[210:213], v[190:193], v[0:3]
	v_mfma_f32_16x16x32_bf16 v[52:55], v[206:209], v[170:173], v[52:55]
	v_mfma_f32_16x16x32_bf16 v[48:51], v[214:217], v[170:173], v[48:51]
	v_mfma_f32_16x16x32_bf16 v[36:39], v[206:209], v[178:181], v[36:39]
	v_mfma_f32_16x16x32_bf16 v[32:35], v[214:217], v[178:181], v[32:35]
	v_mfma_f32_16x16x32_bf16 v[20:23], v[206:209], v[186:189], v[20:23]
	v_mfma_f32_16x16x32_bf16 v[16:19], v[214:217], v[186:189], v[16:19]
	v_mfma_f32_16x16x32_bf16 v[4:7], v[206:209], v[194:197], v[4:7]
	v_mfma_f32_16x16x32_bf16 v[0:3], v[214:217], v[194:197], v[0:3]
	s_setprio 0
	s_add_i32 s61, s61, 2
	s_add_u32 s2, s2, 0x100
	s_addc_u32 s3, s3, 0
	s_add_u32 s59, s59, 0x100
	s_addc_u32 s60, s60, 0
	s_cmp_gt_u32 s61, 13
	s_barrier

; #define PG8_STAGE(bufoff, gbase, voff) do { _Pragma("unroll") for (int _i = 0; _i < 2; ++_i) \
;         __builtin_amdgcn_global_load_lds((const unsigned*)((const char*)(gbase) + (voff)[_i]), (LAS unsigned*)(lds + (bufoff) + ldsw + _i * 8192), 16, 0, 0); } while (0)
; #define PG8_LDA(dst, b, h) do { _Pragma("unroll") for (int m = 0; m < 4; ++m) _Pragma("unroll") for (int k = 0; k < 2; ++k) dst[m][k] = *(const LAS bf16x8*)(lds + PG8_SA(b, h) + aoff + m * 2048 + k * 1024); } while (0)
; #define PG8_LDB(dst, b, h) do { _Pragma("unroll") for (int n = 0; n < 2; ++n) _Pragma("unroll") for (int k = 0; k < 2; ++k) dst[n][k] = *(const LAS bf16x8*)(lds + PG8_SB(b, h) + boff + n * 2048 + k * 1024); } while (0)
; #define PG8_MMA(ai, bj, At, Bt) do { __builtin_amdgcn_s_setprio(1); _Pragma("unroll") for (int m = 0; m < 4; ++m) _Pragma("unroll") for (int n = 0; n < 2; ++n) _Pragma("unroll") for (int k = 0; k < 2; ++k) \
;         acc[ai][bj][m][n] = __builtin_amdgcn_mfma_f32_16x16x32_bf16(Bt[n][k], At[m][k], acc[ai][bj][m][n], 0, 0, 0); __builtin_amdgcn_s_setprio(0); } while (0)
; #define PG8_WAIT_L(n) asm volatile("s_waitcnt lgkmcnt(" #n ")" ::: "memory")
; #define PG8_BAR __builtin_amdgcn_s_barrier()
; #define PG8_SCHED __builtin_amdgcn_sched_barrier(0)
; template <class Epi, class Sched>
; __device__ __forceinline__ void gemm_phase(LAS unsigned char* lds, const Gemm g, const Sched& S, const Epi& E) {
;     ...
;             PG8_LDB(B0, 0, 0); PG8_SCHED; PG8_LDA(At, 0, 0); PG8_STAGE(PG8_SA(1, 1), a1 + hstep, voffA);
;             PG8_WAIT_L(8); PG8_BAR; PG8_WAIT_L(0); PG8_MMA(0, 0, At, B0); PG8_BAR; PG8_SCHED;
;             PG8_LDB(B1, 0, 1); PG8_STAGE(PG8_SB(0, 0), b2, voffB);
;             PG8_BAR; PG8_WAIT_L(0); PG8_MMA(0, 1, At, B1); PG8_BAR;
;             PG8_LDA(At, 0, 1); PG8_STAGE(PG8_SA(0, 0), a2, voffA);
;             PG8_BAR; PG8_WAIT_L(0); PG8_MMA(1, 0, At, B0); PG8_BAR; PG8_SCHED;
;     ...
; #pragma unroll
;         for (int a = 0; a < 2; ++a)
; #pragma unroll
;             for (int b = 0; b < 2; ++b)
; #pragma unroll
;                 for (int m = 0; m < 4; ++m)
; #pragma unroll
;                     for (int n = 0; n < 2; ++n) acc[a][b][m][n] = (f32x4){0.f, 0.f, 0.f, 0.f};
.LBB0_712:
	s_ashr_i32 s15, s14, 31
	v_cmp_lt_i64_e64 s[26:27], s[16:17], 64
	s_lshl_b64 s[16:17], s[14:15], 19
	s_add_u32 s16, s38, s16
	s_addc_u32 s17, s39, s17
	s_and_b64 s[18:19], s[26:27], exec
	s_cselect_b32 s15, s17, s23
	s_cselect_b32 s54, s16, s22
	s_ashr_i32 s13, s12, 31
	s_lshl_b64 s[18:19], s[12:13], 19
	s_add_u32 s18, s28, s18
	s_addc_u32 s19, s29, s19
	s_and_b64 s[26:27], s[26:27], exec
	s_cselect_b32 s13, s19, s25
	s_cselect_b32 s55, s18, s24
	s_add_u32 s22, s22, 0x40080
	s_addc_u32 s23, s23, 0
	s_add_u32 s56, s24, 0x100
	s_addc_u32 s57, s25, 0
	s_mov_b32 s58, -2
	s_waitcnt lgkmcnt(0)
	ds_read_b128 v[146:149], v143
	ds_read_b128 v[150:153], v143 offset:1024
	ds_read_b128 v[154:157], v143 offset:2048
	ds_read_b128 v[158:161], v143 offset:3072
	s_add_u32 s24, s22, 0xfffc0080
	s_addc_u32 s25, s23, -1
	s_cmp_eq_u32 s58, 12
	s_cselect_b32 s27, s15, s25
	s_cselect_b32 s26, s54, s24
	s_cselect_b32 s25, s13, s57
	s_cselect_b32 s24, s55, s56
	v_lshl_add_u64 v[194:195], s[22:23], 0, v[136:137]
	s_add_i32 m0, s21, 0xc000
	ds_read_b128 v[162:165], v144
	ds_read_b128 v[166:169], v144 offset:1024
	ds_read_b128 v[170:173], v144 offset:2048
	ds_read_b128 v[174:177], v144 offset:3072
	ds_read_b128 v[178:181], v144 offset:4096
	ds_read_b128 v[182:185], v144 offset:5120
	ds_read_b128 v[186:189], v144 offset:6144
	ds_read_b128 v[190:193], v144 offset:7168
	global_load_lds_dwordx4 v[194:195], off
	v_lshl_add_u64 v[194:195], s[22:23], 0, v[138:139]
	s_add_i32 m0, s21, 0xe000
	s_nop 0
	global_load_lds_dwordx4 v[194:195], off
	s_waitcnt lgkmcnt(8)
	s_barrier
	s_waitcnt lgkmcnt(0)
	s_setprio 1
	s_waitcnt lgkmcnt(0)
	v_mfma_f32_16x16x32_bf16 v[124:127], v[146:149], v[162:165], 0
	v_mfma_f32_16x16x32_bf16 v[120:123], v[154:157], v[162:165], 0
	v_mfma_f32_16x16x32_bf16 v[116:119], v[146:149], v[170:173], 0
	v_mfma_f32_16x16x32_bf16 v[108:111], v[154:157], v[170:173], 0
	v_mfma_f32_16x16x32_bf16 v[100:103], v[146:149], v[178:181], 0
	v_mfma_f32_16x16x32_bf16 v[92:95], v[154:157], v[178:181], 0
	v_mfma_f32_16x16x32_bf16 v[84:87], v[146:149], v[186:189], 0
	v_mfma_f32_16x16x32_bf16 v[76:79], v[154:157], v[186:189], 0
	v_mfma_f32_16x16x32_bf16 v[124:127], v[150:153], v[166:169], v[124:127]
	v_mfma_f32_16x16x32_bf16 v[120:123], v[158:161], v[166:169], v[120:123]
	v_mfma_f32_16x16x32_bf16 v[116:119], v[150:153], v[174:177], v[116:119]
	v_mfma_f32_16x16x32_bf16 v[108:111], v[158:161], v[174:177], v[108:111]
	v_mfma_f32_16x16x32_bf16 v[100:103], v[150:153], v[182:185], v[100:103]
	v_mfma_f32_16x16x32_bf16 v[92:95], v[158:161], v[182:185], v[92:95]
	v_mfma_f32_16x16x32_bf16 v[84:87], v[150:153], v[190:193], v[84:87]
	v_mfma_f32_16x16x32_bf16 v[76:79], v[158:161], v[190:193], v[76:79]
	s_setprio 0
	s_barrier
	s_add_i32 s59, s46, s34
	v_lshl_add_u64 v[198:199], s[24:25], 0, v[130:131]
	s_mov_b32 m0, s59
	ds_read_b128 v[194:197], v145
	ds_read_b128 v[202:205], v145 offset:1024
	ds_read_b128 v[206:209], v145 offset:2048
	ds_read_b128 v[210:213], v145 offset:3072
	global_load_lds_dwordx4 v[198:199], off
	v_lshl_add_u64 v[214:215], s[24:25], 0, v[134:135]
	s_add_i32 m0, s59, 0x2000
	s_nop 0
	global_load_lds_dwordx4 v[214:215], off
	s_barrier
	s_waitcnt lgkmcnt(0)
	s_setprio 1
	s_waitcnt lgkmcnt(0)
	v_mfma_f32_16x16x32_bf16 v[112:115], v[194:197], v[162:165], 0
	v_mfma_f32_16x16x32_bf16 v[104:107], v[206:209], v[162:165], 0
	v_mfma_f32_16x16x32_bf16 v[96:99], v[194:197], v[170:173], 0
	v_mfma_f32_16x16x32_bf16 v[88:91], v[206:209], v[170:173], 0
	v_mfma_f32_16x16x32_bf16 v[80:83], v[194:197], v[178:181], 0
	v_mfma_f32_16x16x32_bf16 v[72:75], v[206:209], v[178:181], 0
	v_mfma_f32_16x16x32_bf16 v[68:71], v[194:197], v[186:189], 0
	v_mfma_f32_16x16x32_bf16 v[64:67], v[206:209], v[186:189], 0
	v_mfma_f32_16x16x32_bf16 v[112:115], v[202:205], v[166:169], v[112:115]
	v_mfma_f32_16x16x32_bf16 v[104:107], v[210:213], v[166:169], v[104:107]
	v_mfma_f32_16x16x32_bf16 v[96:99], v[202:205], v[174:177], v[96:99]
	v_mfma_f32_16x16x32_bf16 v[88:91], v[210:213], v[174:177], v[88:91]
	v_mfma_f32_16x16x32_bf16 v[80:83], v[202:205], v[182:185], v[80:83]
	v_mfma_f32_16x16x32_bf16 v[72:75], v[210:213], v[182:185], v[72:75]
	v_mfma_f32_16x16x32_bf16 v[68:71], v[202:205], v[190:193], v[68:71]
	v_mfma_f32_16x16x32_bf16 v[64:67], v[210:213], v[190:193], v[64:67]
	s_setprio 0
	s_mov_b32 m0, s21
	v_lshl_add_u64 v[216:217], s[26:27], 0, v[128:129]
	s_barrier
	ds_read_b128 v[162:165], v144 offset:16384
	ds_read_b128 v[166:169], v144 offset:17408
	ds_read_b128 v[170:173], v144 offset:18432
	ds_read_b128 v[174:177], v144 offset:19456
	ds_read_b128 v[178:181], v144 offset:20480
	ds_read_b128 v[182:185], v144 offset:21504
	ds_read_b128 v[186:189], v144 offset:22528
	ds_read_b128 v[190:193], v144 offset:23552
	global_load_lds_dwordx4 v[216:217], off
	v_lshl_add_u64 v[218:219], s[26:27], 0, v[132:133]
	s_mov_b32 m0, s35
	s_nop 0
	global_load_lds_dwordx4 v[218:219], off
	s_barrier
	s_waitcnt lgkmcnt(0)
	s_setprio 1
	s_waitcnt lgkmcnt(0)
	v_mfma_f32_16x16x32_bf16 v[60:63], v[146:149], v[162:165], 0
	v_mfma_f32_16x16x32_bf16 v[56:59], v[154:157], v[162:165], 0
	v_mfma_f32_16x16x32_bf16 v[52:55], v[146:149], v[170:173], 0
	v_mfma_f32_16x16x32_bf16 v[44:47], v[154:157], v[170:173], 0
	v_mfma_f32_16x16x32_bf16 v[36:39], v[146:149], v[178:181], 0
	v_mfma_f32_16x16x32_bf16 v[28:31], v[154:157], v[178:181], 0
	v_mfma_f32_16x16x32_bf16 v[20:23], v[146:149], v[186:189], 0
	v_mfma_f32_16x16x32_bf16 v[12:15], v[154:157], v[186:189], 0
	v_mfma_f32_16x16x32_bf16 v[60:63], v[150:153], v[166:169], v[60:63]
	v_mfma_f32_16x16x32_bf16 v[56:59], v[158:161], v[166:169], v[56:59]
	v_mfma_f32_16x16x32_bf16 v[52:55], v[150:153], v[174:177], v[52:55]
	v_mfma_f32_16x16x32_bf16 v[44:47], v[158:161], v[174:177], v[44:47]
	v_mfma_f32_16x16x32_bf16 v[36:39], v[150:153], v[182:185], v[36:39]
	v_mfma_f32_16x16x32_bf16 v[28:31], v[158:161], v[182:185], v[28:31]
	v_mfma_f32_16x16x32_bf16 v[20:23], v[150:153], v[190:193], v[20:23]
	v_mfma_f32_16x16x32_bf16 v[12:15], v[158:161], v[190:193], v[12:15]
	s_setprio 0
	s_barrier
; #define PG8_STAGE(bufoff, gbase, voff) do { _Pragma("unroll") for (int _i = 0; _i < 2; ++_i) \
;         __builtin_amdgcn_global_load_lds((const unsigned*)((const char*)(gbase) + (voff)[_i]), (LAS unsigned*)(lds + (bufoff) + ldsw + _i * 8192), 16, 0, 0); } while (0)
; #define PG8_LDA(dst, b, h) do { _Pragma("unroll") for (int m = 0; m < 4; ++m) _Pragma("unroll") for (int k = 0; k < 2; ++k) dst[m][k] = *(const LAS bf16x8*)(lds + PG8_SA(b, h) + aoff + m * 2048 + k * 1024); } while (0)
; #define PG8_LDB(dst, b, h) do { _Pragma("unroll") for (int n = 0; n < 2; ++n) _Pragma("unroll") for (int k = 0; k < 2; ++k) dst[n][k] = *(const LAS bf16x8*)(lds + PG8_SB(b, h) + boff + n * 2048 + k * 1024); } while (0)
; #define PG8_MMA(ai, bj, At, Bt) do { __builtin_amdgcn_s_setprio(1); _Pragma("unroll") for (int m = 0; m < 4; ++m) _Pragma("unroll") for (int n = 0; n < 2; ++n) _Pragma("unroll") for (int k = 0; k < 2; ++k) \
;         acc[ai][bj][m][n] = __builtin_amdgcn_mfma_f32_16x16x32_bf16(Bt[n][k], At[m][k], acc[ai][bj][m][n], 0, 0, 0); __builtin_amdgcn_s_setprio(0); } while (0)
; #define PG8_WAIT_V(n) asm volatile("s_waitcnt vmcnt(" #n ")" ::: "memory")
; #define PG8_WAIT_L(n) asm volatile("s_waitcnt lgkmcnt(" #n ")" ::: "memory")
; #define PG8_BAR __builtin_amdgcn_s_barrier()
; #define PG8_SCHED __builtin_amdgcn_sched_barrier(0)
; template <class Epi, class Sched>
; __device__ __forceinline__ void gemm_phase(LAS unsigned char* lds, const Gemm g, const Sched& S, const Epi& E) {
;     ...
;             PG8_STAGE(PG8_SB(0, 1), b2 + hstep, voffB);
;             PG8_WAIT_V(6); PG8_BAR; PG8_MMA(1, 1, At, B1); PG8_BAR;
;             PG8_LDB(B0, 1, 0); PG8_SCHED; PG8_LDA(At, 1, 0); PG8_STAGE(PG8_SA(0, 1), a2 + hstep, voffA);
;             PG8_WAIT_L(8); PG8_BAR; PG8_WAIT_L(0); PG8_MMA(0, 0, At, B0); PG8_BAR; PG8_SCHED;
;             PG8_LDB(B1, 1, 1); PG8_STAGE(PG8_SB(1, 0), b3, voffB);
	s_add_u32 s60, s24, 0x40000
	s_addc_u32 s61, s25, 0
	s_add_i32 s59, s47, s34
	v_lshl_add_u64 v[146:147], s[60:61], 0, v[130:131]
	s_mov_b32 m0, s59
	s_nop 0
	global_load_lds_dwordx4 v[146:147], off
	v_lshl_add_u64 v[146:147], s[60:61], 0, v[134:135]
	s_add_i32 m0, s59, 0x2000
	s_nop 0
	global_load_lds_dwordx4 v[146:147], off
	s_waitcnt vmcnt(6)
	s_barrier
	s_setprio 1
	v_mfma_f32_16x16x32_bf16 v[48:51], v[194:197], v[162:165], 0
	v_mfma_f32_16x16x32_bf16 v[40:43], v[206:209], v[162:165], 0
	v_mfma_f32_16x16x32_bf16 v[32:35], v[194:197], v[170:173], 0
	v_mfma_f32_16x16x32_bf16 v[24:27], v[206:209], v[170:173], 0
	v_mfma_f32_16x16x32_bf16 v[16:19], v[194:197], v[178:181], 0
	v_mfma_f32_16x16x32_bf16 v[8:11], v[206:209], v[178:181], 0
	v_mfma_f32_16x16x32_bf16 v[4:7], v[194:197], v[186:189], 0
	v_mfma_f32_16x16x32_bf16 v[0:3], v[206:209], v[186:189], 0
	v_mfma_f32_16x16x32_bf16 v[48:51], v[202:205], v[166:169], v[48:51]
	v_mfma_f32_16x16x32_bf16 v[40:43], v[210:213], v[166:169], v[40:43]
	v_mfma_f32_16x16x32_bf16 v[32:35], v[202:205], v[174:177], v[32:35]
	v_mfma_f32_16x16x32_bf16 v[24:27], v[210:213], v[174:177], v[24:27]
	v_mfma_f32_16x16x32_bf16 v[16:19], v[202:205], v[182:185], v[16:19]
	v_mfma_f32_16x16x32_bf16 v[8:11], v[210:213], v[182:185], v[8:11]
	v_mfma_f32_16x16x32_bf16 v[4:7], v[202:205], v[190:193], v[4:7]
	v_mfma_f32_16x16x32_bf16 v[0:3], v[210:213], v[190:193], v[0:3]
	s_setprio 0
	s_add_i32 s59, 0, 0x18000
	v_add_u32_e32 v158, s59, v142
	s_barrier
	ds_read_b128 v[146:149], v158
	ds_read_b128 v[150:153], v158 offset:1024
	ds_read_b128 v[154:157], v158 offset:2048
	ds_read_b128 v[158:161], v158 offset:3072
	s_add_u32 s26, s26, 0x40000
	s_addc_u32 s27, s27, 0
	s_mov_b32 m0, s36
	v_lshl_add_u64 v[194:195], s[26:27], 0, v[128:129]
	ds_read_b128 v[162:165], v144 offset:32768
	ds_read_b128 v[166:169], v144 offset:33792
	ds_read_b128 v[170:173], v144 offset:34816
	ds_read_b128 v[174:177], v144 offset:35840
	ds_read_b128 v[178:181], v144 offset:36864
	ds_read_b128 v[182:185], v144 offset:37888
	ds_read_b128 v[186:189], v144 offset:38912
	ds_read_b128 v[190:193], v144 offset:39936
	global_load_lds_dwordx4 v[194:195], off
	v_lshl_add_u64 v[194:195], s[26:27], 0, v[132:133]
	s_mov_b32 m0, s37
	s_nop 0
	global_load_lds_dwordx4 v[194:195], off
	s_waitcnt lgkmcnt(8)
	s_barrier
	s_waitcnt lgkmcnt(0)
	s_setprio 1
	s_waitcnt lgkmcnt(0)
	v_mfma_f32_16x16x32_bf16 v[124:127], v[146:149], v[162:165], v[124:127]
	v_mfma_f32_16x16x32_bf16 v[120:123], v[154:157], v[162:165], v[120:123]
	v_mfma_f32_16x16x32_bf16 v[116:119], v[146:149], v[170:173], v[116:119]
	v_mfma_f32_16x16x32_bf16 v[108:111], v[154:157], v[170:173], v[108:111]
	v_mfma_f32_16x16x32_bf16 v[100:103], v[146:149], v[178:181], v[100:103]
	v_mfma_f32_16x16x32_bf16 v[92:95], v[154:157], v[178:181], v[92:95]
	v_mfma_f32_16x16x32_bf16 v[84:87], v[146:149], v[186:189], v[84:87]
	v_mfma_f32_16x16x32_bf16 v[76:79], v[154:157], v[186:189], v[76:79]
	v_mfma_f32_16x16x32_bf16 v[124:127], v[150:153], v[166:169], v[124:127]
	v_mfma_f32_16x16x32_bf16 v[120:123], v[158:161], v[166:169], v[120:123]
	v_mfma_f32_16x16x32_bf16 v[116:119], v[150:153], v[174:177], v[116:119]
	v_mfma_f32_16x16x32_bf16 v[108:111], v[158:161], v[174:177], v[108:111]
	v_mfma_f32_16x16x32_bf16 v[100:103], v[150:153], v[182:185], v[100:103]
	v_mfma_f32_16x16x32_bf16 v[92:95], v[158:161], v[182:185], v[92:95]
	v_mfma_f32_16x16x32_bf16 v[84:87], v[150:153], v[190:193], v[84:87]
	v_mfma_f32_16x16x32_bf16 v[76:79], v[158:161], v[190:193], v[76:79]
	s_setprio 0
	s_barrier
	s_add_i32 s26, 0, 0x1c000
	s_add_i32 s27, s59, s34
	v_add_u32_e32 v210, s26, v142
	v_lshl_add_u64 v[198:199], v[198:199], 0, s[0:1]
	s_mov_b32 m0, s27
	ds_read_b128 v[194:197], v210
	ds_read_b128 v[202:205], v210 offset:1024
	ds_read_b128 v[206:209], v210 offset:2048
	ds_read_b128 v[210:213], v210 offset:3072
	global_load_lds_dwordx4 v[198:199], off
	v_lshl_add_u64 v[198:199], v[214:215], 0, s[0:1]
	s_add_i32 m0, s27, 0x2000
	s_nop 0
	global_load_lds_dwordx4 v[198:199], off
	s_barrier
; #define PG8_STAGE(bufoff, gbase, voff) do { _Pragma("unroll") for (int _i = 0; _i < 2; ++_i) \
;         __builtin_amdgcn_global_load_lds((const unsigned*)((const char*)(gbase) + (voff)[_i]), (LAS unsigned*)(lds + (bufoff) + ldsw + _i * 8192), 16, 0, 0); } while (0)
; #define PG8_LDA(dst, b, h) do { _Pragma("unroll") for (int m = 0; m < 4; ++m) _Pragma("unroll") for (int k = 0; k < 2; ++k) dst[m][k] = *(const LAS bf16x8*)(lds + PG8_SA(b, h) + aoff + m * 2048 + k * 1024); } while (0)
; #define PG8_MMA(ai, bj, At, Bt) do { __builtin_amdgcn_s_setprio(1); _Pragma("unroll") for (int m = 0; m < 4; ++m) _Pragma("unroll") for (int n = 0; n < 2; ++n) _Pragma("unroll") for (int k = 0; k < 2; ++k) \
;         acc[ai][bj][m][n] = __builtin_amdgcn_mfma_f32_16x16x32_bf16(Bt[n][k], At[m][k], acc[ai][bj][m][n], 0, 0, 0); __builtin_amdgcn_s_setprio(0); } while (0)
; #define PG8_WAIT_V(n) asm volatile("s_waitcnt vmcnt(" #n ")" ::: "memory")
; #define PG8_WAIT_L(n) asm volatile("s_waitcnt lgkmcnt(" #n ")" ::: "memory")
; #define PG8_BAR __builtin_amdgcn_s_barrier()
; #define PG8_SCHED __builtin_amdgcn_sched_barrier(0)
; template <class Epi, class Sched>
; __device__ __forceinline__ void gemm_phase(LAS unsigned char* lds, const Gemm g, const Sched& S, const Epi& E) {
;     ...
;             PG8_BAR; PG8_WAIT_L(0); PG8_MMA(0, 1, At, B1); PG8_BAR;
;             PG8_LDA(At, 1, 1); PG8_STAGE(PG8_SA(1, 0), a3, voffA);
;             PG8_BAR; PG8_WAIT_L(0); PG8_MMA(1, 0, At, B0); PG8_BAR; PG8_SCHED;
;             PG8_STAGE(PG8_SB(1, 1), b3 + hstep, voffB);
;             PG8_WAIT_V(6); PG8_BAR; PG8_MMA(1, 1, At, B1); PG8_BAR;
	s_waitcnt lgkmcnt(0)
	s_setprio 1
	s_waitcnt lgkmcnt(0)
	v_mfma_f32_16x16x32_bf16 v[112:115], v[194:197], v[162:165], v[112:115]
	v_mfma_f32_16x16x32_bf16 v[104:107], v[206:209], v[162:165], v[104:107]
	v_mfma_f32_16x16x32_bf16 v[96:99], v[194:197], v[170:173], v[96:99]
	v_mfma_f32_16x16x32_bf16 v[88:91], v[206:209], v[170:173], v[88:91]
	v_mfma_f32_16x16x32_bf16 v[80:83], v[194:197], v[178:181], v[80:83]
	v_mfma_f32_16x16x32_bf16 v[72:75], v[206:209], v[178:181], v[72:75]
	v_mfma_f32_16x16x32_bf16 v[68:71], v[194:197], v[186:189], v[68:71]
	v_mfma_f32_16x16x32_bf16 v[64:67], v[206:209], v[186:189], v[64:67]
	v_mfma_f32_16x16x32_bf16 v[112:115], v[202:205], v[166:169], v[112:115]
	v_mfma_f32_16x16x32_bf16 v[104:107], v[210:213], v[166:169], v[104:107]
	v_mfma_f32_16x16x32_bf16 v[96:99], v[202:205], v[174:177], v[96:99]
	v_mfma_f32_16x16x32_bf16 v[88:91], v[210:213], v[174:177], v[88:91]
	v_mfma_f32_16x16x32_bf16 v[80:83], v[202:205], v[182:185], v[80:83]
	v_mfma_f32_16x16x32_bf16 v[72:75], v[210:213], v[182:185], v[72:75]
	v_mfma_f32_16x16x32_bf16 v[68:71], v[202:205], v[190:193], v[68:71]
	v_mfma_f32_16x16x32_bf16 v[64:67], v[210:213], v[190:193], v[64:67]
	s_setprio 0
	s_mov_b32 m0, s43
	v_lshl_add_u64 v[198:199], v[216:217], 0, s[0:1]
	s_barrier
	ds_read_b128 v[162:165], v144 offset:49152
	ds_read_b128 v[166:169], v144 offset:50176
	ds_read_b128 v[170:173], v144 offset:51200
	ds_read_b128 v[174:177], v144 offset:52224
	ds_read_b128 v[178:181], v144 offset:53248
	ds_read_b128 v[182:185], v144 offset:54272
	ds_read_b128 v[186:189], v144 offset:55296
	ds_read_b128 v[190:193], v144 offset:56320
	global_load_lds_dwordx4 v[198:199], off
	v_lshl_add_u64 v[198:199], v[218:219], 0, s[0:1]
	s_mov_b32 m0, s44
	s_nop 0
	global_load_lds_dwordx4 v[198:199], off
	s_barrier
	s_waitcnt lgkmcnt(0)
	s_setprio 1
	s_waitcnt lgkmcnt(0)
	v_mfma_f32_16x16x32_bf16 v[60:63], v[146:149], v[162:165], v[60:63]
	v_mfma_f32_16x16x32_bf16 v[56:59], v[154:157], v[162:165], v[56:59]
	v_mfma_f32_16x16x32_bf16 v[52:55], v[146:149], v[170:173], v[52:55]
	v_mfma_f32_16x16x32_bf16 v[44:47], v[154:157], v[170:173], v[44:47]
	v_mfma_f32_16x16x32_bf16 v[36:39], v[146:149], v[178:181], v[36:39]
	v_mfma_f32_16x16x32_bf16 v[28:31], v[154:157], v[178:181], v[28:31]
	v_mfma_f32_16x16x32_bf16 v[20:23], v[146:149], v[186:189], v[20:23]
	v_mfma_f32_16x16x32_bf16 v[12:15], v[154:157], v[186:189], v[12:15]
	v_mfma_f32_16x16x32_bf16 v[60:63], v[150:153], v[166:169], v[60:63]
	v_mfma_f32_16x16x32_bf16 v[56:59], v[158:161], v[166:169], v[56:59]
	v_mfma_f32_16x16x32_bf16 v[52:55], v[150:153], v[174:177], v[52:55]
	v_mfma_f32_16x16x32_bf16 v[44:47], v[158:161], v[174:177], v[44:47]
	v_mfma_f32_16x16x32_bf16 v[36:39], v[150:153], v[182:185], v[36:39]
	v_mfma_f32_16x16x32_bf16 v[28:31], v[158:161], v[182:185], v[28:31]
	v_mfma_f32_16x16x32_bf16 v[20:23], v[150:153], v[190:193], v[20:23]
	v_mfma_f32_16x16x32_bf16 v[12:15], v[158:161], v[190:193], v[12:15]
	s_setprio 0
	s_barrier
	s_add_u32 s24, s24, 0x40080
	s_addc_u32 s25, s25, 0
	s_add_i32 s26, s26, s34
	v_lshl_add_u64 v[146:147], s[24:25], 0, v[130:131]
	s_mov_b32 m0, s26
	s_nop 0
	global_load_lds_dwordx4 v[146:147], off
	v_lshl_add_u64 v[146:147], s[24:25], 0, v[134:135]
	s_add_i32 m0, s26, 0x2000
	s_nop 0
	global_load_lds_dwordx4 v[146:147], off
	s_waitcnt vmcnt(6)
	s_barrier
	s_setprio 1
	v_mfma_f32_16x16x32_bf16 v[48:51], v[194:197], v[162:165], v[48:51]
	v_mfma_f32_16x16x32_bf16 v[40:43], v[206:209], v[162:165], v[40:43]
	v_mfma_f32_16x16x32_bf16 v[32:35], v[194:197], v[170:173], v[32:35]
	v_mfma_f32_16x16x32_bf16 v[24:27], v[206:209], v[170:173], v[24:27]
	v_mfma_f32_16x16x32_bf16 v[16:19], v[194:197], v[178:181], v[16:19]
	v_mfma_f32_16x16x32_bf16 v[8:11], v[206:209], v[178:181], v[8:11]
	v_mfma_f32_16x16x32_bf16 v[4:7], v[194:197], v[186:189], v[4:7]
	v_mfma_f32_16x16x32_bf16 v[0:3], v[206:209], v[186:189], v[0:3]
	v_mfma_f32_16x16x32_bf16 v[48:51], v[202:205], v[166:169], v[48:51]
	v_mfma_f32_16x16x32_bf16 v[40:43], v[210:213], v[166:169], v[40:43]
	v_mfma_f32_16x16x32_bf16 v[32:35], v[202:205], v[174:177], v[32:35]
	v_mfma_f32_16x16x32_bf16 v[24:27], v[210:213], v[174:177], v[24:27]
	v_mfma_f32_16x16x32_bf16 v[16:19], v[202:205], v[182:185], v[16:19]
	v_mfma_f32_16x16x32_bf16 v[8:11], v[210:213], v[182:185], v[8:11]
	v_mfma_f32_16x16x32_bf16 v[4:7], v[202:205], v[190:193], v[4:7]
	v_mfma_f32_16x16x32_bf16 v[0:3], v[210:213], v[190:193], v[0:3]
	s_setprio 0
	s_add_i32 s58, s58, 2
	s_add_u32 s22, s22, 0x100
	s_addc_u32 s23, s23, 0
	s_add_u32 s56, s56, 0x100
	s_addc_u32 s57, s57, 0
	s_cmp_gt_u32 s58, 13
	s_barrier

; #define PG8_STAGE(bufoff, gbase, voff) do { _Pragma("unroll") for (int _i = 0; _i < 2; ++_i) \
;         __builtin_amdgcn_global_load_lds((const unsigned*)((const char*)(gbase) + (voff)[_i]), (LAS unsigned*)(lds + (bufoff) + ldsw + _i * 8192), 16, 0, 0); } while (0)
; #define PG8_LDA(dst, b, h) do { _Pragma("unroll") for (int m = 0; m < 4; ++m) _Pragma("unroll") for (int k = 0; k < 2; ++k) dst[m][k] = *(const LAS bf16x8*)(lds + PG8_SA(b, h) + aoff + m * 2048 + k * 1024); } while (0)
; #define PG8_LDB(dst, b, h) do { _Pragma("unroll") for (int n = 0; n < 2; ++n) _Pragma("unroll") for (int k = 0; k < 2; ++k) dst[n][k] = *(const LAS bf16x8*)(lds + PG8_SB(b, h) + boff + n * 2048 + k * 1024); } while (0)
; #define PG8_MMA(ai, bj, At, Bt) do { __builtin_amdgcn_s_setprio(1); _Pragma("unroll") for (int m = 0; m < 4; ++m) _Pragma("unroll") for (int n = 0; n < 2; ++n) _Pragma("unroll") for (int k = 0; k < 2; ++k) \
;         acc[ai][bj][m][n] = __builtin_amdgcn_mfma_f32_16x16x32_bf16(Bt[n][k], At[m][k], acc[ai][bj][m][n], 0, 0, 0); __builtin_amdgcn_s_setprio(0); } while (0)
; #define PG8_WAIT_L(n) asm volatile("s_waitcnt lgkmcnt(" #n ")" ::: "memory")
; #define PG8_BAR __builtin_amdgcn_s_barrier()
; #define PG8_SCHED __builtin_amdgcn_sched_barrier(0)
; template <class Epi, class Sched>
; __device__ __forceinline__ void gemm_phase(LAS unsigned char* lds, const Gemm g, const Sched& S, const Epi& E) {
;     ...
;             PG8_LDB(B0, 0, 0); PG8_SCHED; PG8_LDA(At, 0, 0); PG8_STAGE(PG8_SA(1, 1), a1 + hstep, voffA);
;             PG8_WAIT_L(8); PG8_BAR; PG8_WAIT_L(0); PG8_MMA(0, 0, At, B0); PG8_BAR; PG8_SCHED;
;             PG8_LDB(B1, 0, 1); PG8_STAGE(PG8_SB(0, 0), b2, voffB);
;             PG8_BAR; PG8_WAIT_L(0); PG8_MMA(0, 1, At, B1); PG8_BAR;
;             PG8_LDA(At, 0, 1); PG8_STAGE(PG8_SA(0, 0), a2, voffA);
;             PG8_BAR; PG8_WAIT_L(0); PG8_MMA(1, 0, At, B0); PG8_BAR; PG8_SCHED;
;     ...
; #pragma unroll
;         for (int a = 0; a < 2; ++a)
; #pragma unroll
;             for (int b = 0; b < 2; ++b)
; #pragma unroll
;                 for (int m = 0; m < 4; ++m)
; #pragma unroll
;                     for (int n = 0; n < 2; ++n) acc[a][b][m][n] = (f32x4){0.f, 0.f, 0.f, 0.f};
.LBB0_825:
	s_ashr_i32 s7, s6, 31
	v_cmp_lt_i64_e32 vcc, s[8:9], v[156:157]
	s_lshl_b64 s[8:9], s[6:7], 20
	s_add_u32 s8, s22, s8
	s_addc_u32 s9, s23, s9
	s_and_b64 s[10:11], vcc, exec
	s_cselect_b32 s7, s9, s15
	s_cselect_b32 s39, s8, s14
	s_ashr_i32 s5, s4, 31
	s_lshl_b64 s[10:11], s[4:5], 20
	s_add_u32 s10, s50, s10
	s_addc_u32 s11, s51, s11
	s_and_b64 s[18:19], vcc, exec
	s_cselect_b32 s5, s11, s17
	s_cselect_b32 s40, s10, s16
	s_add_u32 s14, s14, 0x80080
	s_addc_u32 s15, s15, 0
	s_add_u32 s41, s16, 0x100
	s_addc_u32 s42, s17, 0
	s_mov_b32 s43, -2
	ds_read_b128 v[128:131], v168
	ds_read_b128 v[132:135], v168 offset:1024
	ds_read_b128 v[136:139], v168 offset:2048
	ds_read_b128 v[140:143], v168 offset:3072
	s_add_u32 s16, s14, 0xfff80080
	s_addc_u32 s17, s15, -1
	s_cmp_eq_u32 s43, 28
	s_cselect_b32 s19, s7, s17
	s_cselect_b32 s18, s39, s16
	s_cselect_b32 s17, s5, s42
	s_cselect_b32 s16, s40, s41
	v_lshl_add_u64 v[202:203], s[14:15], 0, v[152:153]
	s_add_i32 m0, s13, 0xc000
	ds_read_b128 v[162:165], v169
	ds_read_b128 v[172:175], v169 offset:1024
	ds_read_b128 v[176:179], v169 offset:2048
	ds_read_b128 v[180:183], v169 offset:3072
	ds_read_b128 v[184:187], v169 offset:4096
	ds_read_b128 v[188:191], v169 offset:5120
	ds_read_b128 v[192:195], v169 offset:6144
	ds_read_b128 v[196:199], v169 offset:7168
	global_load_lds_dwordx4 v[202:203], off
	v_lshl_add_u64 v[202:203], s[14:15], 0, v[154:155]
	s_add_i32 m0, s13, 0xe000
	s_nop 0
	global_load_lds_dwordx4 v[202:203], off
	s_waitcnt lgkmcnt(8)
	s_barrier
	s_waitcnt lgkmcnt(0)
	s_setprio 1
	s_waitcnt lgkmcnt(0)
	v_mfma_f32_16x16x32_bf16 v[124:127], v[128:131], v[162:165], 0
	v_mfma_f32_16x16x32_bf16 v[120:123], v[136:139], v[162:165], 0
	v_mfma_f32_16x16x32_bf16 v[116:119], v[128:131], v[176:179], 0
	v_mfma_f32_16x16x32_bf16 v[112:115], v[136:139], v[176:179], 0
	v_mfma_f32_16x16x32_bf16 v[108:111], v[128:131], v[184:187], 0
	v_mfma_f32_16x16x32_bf16 v[100:103], v[136:139], v[184:187], 0
	v_mfma_f32_16x16x32_bf16 v[76:79], v[128:131], v[192:195], 0
	v_mfma_f32_16x16x32_bf16 v[72:75], v[136:139], v[192:195], 0
	v_mfma_f32_16x16x32_bf16 v[124:127], v[132:135], v[172:175], v[124:127]
	v_mfma_f32_16x16x32_bf16 v[120:123], v[140:143], v[172:175], v[120:123]
	v_mfma_f32_16x16x32_bf16 v[116:119], v[132:135], v[180:183], v[116:119]
	v_mfma_f32_16x16x32_bf16 v[112:115], v[140:143], v[180:183], v[112:115]
	v_mfma_f32_16x16x32_bf16 v[108:111], v[132:135], v[188:191], v[108:111]
	v_mfma_f32_16x16x32_bf16 v[100:103], v[140:143], v[188:191], v[100:103]
	v_mfma_f32_16x16x32_bf16 v[76:79], v[132:135], v[196:199], v[76:79]
	v_mfma_f32_16x16x32_bf16 v[72:75], v[140:143], v[196:199], v[72:75]
	s_setprio 0
	s_barrier
	s_add_i32 s44, s35, s24
	v_lshl_add_u64 v[218:219], s[16:17], 0, v[146:147]
	s_mov_b32 m0, s44
	ds_read_b128 v[202:205], v170
	ds_read_b128 v[206:209], v170 offset:1024
	ds_read_b128 v[210:213], v170 offset:2048
	ds_read_b128 v[214:217], v170 offset:3072
	global_load_lds_dwordx4 v[218:219], off
	v_lshl_add_u64 v[220:221], s[16:17], 0, v[150:151]
	s_add_i32 m0, s44, 0x2000
	s_nop 0
	global_load_lds_dwordx4 v[220:221], off
	s_barrier
	s_waitcnt lgkmcnt(0)
	s_setprio 1
	s_waitcnt lgkmcnt(0)
	v_mfma_f32_16x16x32_bf16 v[104:107], v[202:205], v[162:165], 0
	v_mfma_f32_16x16x32_bf16 v[96:99], v[210:213], v[162:165], 0
	v_mfma_f32_16x16x32_bf16 v[92:95], v[202:205], v[176:179], 0
	v_mfma_f32_16x16x32_bf16 v[88:91], v[210:213], v[176:179], 0
	v_mfma_f32_16x16x32_bf16 v[84:87], v[202:205], v[184:187], 0
	v_mfma_f32_16x16x32_bf16 v[80:83], v[210:213], v[184:187], 0
	v_mfma_f32_16x16x32_bf16 v[68:71], v[202:205], v[192:195], 0
	v_mfma_f32_16x16x32_bf16 v[64:67], v[210:213], v[192:195], 0
	v_mfma_f32_16x16x32_bf16 v[104:107], v[206:209], v[172:175], v[104:107]
	v_mfma_f32_16x16x32_bf16 v[96:99], v[214:217], v[172:175], v[96:99]
	v_mfma_f32_16x16x32_bf16 v[92:95], v[206:209], v[180:183], v[92:95]
	v_mfma_f32_16x16x32_bf16 v[88:91], v[214:217], v[180:183], v[88:91]
	v_mfma_f32_16x16x32_bf16 v[84:87], v[206:209], v[188:191], v[84:87]
	v_mfma_f32_16x16x32_bf16 v[80:83], v[214:217], v[188:191], v[80:83]
	v_mfma_f32_16x16x32_bf16 v[68:71], v[206:209], v[196:199], v[68:71]
	v_mfma_f32_16x16x32_bf16 v[64:67], v[214:217], v[196:199], v[64:67]
	s_setprio 0
	s_mov_b32 m0, s13
	v_lshl_add_u64 v[222:223], s[18:19], 0, v[144:145]
	s_barrier
	ds_read_b128 v[162:165], v169 offset:16384
	ds_read_b128 v[172:175], v169 offset:17408
	ds_read_b128 v[176:179], v169 offset:18432
	ds_read_b128 v[180:183], v169 offset:19456
	ds_read_b128 v[184:187], v169 offset:20480
	ds_read_b128 v[188:191], v169 offset:21504
	ds_read_b128 v[192:195], v169 offset:22528
	ds_read_b128 v[196:199], v169 offset:23552
	global_load_lds_dwordx4 v[222:223], off
	v_lshl_add_u64 v[224:225], s[18:19], 0, v[148:149]
	s_mov_b32 m0, s25
	s_nop 0
	global_load_lds_dwordx4 v[224:225], off
	s_barrier
	s_waitcnt lgkmcnt(0)
	s_setprio 1
	s_waitcnt lgkmcnt(0)
	v_mfma_f32_16x16x32_bf16 v[60:63], v[128:131], v[162:165], 0
	v_mfma_f32_16x16x32_bf16 v[56:59], v[136:139], v[162:165], 0
	v_mfma_f32_16x16x32_bf16 v[48:51], v[128:131], v[176:179], 0
	v_mfma_f32_16x16x32_bf16 v[40:43], v[136:139], v[176:179], 0
	v_mfma_f32_16x16x32_bf16 v[32:35], v[128:131], v[184:187], 0
	v_mfma_f32_16x16x32_bf16 v[24:27], v[136:139], v[184:187], 0
	v_mfma_f32_16x16x32_bf16 v[16:19], v[128:131], v[192:195], 0
	v_mfma_f32_16x16x32_bf16 v[8:11], v[136:139], v[192:195], 0
	v_mfma_f32_16x16x32_bf16 v[60:63], v[132:135], v[172:175], v[60:63]
	v_mfma_f32_16x16x32_bf16 v[56:59], v[140:143], v[172:175], v[56:59]
	v_mfma_f32_16x16x32_bf16 v[48:51], v[132:135], v[180:183], v[48:51]
	v_mfma_f32_16x16x32_bf16 v[40:43], v[140:143], v[180:183], v[40:43]
	v_mfma_f32_16x16x32_bf16 v[32:35], v[132:135], v[188:191], v[32:35]
	v_mfma_f32_16x16x32_bf16 v[24:27], v[140:143], v[188:191], v[24:27]
	v_mfma_f32_16x16x32_bf16 v[16:19], v[132:135], v[196:199], v[16:19]
	v_mfma_f32_16x16x32_bf16 v[8:11], v[140:143], v[196:199], v[8:11]
	s_setprio 0
	s_barrier
; #define PG8_STAGE(bufoff, gbase, voff) do { _Pragma("unroll") for (int _i = 0; _i < 2; ++_i) \
;         __builtin_amdgcn_global_load_lds((const unsigned*)((const char*)(gbase) + (voff)[_i]), (LAS unsigned*)(lds + (bufoff) + ldsw + _i * 8192), 16, 0, 0); } while (0)
; #define PG8_LDA(dst, b, h) do { _Pragma("unroll") for (int m = 0; m < 4; ++m) _Pragma("unroll") for (int k = 0; k < 2; ++k) dst[m][k] = *(const LAS bf16x8*)(lds + PG8_SA(b, h) + aoff + m * 2048 + k * 1024); } while (0)
; #define PG8_LDB(dst, b, h) do { _Pragma("unroll") for (int n = 0; n < 2; ++n) _Pragma("unroll") for (int k = 0; k < 2; ++k) dst[n][k] = *(const LAS bf16x8*)(lds + PG8_SB(b, h) + boff + n * 2048 + k * 1024); } while (0)
; #define PG8_MMA(ai, bj, At, Bt) do { __builtin_amdgcn_s_setprio(1); _Pragma("unroll") for (int m = 0; m < 4; ++m) _Pragma("unroll") for (int n = 0; n < 2; ++n) _Pragma("unroll") for (int k = 0; k < 2; ++k) \
;         acc[ai][bj][m][n] = __builtin_amdgcn_mfma_f32_16x16x32_bf16(Bt[n][k], At[m][k], acc[ai][bj][m][n], 0, 0, 0); __builtin_amdgcn_s_setprio(0); } while (0)
; #define PG8_WAIT_V(n) asm volatile("s_waitcnt vmcnt(" #n ")" ::: "memory")
; #define PG8_WAIT_L(n) asm volatile("s_waitcnt lgkmcnt(" #n ")" ::: "memory")
; #define PG8_BAR __builtin_amdgcn_s_barrier()
; #define PG8_SCHED __builtin_amdgcn_sched_barrier(0)
; template <class Epi, class Sched>
; __device__ __forceinline__ void gemm_phase(LAS unsigned char* lds, const Gemm g, const Sched& S, const Epi& E) {
;     ...
;             PG8_STAGE(PG8_SB(0, 1), b2 + hstep, voffB);
;             PG8_WAIT_V(6); PG8_BAR; PG8_MMA(1, 1, At, B1); PG8_BAR;
;             PG8_LDB(B0, 1, 0); PG8_SCHED; PG8_LDA(At, 1, 0); PG8_STAGE(PG8_SA(0, 1), a2 + hstep, voffA);
;             PG8_WAIT_L(8); PG8_BAR; PG8_WAIT_L(0); PG8_MMA(0, 0, At, B0); PG8_BAR; PG8_SCHED;
;             PG8_LDB(B1, 1, 1); PG8_STAGE(PG8_SB(1, 0), b3, voffB);
	s_add_u32 s44, s16, 0x80000
	s_addc_u32 s45, s17, 0
	s_add_i32 s46, s36, s24
	v_lshl_add_u64 v[128:129], s[44:45], 0, v[146:147]
	s_mov_b32 m0, s46
	s_nop 0
	global_load_lds_dwordx4 v[128:129], off
	v_lshl_add_u64 v[128:129], s[44:45], 0, v[150:151]
	s_add_i32 m0, s46, 0x2000
	s_nop 0
	global_load_lds_dwordx4 v[128:129], off
	s_waitcnt vmcnt(6)
	s_barrier
	s_setprio 1
	v_mfma_f32_16x16x32_bf16 v[52:55], v[202:205], v[162:165], 0
	v_mfma_f32_16x16x32_bf16 v[44:47], v[210:213], v[162:165], 0
	v_mfma_f32_16x16x32_bf16 v[36:39], v[202:205], v[176:179], 0
	v_mfma_f32_16x16x32_bf16 v[28:31], v[210:213], v[176:179], 0
	v_mfma_f32_16x16x32_bf16 v[20:23], v[202:205], v[184:187], 0
	v_mfma_f32_16x16x32_bf16 v[12:15], v[210:213], v[184:187], 0
	v_mfma_f32_16x16x32_bf16 v[4:7], v[202:205], v[192:195], 0
	v_mfma_f32_16x16x32_bf16 v[0:3], v[210:213], v[192:195], 0
	v_mfma_f32_16x16x32_bf16 v[52:55], v[206:209], v[172:175], v[52:55]
	v_mfma_f32_16x16x32_bf16 v[44:47], v[214:217], v[172:175], v[44:47]
	v_mfma_f32_16x16x32_bf16 v[36:39], v[206:209], v[180:183], v[36:39]
	v_mfma_f32_16x16x32_bf16 v[28:31], v[214:217], v[180:183], v[28:31]
	v_mfma_f32_16x16x32_bf16 v[20:23], v[206:209], v[188:191], v[20:23]
	v_mfma_f32_16x16x32_bf16 v[12:15], v[214:217], v[188:191], v[12:15]
	v_mfma_f32_16x16x32_bf16 v[4:7], v[206:209], v[196:199], v[4:7]
	v_mfma_f32_16x16x32_bf16 v[0:3], v[214:217], v[196:199], v[0:3]
	s_setprio 0
	s_add_i32 s44, 0, 0x18000
	v_add_u32_e32 v140, s44, v167
	s_barrier
	ds_read_b128 v[128:131], v140
	ds_read_b128 v[132:135], v140 offset:1024
	ds_read_b128 v[136:139], v140 offset:2048
	ds_read_b128 v[140:143], v140 offset:3072
	s_add_u32 s18, s18, 0x80000
	s_addc_u32 s19, s19, 0
	s_mov_b32 m0, s26
	v_lshl_add_u64 v[202:203], s[18:19], 0, v[144:145]
	ds_read_b128 v[162:165], v169 offset:32768
	ds_read_b128 v[172:175], v169 offset:33792
	ds_read_b128 v[176:179], v169 offset:34816
	ds_read_b128 v[180:183], v169 offset:35840
	ds_read_b128 v[184:187], v169 offset:36864
	ds_read_b128 v[188:191], v169 offset:37888
	ds_read_b128 v[192:195], v169 offset:38912
	ds_read_b128 v[196:199], v169 offset:39936
	global_load_lds_dwordx4 v[202:203], off
	v_lshl_add_u64 v[202:203], s[18:19], 0, v[148:149]
	s_mov_b32 m0, s27
	s_nop 0
	global_load_lds_dwordx4 v[202:203], off
	s_waitcnt lgkmcnt(8)
	s_barrier
	s_waitcnt lgkmcnt(0)
	s_setprio 1
	s_waitcnt lgkmcnt(0)
	v_mfma_f32_16x16x32_bf16 v[124:127], v[128:131], v[162:165], v[124:127]
	v_mfma_f32_16x16x32_bf16 v[120:123], v[136:139], v[162:165], v[120:123]
	v_mfma_f32_16x16x32_bf16 v[116:119], v[128:131], v[176:179], v[116:119]
	v_mfma_f32_16x16x32_bf16 v[112:115], v[136:139], v[176:179], v[112:115]
	v_mfma_f32_16x16x32_bf16 v[108:111], v[128:131], v[184:187], v[108:111]
	v_mfma_f32_16x16x32_bf16 v[100:103], v[136:139], v[184:187], v[100:103]
	v_mfma_f32_16x16x32_bf16 v[76:79], v[128:131], v[192:195], v[76:79]
	v_mfma_f32_16x16x32_bf16 v[72:75], v[136:139], v[192:195], v[72:75]
	v_mfma_f32_16x16x32_bf16 v[124:127], v[132:135], v[172:175], v[124:127]
	v_mfma_f32_16x16x32_bf16 v[120:123], v[140:143], v[172:175], v[120:123]
	v_mfma_f32_16x16x32_bf16 v[116:119], v[132:135], v[180:183], v[116:119]
	v_mfma_f32_16x16x32_bf16 v[112:115], v[140:143], v[180:183], v[112:115]
	v_mfma_f32_16x16x32_bf16 v[108:111], v[132:135], v[188:191], v[108:111]
	v_mfma_f32_16x16x32_bf16 v[100:103], v[140:143], v[188:191], v[100:103]
	v_mfma_f32_16x16x32_bf16 v[76:79], v[132:135], v[196:199], v[76:79]
	v_mfma_f32_16x16x32_bf16 v[72:75], v[140:143], v[196:199], v[72:75]
	s_setprio 0
	s_barrier
	s_add_i32 s18, 0, 0x1c000
	s_add_i32 s19, s44, s24
	v_add_u32_e32 v160, s18, v167
	v_lshl_add_u64 v[218:219], v[218:219], 0, s[0:1]
	s_mov_b32 m0, s19
	ds_read_b128 v[202:205], v160
	ds_read_b128 v[206:209], v160 offset:1024
	ds_read_b128 v[210:213], v160 offset:2048
	ds_read_b128 v[214:217], v160 offset:3072
	global_load_lds_dwordx4 v[218:219], off
	v_lshl_add_u64 v[218:219], v[220:221], 0, s[0:1]
	s_add_i32 m0, s19, 0x2000
	s_nop 0
	global_load_lds_dwordx4 v[218:219], off
	s_barrier
; #define PG8_STAGE(bufoff, gbase, voff) do { _Pragma("unroll") for (int _i = 0; _i < 2; ++_i) \
;         __builtin_amdgcn_global_load_lds((const unsigned*)((const char*)(gbase) + (voff)[_i]), (LAS unsigned*)(lds + (bufoff) + ldsw + _i * 8192), 16, 0, 0); } while (0)
; #define PG8_LDA(dst, b, h) do { _Pragma("unroll") for (int m = 0; m < 4; ++m) _Pragma("unroll") for (int k = 0; k < 2; ++k) dst[m][k] = *(const LAS bf16x8*)(lds + PG8_SA(b, h) + aoff + m * 2048 + k * 1024); } while (0)
; #define PG8_MMA(ai, bj, At, Bt) do { __builtin_amdgcn_s_setprio(1); _Pragma("unroll") for (int m = 0; m < 4; ++m) _Pragma("unroll") for (int n = 0; n < 2; ++n) _Pragma("unroll") for (int k = 0; k < 2; ++k) \
;         acc[ai][bj][m][n] = __builtin_amdgcn_mfma_f32_16x16x32_bf16(Bt[n][k], At[m][k], acc[ai][bj][m][n], 0, 0, 0); __builtin_amdgcn_s_setprio(0); } while (0)
; #define PG8_WAIT_V(n) asm volatile("s_waitcnt vmcnt(" #n ")" ::: "memory")
; #define PG8_WAIT_L(n) asm volatile("s_waitcnt lgkmcnt(" #n ")" ::: "memory")
; #define PG8_BAR __builtin_amdgcn_s_barrier()
; #define PG8_SCHED __builtin_amdgcn_sched_barrier(0)
; template <class Epi, class Sched>
; __device__ __forceinline__ void gemm_phase(LAS unsigned char* lds, const Gemm g, const Sched& S, const Epi& E) {
;     ...
;             PG8_BAR; PG8_WAIT_L(0); PG8_MMA(0, 1, At, B1); PG8_BAR;
;             PG8_LDA(At, 1, 1); PG8_STAGE(PG8_SA(1, 0), a3, voffA);
;             PG8_BAR; PG8_WAIT_L(0); PG8_MMA(1, 0, At, B0); PG8_BAR; PG8_SCHED;
;             PG8_STAGE(PG8_SB(1, 1), b3 + hstep, voffB);
;             PG8_WAIT_V(6); PG8_BAR; PG8_MMA(1, 1, At, B1); PG8_BAR;
	s_waitcnt lgkmcnt(0)
	s_setprio 1
	s_waitcnt lgkmcnt(0)
	v_mfma_f32_16x16x32_bf16 v[104:107], v[202:205], v[162:165], v[104:107]
	v_mfma_f32_16x16x32_bf16 v[96:99], v[210:213], v[162:165], v[96:99]
	v_mfma_f32_16x16x32_bf16 v[92:95], v[202:205], v[176:179], v[92:95]
	v_mfma_f32_16x16x32_bf16 v[88:91], v[210:213], v[176:179], v[88:91]
	v_mfma_f32_16x16x32_bf16 v[84:87], v[202:205], v[184:187], v[84:87]
	v_mfma_f32_16x16x32_bf16 v[80:83], v[210:213], v[184:187], v[80:83]
	v_mfma_f32_16x16x32_bf16 v[68:71], v[202:205], v[192:195], v[68:71]
	v_mfma_f32_16x16x32_bf16 v[64:67], v[210:213], v[192:195], v[64:67]
	v_mfma_f32_16x16x32_bf16 v[104:107], v[206:209], v[172:175], v[104:107]
	v_mfma_f32_16x16x32_bf16 v[96:99], v[214:217], v[172:175], v[96:99]
	v_mfma_f32_16x16x32_bf16 v[92:95], v[206:209], v[180:183], v[92:95]
	v_mfma_f32_16x16x32_bf16 v[88:91], v[214:217], v[180:183], v[88:91]
	v_mfma_f32_16x16x32_bf16 v[84:87], v[206:209], v[188:191], v[84:87]
	v_mfma_f32_16x16x32_bf16 v[80:83], v[214:217], v[188:191], v[80:83]
	v_mfma_f32_16x16x32_bf16 v[68:71], v[206:209], v[196:199], v[68:71]
	v_mfma_f32_16x16x32_bf16 v[64:67], v[214:217], v[196:199], v[64:67]
	s_setprio 0
	s_mov_b32 m0, s31
	v_lshl_add_u64 v[218:219], v[222:223], 0, s[0:1]
	s_barrier
	ds_read_b128 v[162:165], v169 offset:49152
	ds_read_b128 v[172:175], v169 offset:50176
	ds_read_b128 v[176:179], v169 offset:51200
	ds_read_b128 v[180:183], v169 offset:52224
	ds_read_b128 v[184:187], v169 offset:53248
	ds_read_b128 v[188:191], v169 offset:54272
	ds_read_b128 v[192:195], v169 offset:55296
	ds_read_b128 v[196:199], v169 offset:56320
	global_load_lds_dwordx4 v[218:219], off
	v_lshl_add_u64 v[218:219], v[224:225], 0, s[0:1]
	s_mov_b32 m0, s33
	s_nop 0
	global_load_lds_dwordx4 v[218:219], off
	s_barrier
	s_waitcnt lgkmcnt(0)
	s_setprio 1
	s_waitcnt lgkmcnt(0)
	v_mfma_f32_16x16x32_bf16 v[60:63], v[128:131], v[162:165], v[60:63]
	v_mfma_f32_16x16x32_bf16 v[56:59], v[136:139], v[162:165], v[56:59]
	v_mfma_f32_16x16x32_bf16 v[48:51], v[128:131], v[176:179], v[48:51]
	v_mfma_f32_16x16x32_bf16 v[40:43], v[136:139], v[176:179], v[40:43]
	v_mfma_f32_16x16x32_bf16 v[32:35], v[128:131], v[184:187], v[32:35]
	v_mfma_f32_16x16x32_bf16 v[24:27], v[136:139], v[184:187], v[24:27]
	v_mfma_f32_16x16x32_bf16 v[16:19], v[128:131], v[192:195], v[16:19]
	v_mfma_f32_16x16x32_bf16 v[8:11], v[136:139], v[192:195], v[8:11]
	v_mfma_f32_16x16x32_bf16 v[60:63], v[132:135], v[172:175], v[60:63]
	v_mfma_f32_16x16x32_bf16 v[56:59], v[140:143], v[172:175], v[56:59]
	v_mfma_f32_16x16x32_bf16 v[48:51], v[132:135], v[180:183], v[48:51]
	v_mfma_f32_16x16x32_bf16 v[40:43], v[140:143], v[180:183], v[40:43]
	v_mfma_f32_16x16x32_bf16 v[32:35], v[132:135], v[188:191], v[32:35]
	v_mfma_f32_16x16x32_bf16 v[24:27], v[140:143], v[188:191], v[24:27]
	v_mfma_f32_16x16x32_bf16 v[16:19], v[132:135], v[196:199], v[16:19]
	v_mfma_f32_16x16x32_bf16 v[8:11], v[140:143], v[196:199], v[8:11]
	s_setprio 0
	s_barrier
	s_add_u32 s16, s16, 0x80080
	s_addc_u32 s17, s17, 0
	s_add_i32 s18, s18, s24
	v_lshl_add_u64 v[128:129], s[16:17], 0, v[146:147]
	s_mov_b32 m0, s18
	s_nop 0
	global_load_lds_dwordx4 v[128:129], off
	v_lshl_add_u64 v[128:129], s[16:17], 0, v[150:151]
	s_add_i32 m0, s18, 0x2000
	s_nop 0
	global_load_lds_dwordx4 v[128:129], off
	s_waitcnt vmcnt(6)
	s_barrier
	s_setprio 1
	v_mfma_f32_16x16x32_bf16 v[52:55], v[202:205], v[162:165], v[52:55]
	v_mfma_f32_16x16x32_bf16 v[44:47], v[210:213], v[162:165], v[44:47]
	v_mfma_f32_16x16x32_bf16 v[36:39], v[202:205], v[176:179], v[36:39]
	v_mfma_f32_16x16x32_bf16 v[28:31], v[210:213], v[176:179], v[28:31]
	v_mfma_f32_16x16x32_bf16 v[20:23], v[202:205], v[184:187], v[20:23]
	v_mfma_f32_16x16x32_bf16 v[12:15], v[210:213], v[184:187], v[12:15]
	v_mfma_f32_16x16x32_bf16 v[4:7], v[202:205], v[192:195], v[4:7]
	v_mfma_f32_16x16x32_bf16 v[0:3], v[210:213], v[192:195], v[0:3]
	v_mfma_f32_16x16x32_bf16 v[52:55], v[206:209], v[172:175], v[52:55]
	v_mfma_f32_16x16x32_bf16 v[44:47], v[214:217], v[172:175], v[44:47]
	v_mfma_f32_16x16x32_bf16 v[36:39], v[206:209], v[180:183], v[36:39]
	v_mfma_f32_16x16x32_bf16 v[28:31], v[214:217], v[180:183], v[28:31]
	v_mfma_f32_16x16x32_bf16 v[20:23], v[206:209], v[188:191], v[20:23]
	v_mfma_f32_16x16x32_bf16 v[12:15], v[214:217], v[188:191], v[12:15]
	v_mfma_f32_16x16x32_bf16 v[4:7], v[206:209], v[196:199], v[4:7]
	v_mfma_f32_16x16x32_bf16 v[0:3], v[214:217], v[196:199], v[0:3]
	s_setprio 0
	s_add_i32 s43, s43, 2
	s_add_u32 s14, s14, 0x100
	s_addc_u32 s15, s15, 0
	s_add_u32 s41, s41, 0x100
	s_addc_u32 s42, s42, 0
	s_cmp_gt_u32 s43, 29
	s_barrier

; #define PG8_STAGE(bufoff, gbase, voff) do { _Pragma("unroll") for (int _i = 0; _i < 2; ++_i) \
;         __builtin_amdgcn_global_load_lds((const unsigned*)((const char*)(gbase) + (voff)[_i]), (LAS unsigned*)(lds + (bufoff) + ldsw + _i * 8192), 16, 0, 0); } while (0)
; #define PG8_LDA(dst, b, h) do { _Pragma("unroll") for (int m = 0; m < 4; ++m) _Pragma("unroll") for (int k = 0; k < 2; ++k) dst[m][k] = *(const LAS bf16x8*)(lds + PG8_SA(b, h) + aoff + m * 2048 + k * 1024); } while (0)
; #define PG8_LDB(dst, b, h) do { _Pragma("unroll") for (int n = 0; n < 2; ++n) _Pragma("unroll") for (int k = 0; k < 2; ++k) dst[n][k] = *(const LAS bf16x8*)(lds + PG8_SB(b, h) + boff + n * 2048 + k * 1024); } while (0)
; #define PG8_MMA(ai, bj, At, Bt) do { __builtin_amdgcn_s_setprio(1); _Pragma("unroll") for (int m = 0; m < 4; ++m) _Pragma("unroll") for (int n = 0; n < 2; ++n) _Pragma("unroll") for (int k = 0; k < 2; ++k) \
;         acc[ai][bj][m][n] = __builtin_amdgcn_mfma_f32_16x16x32_bf16(Bt[n][k], At[m][k], acc[ai][bj][m][n], 0, 0, 0); __builtin_amdgcn_s_setprio(0); } while (0)
; #define PG8_WAIT_L(n) asm volatile("s_waitcnt lgkmcnt(" #n ")" ::: "memory")
; #define PG8_BAR __builtin_amdgcn_s_barrier()
; #define PG8_SCHED __builtin_amdgcn_sched_barrier(0)
; template <class Epi, class Sched>
; __device__ __forceinline__ void gemm_phase(LAS unsigned char* lds, const Gemm g, const Sched& S, const Epi& E) {
;     ...
;             PG8_LDB(B0, 0, 0); PG8_SCHED; PG8_LDA(At, 0, 0); PG8_STAGE(PG8_SA(1, 1), a1 + hstep, voffA);
;             PG8_WAIT_L(8); PG8_BAR; PG8_WAIT_L(0); PG8_MMA(0, 0, At, B0); PG8_BAR; PG8_SCHED;
;             PG8_LDB(B1, 0, 1); PG8_STAGE(PG8_SB(0, 0), b2, voffB);
;             PG8_BAR; PG8_WAIT_L(0); PG8_MMA(0, 1, At, B1); PG8_BAR;
;             PG8_LDA(At, 0, 1); PG8_STAGE(PG8_SA(0, 0), a2, voffA);
;             PG8_BAR; PG8_WAIT_L(0); PG8_MMA(1, 0, At, B0); PG8_BAR; PG8_SCHED;
;     ...
; #pragma unroll
;         for (int a = 0; a < 2; ++a)
; #pragma unroll
;             for (int b = 0; b < 2; ++b)
; #pragma unroll
;                 for (int m = 0; m < 4; ++m)
; #pragma unroll
;                     for (int n = 0; n < 2; ++n) acc[a][b][m][n] = (f32x4){0.f, 0.f, 0.f, 0.f};
.LBB0_901:
	s_add_u32 s56, s26, 0x100
	s_addc_u32 s57, s27, 0
	s_mov_b32 s58, -2
	s_waitcnt vmcnt(0)
	ds_read_b128 v[128:131], v237
	ds_read_b128 v[132:135], v237 offset:1024
	ds_read_b128 v[136:139], v237 offset:2048
	ds_read_b128 v[140:143], v237 offset:3072
	s_add_u32 s26, s24, 0x100
	s_addc_u32 s27, s25, 0
	s_cmp_eq_u32 s58, 20
	s_cselect_b32 s31, s5, s27
	s_cselect_b32 s30, s4, s26
	s_cselect_b32 s29, s7, s57
	s_cselect_b32 s28, s6, s56
	v_lshl_add_u64 v[176:177], s[24:25], 0, v[210:211]
	s_add_i32 m0, s38, 0xc000
	ds_read_b128 v[144:147], v238
	ds_read_b128 v[148:151], v238 offset:1024
	ds_read_b128 v[152:155], v238 offset:2048
	ds_read_b128 v[156:159], v238 offset:3072
	ds_read_b128 v[160:163], v238 offset:4096
	ds_read_b128 v[164:167], v238 offset:5120
	ds_read_b128 v[168:171], v238 offset:6144
	ds_read_b128 v[172:175], v238 offset:7168
	global_load_lds_dwordx4 v[176:177], off
	v_lshl_add_u64 v[176:177], s[24:25], 0, v[212:213]
	s_add_i32 m0, s38, 0xe000
	s_nop 0
	global_load_lds_dwordx4 v[176:177], off
	s_waitcnt lgkmcnt(8)
	s_barrier
	s_waitcnt lgkmcnt(0)
	s_setprio 1
	s_waitcnt lgkmcnt(0)
	v_mfma_f32_16x16x32_bf16 v[124:127], v[128:131], v[144:147], 0
	v_mfma_f32_16x16x32_bf16 v[120:123], v[136:139], v[144:147], 0
	v_mfma_f32_16x16x32_bf16 v[108:111], v[128:131], v[152:155], 0
	v_mfma_f32_16x16x32_bf16 v[104:107], v[136:139], v[152:155], 0
	v_mfma_f32_16x16x32_bf16 v[92:95], v[128:131], v[160:163], 0
	v_mfma_f32_16x16x32_bf16 v[88:91], v[136:139], v[160:163], 0
	v_mfma_f32_16x16x32_bf16 v[76:79], v[128:131], v[168:171], 0
	v_mfma_f32_16x16x32_bf16 v[72:75], v[136:139], v[168:171], 0
	v_mfma_f32_16x16x32_bf16 v[124:127], v[132:135], v[148:151], v[124:127]
	v_mfma_f32_16x16x32_bf16 v[120:123], v[140:143], v[148:151], v[120:123]
	v_mfma_f32_16x16x32_bf16 v[108:111], v[132:135], v[156:159], v[108:111]
	v_mfma_f32_16x16x32_bf16 v[104:107], v[140:143], v[156:159], v[104:107]
	v_mfma_f32_16x16x32_bf16 v[92:95], v[132:135], v[164:167], v[92:95]
	v_mfma_f32_16x16x32_bf16 v[88:91], v[140:143], v[164:167], v[88:91]
	v_mfma_f32_16x16x32_bf16 v[76:79], v[132:135], v[172:175], v[76:79]
	v_mfma_f32_16x16x32_bf16 v[72:75], v[140:143], v[172:175], v[72:75]
	s_setprio 0
	s_barrier
	s_add_i32 s24, s50, s37
	v_lshl_add_u64 v[192:193], s[28:29], 0, v[204:205]
	s_mov_b32 m0, s24
	ds_read_b128 v[176:179], v239
	ds_read_b128 v[180:183], v239 offset:1024
	ds_read_b128 v[184:187], v239 offset:2048
	ds_read_b128 v[188:191], v239 offset:3072
	global_load_lds_dwordx4 v[192:193], off
	v_lshl_add_u64 v[194:195], s[28:29], 0, v[208:209]
	s_add_i32 m0, s24, 0x2000
	s_nop 0
	global_load_lds_dwordx4 v[194:195], off
	s_barrier
	s_waitcnt lgkmcnt(0)
	s_setprio 1
	s_waitcnt lgkmcnt(0)
	v_mfma_f32_16x16x32_bf16 v[116:119], v[176:179], v[144:147], 0
	v_mfma_f32_16x16x32_bf16 v[112:115], v[184:187], v[144:147], 0
	v_mfma_f32_16x16x32_bf16 v[100:103], v[176:179], v[152:155], 0
	v_mfma_f32_16x16x32_bf16 v[96:99], v[184:187], v[152:155], 0
	v_mfma_f32_16x16x32_bf16 v[84:87], v[176:179], v[160:163], 0
	v_mfma_f32_16x16x32_bf16 v[80:83], v[184:187], v[160:163], 0
	v_mfma_f32_16x16x32_bf16 v[68:71], v[176:179], v[168:171], 0
	v_mfma_f32_16x16x32_bf16 v[64:67], v[184:187], v[168:171], 0
	v_mfma_f32_16x16x32_bf16 v[116:119], v[180:183], v[148:151], v[116:119]
	v_mfma_f32_16x16x32_bf16 v[112:115], v[188:191], v[148:151], v[112:115]
	v_mfma_f32_16x16x32_bf16 v[100:103], v[180:183], v[156:159], v[100:103]
	v_mfma_f32_16x16x32_bf16 v[96:99], v[188:191], v[156:159], v[96:99]
	v_mfma_f32_16x16x32_bf16 v[84:87], v[180:183], v[164:167], v[84:87]
	v_mfma_f32_16x16x32_bf16 v[80:83], v[188:191], v[164:167], v[80:83]
	v_mfma_f32_16x16x32_bf16 v[68:71], v[180:183], v[172:175], v[68:71]
	v_mfma_f32_16x16x32_bf16 v[64:67], v[188:191], v[172:175], v[64:67]
	s_setprio 0
	s_mov_b32 m0, s38
	v_lshl_add_u64 v[196:197], s[30:31], 0, v[202:203]
	s_barrier
	ds_read_b128 v[144:147], v238 offset:16384
	ds_read_b128 v[148:151], v238 offset:17408
	ds_read_b128 v[152:155], v238 offset:18432
	ds_read_b128 v[156:159], v238 offset:19456
	ds_read_b128 v[160:163], v238 offset:20480
	ds_read_b128 v[164:167], v238 offset:21504
	ds_read_b128 v[168:171], v238 offset:22528
	ds_read_b128 v[172:175], v238 offset:23552
	global_load_lds_dwordx4 v[196:197], off
	v_lshl_add_u64 v[198:199], s[30:31], 0, v[206:207]
	s_mov_b32 m0, s39
	s_nop 0
	global_load_lds_dwordx4 v[198:199], off
	s_barrier
	s_waitcnt lgkmcnt(0)
	s_setprio 1
	s_waitcnt lgkmcnt(0)
	v_mfma_f32_16x16x32_bf16 v[60:63], v[128:131], v[144:147], 0
	v_mfma_f32_16x16x32_bf16 v[56:59], v[136:139], v[144:147], 0
	v_mfma_f32_16x16x32_bf16 v[44:47], v[128:131], v[152:155], 0
	v_mfma_f32_16x16x32_bf16 v[40:43], v[136:139], v[152:155], 0
	v_mfma_f32_16x16x32_bf16 v[28:31], v[128:131], v[160:163], 0
	v_mfma_f32_16x16x32_bf16 v[24:27], v[136:139], v[160:163], 0
	v_mfma_f32_16x16x32_bf16 v[12:15], v[128:131], v[168:171], 0
	v_mfma_f32_16x16x32_bf16 v[8:11], v[136:139], v[168:171], 0
	v_mfma_f32_16x16x32_bf16 v[60:63], v[132:135], v[148:151], v[60:63]
	v_mfma_f32_16x16x32_bf16 v[56:59], v[140:143], v[148:151], v[56:59]
	v_mfma_f32_16x16x32_bf16 v[44:47], v[132:135], v[156:159], v[44:47]
	v_mfma_f32_16x16x32_bf16 v[40:43], v[140:143], v[156:159], v[40:43]
	v_mfma_f32_16x16x32_bf16 v[28:31], v[132:135], v[164:167], v[28:31]
	v_mfma_f32_16x16x32_bf16 v[24:27], v[140:143], v[164:167], v[24:27]
	v_mfma_f32_16x16x32_bf16 v[12:15], v[132:135], v[172:175], v[12:15]
	v_mfma_f32_16x16x32_bf16 v[8:11], v[140:143], v[172:175], v[8:11]
	s_setprio 0
	s_barrier
; #define PG8_STAGE(bufoff, gbase, voff) do { _Pragma("unroll") for (int _i = 0; _i < 2; ++_i) \
;         __builtin_amdgcn_global_load_lds((const unsigned*)((const char*)(gbase) + (voff)[_i]), (LAS unsigned*)(lds + (bufoff) + ldsw + _i * 8192), 16, 0, 0); } while (0)
; #define PG8_LDA(dst, b, h) do { _Pragma("unroll") for (int m = 0; m < 4; ++m) _Pragma("unroll") for (int k = 0; k < 2; ++k) dst[m][k] = *(const LAS bf16x8*)(lds + PG8_SA(b, h) + aoff + m * 2048 + k * 1024); } while (0)
; #define PG8_LDB(dst, b, h) do { _Pragma("unroll") for (int n = 0; n < 2; ++n) _Pragma("unroll") for (int k = 0; k < 2; ++k) dst[n][k] = *(const LAS bf16x8*)(lds + PG8_SB(b, h) + boff + n * 2048 + k * 1024); } while (0)
; #define PG8_MMA(ai, bj, At, Bt) do { __builtin_amdgcn_s_setprio(1); _Pragma("unroll") for (int m = 0; m < 4; ++m) _Pragma("unroll") for (int n = 0; n < 2; ++n) _Pragma("unroll") for (int k = 0; k < 2; ++k) \
;         acc[ai][bj][m][n] = __builtin_amdgcn_mfma_f32_16x16x32_bf16(Bt[n][k], At[m][k], acc[ai][bj][m][n], 0, 0, 0); __builtin_amdgcn_s_setprio(0); } while (0)
; #define PG8_WAIT_V(n) asm volatile("s_waitcnt vmcnt(" #n ")" ::: "memory")
; #define PG8_WAIT_L(n) asm volatile("s_waitcnt lgkmcnt(" #n ")" ::: "memory")
; #define PG8_BAR __builtin_amdgcn_s_barrier()
; #define PG8_SCHED __builtin_amdgcn_sched_barrier(0)
; template <class Epi, class Sched>
; __device__ __forceinline__ void gemm_phase(LAS unsigned char* lds, const Gemm g, const Sched& S, const Epi& E) {
;     ...
;             PG8_STAGE(PG8_SB(0, 1), b2 + hstep, voffB);
;             PG8_WAIT_V(6); PG8_BAR; PG8_MMA(1, 1, At, B1); PG8_BAR;
;             PG8_LDB(B0, 1, 0); PG8_SCHED; PG8_LDA(At, 1, 0); PG8_STAGE(PG8_SA(0, 1), a2 + hstep, voffA);
;             PG8_WAIT_L(8); PG8_BAR; PG8_WAIT_L(0); PG8_MMA(0, 0, At, B0); PG8_BAR; PG8_SCHED;
;             PG8_LDB(B1, 1, 1); PG8_STAGE(PG8_SB(1, 0), b3, voffB);
	s_add_u32 s24, s28, 0x60000
	s_addc_u32 s25, s29, 0
	s_add_i32 s59, s51, s37
	v_lshl_add_u64 v[128:129], s[24:25], 0, v[204:205]
	s_mov_b32 m0, s59
	s_nop 0
	global_load_lds_dwordx4 v[128:129], off
	v_lshl_add_u64 v[128:129], s[24:25], 0, v[208:209]
	s_add_i32 m0, s59, 0x2000
	s_nop 0
	global_load_lds_dwordx4 v[128:129], off
	s_waitcnt vmcnt(6)
	s_barrier
	s_setprio 1
	v_mfma_f32_16x16x32_bf16 v[52:55], v[176:179], v[144:147], 0
	v_mfma_f32_16x16x32_bf16 v[48:51], v[184:187], v[144:147], 0
	v_mfma_f32_16x16x32_bf16 v[36:39], v[176:179], v[152:155], 0
	v_mfma_f32_16x16x32_bf16 v[32:35], v[184:187], v[152:155], 0
	v_mfma_f32_16x16x32_bf16 v[20:23], v[176:179], v[160:163], 0
	v_mfma_f32_16x16x32_bf16 v[16:19], v[184:187], v[160:163], 0
	v_mfma_f32_16x16x32_bf16 v[4:7], v[176:179], v[168:171], 0
	v_mfma_f32_16x16x32_bf16 v[0:3], v[184:187], v[168:171], 0
	v_mfma_f32_16x16x32_bf16 v[52:55], v[180:183], v[148:151], v[52:55]
	v_mfma_f32_16x16x32_bf16 v[48:51], v[188:191], v[148:151], v[48:51]
	v_mfma_f32_16x16x32_bf16 v[36:39], v[180:183], v[156:159], v[36:39]
	v_mfma_f32_16x16x32_bf16 v[32:35], v[188:191], v[156:159], v[32:35]
	v_mfma_f32_16x16x32_bf16 v[20:23], v[180:183], v[164:167], v[20:23]
	v_mfma_f32_16x16x32_bf16 v[16:19], v[188:191], v[164:167], v[16:19]
	v_mfma_f32_16x16x32_bf16 v[4:7], v[180:183], v[172:175], v[4:7]
	v_mfma_f32_16x16x32_bf16 v[0:3], v[188:191], v[172:175], v[0:3]
	s_setprio 0
	s_add_i32 s59, 0, 0x18000
	v_add_u32_e32 v140, s59, v236
	s_barrier
	ds_read_b128 v[128:131], v140
	ds_read_b128 v[132:135], v140 offset:1024
	ds_read_b128 v[136:139], v140 offset:2048
	ds_read_b128 v[140:143], v140 offset:3072
	s_add_u32 s24, s30, 0x60000
	s_addc_u32 s25, s31, 0
	s_mov_b32 m0, s40
	v_lshl_add_u64 v[176:177], s[24:25], 0, v[202:203]
	ds_read_b128 v[144:147], v238 offset:32768
	ds_read_b128 v[148:151], v238 offset:33792
	ds_read_b128 v[152:155], v238 offset:34816
	ds_read_b128 v[156:159], v238 offset:35840
	ds_read_b128 v[160:163], v238 offset:36864
	ds_read_b128 v[164:167], v238 offset:37888
	ds_read_b128 v[168:171], v238 offset:38912
	ds_read_b128 v[172:175], v238 offset:39936
	global_load_lds_dwordx4 v[176:177], off
	v_lshl_add_u64 v[176:177], s[24:25], 0, v[206:207]
	s_mov_b32 m0, s41
	s_nop 0
	global_load_lds_dwordx4 v[176:177], off
	s_waitcnt lgkmcnt(8)
	s_barrier
	s_waitcnt lgkmcnt(0)
	s_setprio 1
	s_waitcnt lgkmcnt(0)
	v_mfma_f32_16x16x32_bf16 v[124:127], v[128:131], v[144:147], v[124:127]
	v_mfma_f32_16x16x32_bf16 v[120:123], v[136:139], v[144:147], v[120:123]
	v_mfma_f32_16x16x32_bf16 v[108:111], v[128:131], v[152:155], v[108:111]
	v_mfma_f32_16x16x32_bf16 v[104:107], v[136:139], v[152:155], v[104:107]
	v_mfma_f32_16x16x32_bf16 v[92:95], v[128:131], v[160:163], v[92:95]
	v_mfma_f32_16x16x32_bf16 v[88:91], v[136:139], v[160:163], v[88:91]
	v_mfma_f32_16x16x32_bf16 v[76:79], v[128:131], v[168:171], v[76:79]
	v_mfma_f32_16x16x32_bf16 v[72:75], v[136:139], v[168:171], v[72:75]
	v_mfma_f32_16x16x32_bf16 v[124:127], v[132:135], v[148:151], v[124:127]
	v_mfma_f32_16x16x32_bf16 v[120:123], v[140:143], v[148:151], v[120:123]
	v_mfma_f32_16x16x32_bf16 v[108:111], v[132:135], v[156:159], v[108:111]
	v_mfma_f32_16x16x32_bf16 v[104:107], v[140:143], v[156:159], v[104:107]
	v_mfma_f32_16x16x32_bf16 v[92:95], v[132:135], v[164:167], v[92:95]
	v_mfma_f32_16x16x32_bf16 v[88:91], v[140:143], v[164:167], v[88:91]
	v_mfma_f32_16x16x32_bf16 v[76:79], v[132:135], v[172:175], v[76:79]
	v_mfma_f32_16x16x32_bf16 v[72:75], v[140:143], v[172:175], v[72:75]
	s_setprio 0
	s_barrier
	s_add_i32 s30, 0, 0x1c000
	s_add_i32 s24, s59, s37
	v_add_u32_e32 v188, s30, v236
	v_lshl_add_u64 v[192:193], v[192:193], 0, s[0:1]
	s_mov_b32 m0, s24
	ds_read_b128 v[176:179], v188
	ds_read_b128 v[180:183], v188 offset:1024
	ds_read_b128 v[184:187], v188 offset:2048
	ds_read_b128 v[188:191], v188 offset:3072
	global_load_lds_dwordx4 v[192:193], off
	v_lshl_add_u64 v[192:193], v[194:195], 0, s[0:1]
	s_add_i32 m0, s24, 0x2000
	s_nop 0
	global_load_lds_dwordx4 v[192:193], off
	s_barrier
; #define PG8_STAGE(bufoff, gbase, voff) do { _Pragma("unroll") for (int _i = 0; _i < 2; ++_i) \
;         __builtin_amdgcn_global_load_lds((const unsigned*)((const char*)(gbase) + (voff)[_i]), (LAS unsigned*)(lds + (bufoff) + ldsw + _i * 8192), 16, 0, 0); } while (0)
; #define PG8_LDA(dst, b, h) do { _Pragma("unroll") for (int m = 0; m < 4; ++m) _Pragma("unroll") for (int k = 0; k < 2; ++k) dst[m][k] = *(const LAS bf16x8*)(lds + PG8_SA(b, h) + aoff + m * 2048 + k * 1024); } while (0)
; #define PG8_MMA(ai, bj, At, Bt) do { __builtin_amdgcn_s_setprio(1); _Pragma("unroll") for (int m = 0; m < 4; ++m) _Pragma("unroll") for (int n = 0; n < 2; ++n) _Pragma("unroll") for (int k = 0; k < 2; ++k) \
;         acc[ai][bj][m][n] = __builtin_amdgcn_mfma_f32_16x16x32_bf16(Bt[n][k], At[m][k], acc[ai][bj][m][n], 0, 0, 0); __builtin_amdgcn_s_setprio(0); } while (0)
; #define PG8_WAIT_V(n) asm volatile("s_waitcnt vmcnt(" #n ")" ::: "memory")
; #define PG8_WAIT_L(n) asm volatile("s_waitcnt lgkmcnt(" #n ")" ::: "memory")
; #define PG8_BAR __builtin_amdgcn_s_barrier()
; #define PG8_SCHED __builtin_amdgcn_sched_barrier(0)
; template <class Epi, class Sched>
; __device__ __forceinline__ void gemm_phase(LAS unsigned char* lds, const Gemm g, const Sched& S, const Epi& E) {
;     ...
;             PG8_BAR; PG8_WAIT_L(0); PG8_MMA(0, 1, At, B1); PG8_BAR;
;             PG8_LDA(At, 1, 1); PG8_STAGE(PG8_SA(1, 0), a3, voffA);
;             PG8_BAR; PG8_WAIT_L(0); PG8_MMA(1, 0, At, B0); PG8_BAR; PG8_SCHED;
;             PG8_STAGE(PG8_SB(1, 1), b3 + hstep, voffB);
;             PG8_WAIT_V(6); PG8_BAR; PG8_MMA(1, 1, At, B1); PG8_BAR;
	s_waitcnt lgkmcnt(0)
	s_setprio 1
	s_waitcnt lgkmcnt(0)
	v_mfma_f32_16x16x32_bf16 v[116:119], v[176:179], v[144:147], v[116:119]
	v_mfma_f32_16x16x32_bf16 v[112:115], v[184:187], v[144:147], v[112:115]
	v_mfma_f32_16x16x32_bf16 v[100:103], v[176:179], v[152:155], v[100:103]
	v_mfma_f32_16x16x32_bf16 v[96:99], v[184:187], v[152:155], v[96:99]
	v_mfma_f32_16x16x32_bf16 v[84:87], v[176:179], v[160:163], v[84:87]
	v_mfma_f32_16x16x32_bf16 v[80:83], v[184:187], v[160:163], v[80:83]
	v_mfma_f32_16x16x32_bf16 v[68:71], v[176:179], v[168:171], v[68:71]
	v_mfma_f32_16x16x32_bf16 v[64:67], v[184:187], v[168:171], v[64:67]
	v_mfma_f32_16x16x32_bf16 v[116:119], v[180:183], v[148:151], v[116:119]
	v_mfma_f32_16x16x32_bf16 v[112:115], v[188:191], v[148:151], v[112:115]
	v_mfma_f32_16x16x32_bf16 v[100:103], v[180:183], v[156:159], v[100:103]
	v_mfma_f32_16x16x32_bf16 v[96:99], v[188:191], v[156:159], v[96:99]
	v_mfma_f32_16x16x32_bf16 v[84:87], v[180:183], v[164:167], v[84:87]
	v_mfma_f32_16x16x32_bf16 v[80:83], v[188:191], v[164:167], v[80:83]
	v_mfma_f32_16x16x32_bf16 v[68:71], v[180:183], v[172:175], v[68:71]
	v_mfma_f32_16x16x32_bf16 v[64:67], v[188:191], v[172:175], v[64:67]
	s_setprio 0
	s_mov_b32 m0, s47
	v_lshl_add_u64 v[192:193], v[196:197], 0, s[0:1]
	s_barrier
	ds_read_b128 v[144:147], v238 offset:49152
	ds_read_b128 v[148:151], v238 offset:50176
	ds_read_b128 v[152:155], v238 offset:51200
	ds_read_b128 v[156:159], v238 offset:52224
	ds_read_b128 v[160:163], v238 offset:53248
	ds_read_b128 v[164:167], v238 offset:54272
	ds_read_b128 v[168:171], v238 offset:55296
	ds_read_b128 v[172:175], v238 offset:56320
	global_load_lds_dwordx4 v[192:193], off
	v_lshl_add_u64 v[192:193], v[198:199], 0, s[0:1]
	s_mov_b32 m0, s48
	s_nop 0
	global_load_lds_dwordx4 v[192:193], off
	s_barrier
	s_waitcnt lgkmcnt(0)
	s_setprio 1
	s_waitcnt lgkmcnt(0)
	v_mfma_f32_16x16x32_bf16 v[60:63], v[128:131], v[144:147], v[60:63]
	v_mfma_f32_16x16x32_bf16 v[56:59], v[136:139], v[144:147], v[56:59]
	v_mfma_f32_16x16x32_bf16 v[44:47], v[128:131], v[152:155], v[44:47]
	v_mfma_f32_16x16x32_bf16 v[40:43], v[136:139], v[152:155], v[40:43]
	v_mfma_f32_16x16x32_bf16 v[28:31], v[128:131], v[160:163], v[28:31]
	v_mfma_f32_16x16x32_bf16 v[24:27], v[136:139], v[160:163], v[24:27]
	v_mfma_f32_16x16x32_bf16 v[12:15], v[128:131], v[168:171], v[12:15]
	v_mfma_f32_16x16x32_bf16 v[8:11], v[136:139], v[168:171], v[8:11]
	v_mfma_f32_16x16x32_bf16 v[60:63], v[132:135], v[148:151], v[60:63]
	v_mfma_f32_16x16x32_bf16 v[56:59], v[140:143], v[148:151], v[56:59]
	v_mfma_f32_16x16x32_bf16 v[44:47], v[132:135], v[156:159], v[44:47]
	v_mfma_f32_16x16x32_bf16 v[40:43], v[140:143], v[156:159], v[40:43]
	v_mfma_f32_16x16x32_bf16 v[28:31], v[132:135], v[164:167], v[28:31]
	v_mfma_f32_16x16x32_bf16 v[24:27], v[140:143], v[164:167], v[24:27]
	v_mfma_f32_16x16x32_bf16 v[12:15], v[132:135], v[172:175], v[12:15]
	v_mfma_f32_16x16x32_bf16 v[8:11], v[140:143], v[172:175], v[8:11]
	s_setprio 0
	s_barrier
	s_add_u32 s24, s28, 0x60080
	s_addc_u32 s25, s29, 0
	s_add_i32 s28, s30, s37
	v_lshl_add_u64 v[128:129], s[24:25], 0, v[204:205]
	s_mov_b32 m0, s28
	s_nop 0
	global_load_lds_dwordx4 v[128:129], off
	v_lshl_add_u64 v[128:129], s[24:25], 0, v[208:209]
	s_add_i32 m0, s28, 0x2000
	s_nop 0
	global_load_lds_dwordx4 v[128:129], off
	s_waitcnt vmcnt(6)
	s_barrier
	s_setprio 1
	v_mfma_f32_16x16x32_bf16 v[52:55], v[176:179], v[144:147], v[52:55]
	v_mfma_f32_16x16x32_bf16 v[48:51], v[184:187], v[144:147], v[48:51]
	v_mfma_f32_16x16x32_bf16 v[36:39], v[176:179], v[152:155], v[36:39]
	v_mfma_f32_16x16x32_bf16 v[32:35], v[184:187], v[152:155], v[32:35]
	v_mfma_f32_16x16x32_bf16 v[20:23], v[176:179], v[160:163], v[20:23]
	v_mfma_f32_16x16x32_bf16 v[16:19], v[184:187], v[160:163], v[16:19]
	v_mfma_f32_16x16x32_bf16 v[4:7], v[176:179], v[168:171], v[4:7]
	v_mfma_f32_16x16x32_bf16 v[0:3], v[184:187], v[168:171], v[0:3]
	v_mfma_f32_16x16x32_bf16 v[52:55], v[180:183], v[148:151], v[52:55]
	v_mfma_f32_16x16x32_bf16 v[48:51], v[188:191], v[148:151], v[48:51]
	v_mfma_f32_16x16x32_bf16 v[36:39], v[180:183], v[156:159], v[36:39]
	v_mfma_f32_16x16x32_bf16 v[32:35], v[188:191], v[156:159], v[32:35]
	v_mfma_f32_16x16x32_bf16 v[20:23], v[180:183], v[164:167], v[20:23]
	v_mfma_f32_16x16x32_bf16 v[16:19], v[188:191], v[164:167], v[16:19]
	v_mfma_f32_16x16x32_bf16 v[4:7], v[180:183], v[172:175], v[4:7]
	v_mfma_f32_16x16x32_bf16 v[0:3], v[188:191], v[172:175], v[0:3]
	s_setprio 0
	s_add_i32 s58, s58, 2
	s_add_u32 s56, s56, 0x100
	s_addc_u32 s57, s57, 0
	s_cmp_gt_u32 s58, 21
	s_mov_b64 s[24:25], s[26:27]
	s_barrier

; #define PG8_STAGE(bufoff, gbase, voff) do { _Pragma("unroll") for (int _i = 0; _i < 2; ++_i) \
;         __builtin_amdgcn_global_load_lds((const unsigned*)((const char*)(gbase) + (voff)[_i]), (LAS unsigned*)(lds + (bufoff) + ldsw + _i * 8192), 16, 0, 0); } while (0)
; #define PG8_LDA(dst, b, h) do { _Pragma("unroll") for (int m = 0; m < 4; ++m) _Pragma("unroll") for (int k = 0; k < 2; ++k) dst[m][k] = *(const LAS bf16x8*)(lds + PG8_SA(b, h) + aoff + m * 2048 + k * 1024); } while (0)
; #define PG8_LDB(dst, b, h) do { _Pragma("unroll") for (int n = 0; n < 2; ++n) _Pragma("unroll") for (int k = 0; k < 2; ++k) dst[n][k] = *(const LAS bf16x8*)(lds + PG8_SB(b, h) + boff + n * 2048 + k * 1024); } while (0)
; #define PG8_MMA(ai, bj, At, Bt) do { __builtin_amdgcn_s_setprio(1); _Pragma("unroll") for (int m = 0; m < 4; ++m) _Pragma("unroll") for (int n = 0; n < 2; ++n) _Pragma("unroll") for (int k = 0; k < 2; ++k) \
;         acc[ai][bj][m][n] = __builtin_amdgcn_mfma_f32_16x16x32_bf16(Bt[n][k], At[m][k], acc[ai][bj][m][n], 0, 0, 0); __builtin_amdgcn_s_setprio(0); } while (0)
; #define PG8_WAIT_L(n) asm volatile("s_waitcnt lgkmcnt(" #n ")" ::: "memory")
; #define PG8_BAR __builtin_amdgcn_s_barrier()
; #define PG8_SCHED __builtin_amdgcn_sched_barrier(0)
; template <class Epi, class Sched>
; __device__ __forceinline__ void gemm_phase(LAS unsigned char* lds, const Gemm g, const Sched& S, const Epi& E) {
;     ...
;             PG8_LDB(B0, 0, 0); PG8_SCHED; PG8_LDA(At, 0, 0); PG8_STAGE(PG8_SA(1, 1), a1 + hstep, voffA);
;             PG8_WAIT_L(8); PG8_BAR; PG8_WAIT_L(0); PG8_MMA(0, 0, At, B0); PG8_BAR; PG8_SCHED;
;             PG8_LDB(B1, 0, 1); PG8_STAGE(PG8_SB(0, 0), b2, voffB);
;             PG8_BAR; PG8_WAIT_L(0); PG8_MMA(0, 1, At, B1); PG8_BAR;
;             PG8_LDA(At, 0, 1); PG8_STAGE(PG8_SA(0, 0), a2, voffA);
;             PG8_BAR; PG8_WAIT_L(0); PG8_MMA(1, 0, At, B0); PG8_BAR; PG8_SCHED;
;     ...
; #pragma unroll
;         for (int a = 0; a < 2; ++a)
; #pragma unroll
;             for (int b = 0; b < 2; ++b)
; #pragma unroll
;                 for (int m = 0; m < 4; ++m)
; #pragma unroll
;                     for (int n = 0; n < 2; ++n) acc[a][b][m][n] = (f32x4){0.f, 0.f, 0.f, 0.f};
.LBB0_1020:
	s_ashr_i32 s7, s6, 31
	v_cmp_lt_i64_e32 vcc, s[10:11], v[140:141]
	s_lshl_b64 s[10:11], s[6:7], 19
	s_add_u32 s10, s96, s10
	s_addc_u32 s11, s97, s11
	s_and_b64 s[12:13], vcc, exec
	s_cselect_b32 s7, s11, s17
	s_cselect_b32 s42, s10, s16
	s_ashr_i32 s5, s4, 31
	s_lshl_b64 s[12:13], s[4:5], 19
	s_add_u32 s12, s23, s12
	s_addc_u32 s13, s24, s13
	s_and_b64 s[20:21], vcc, exec
	s_cselect_b32 s5, s13, s19
	s_cselect_b32 s43, s12, s18
	s_add_u32 s16, s16, 0x40080
	s_addc_u32 s17, s17, 0
	s_add_u32 s44, s18, 0x100
	s_addc_u32 s45, s19, 0
	s_mov_b32 s46, -2
	ds_read_b128 v[150:153], v147
	ds_read_b128 v[154:157], v147 offset:1024
	ds_read_b128 v[158:161], v147 offset:2048
	ds_read_b128 v[162:165], v147 offset:3072
	s_add_u32 s18, s16, 0xfffc0080
	s_addc_u32 s19, s17, -1
	s_cmp_eq_u32 s46, 12
	s_cselect_b32 s21, s7, s19
	s_cselect_b32 s20, s42, s18
	s_cselect_b32 s19, s5, s45
	s_cselect_b32 s18, s43, s44
	v_lshl_add_u64 v[198:199], s[16:17], 0, v[136:137]
	s_add_i32 m0, s15, 0xc000
	ds_read_b128 v[166:169], v148
	ds_read_b128 v[170:173], v148 offset:1024
	ds_read_b128 v[174:177], v148 offset:2048
	ds_read_b128 v[178:181], v148 offset:3072
	ds_read_b128 v[182:185], v148 offset:4096
	ds_read_b128 v[186:189], v148 offset:5120
	ds_read_b128 v[190:193], v148 offset:6144
	ds_read_b128 v[194:197], v148 offset:7168
	global_load_lds_dwordx4 v[198:199], off
	v_lshl_add_u64 v[198:199], s[16:17], 0, v[138:139]
	s_add_i32 m0, s15, 0xe000
	s_nop 0
	global_load_lds_dwordx4 v[198:199], off
	s_waitcnt lgkmcnt(8)
	s_barrier
	s_waitcnt lgkmcnt(0)
	s_setprio 1
	s_waitcnt lgkmcnt(0)
	v_mfma_f32_16x16x32_bf16 v[124:127], v[150:153], v[166:169], 0
	v_mfma_f32_16x16x32_bf16 v[116:119], v[158:161], v[166:169], 0
	v_mfma_f32_16x16x32_bf16 v[108:111], v[150:153], v[174:177], 0
	v_mfma_f32_16x16x32_bf16 v[100:103], v[158:161], v[174:177], 0
	v_mfma_f32_16x16x32_bf16 v[92:95], v[150:153], v[182:185], 0
	v_mfma_f32_16x16x32_bf16 v[84:87], v[158:161], v[182:185], 0
	v_mfma_f32_16x16x32_bf16 v[76:79], v[150:153], v[190:193], 0
	v_mfma_f32_16x16x32_bf16 v[68:71], v[158:161], v[190:193], 0
	v_mfma_f32_16x16x32_bf16 v[124:127], v[154:157], v[170:173], v[124:127]
	v_mfma_f32_16x16x32_bf16 v[116:119], v[162:165], v[170:173], v[116:119]
	v_mfma_f32_16x16x32_bf16 v[108:111], v[154:157], v[178:181], v[108:111]
	v_mfma_f32_16x16x32_bf16 v[100:103], v[162:165], v[178:181], v[100:103]
	v_mfma_f32_16x16x32_bf16 v[92:95], v[154:157], v[186:189], v[92:95]
	v_mfma_f32_16x16x32_bf16 v[84:87], v[162:165], v[186:189], v[84:87]
	v_mfma_f32_16x16x32_bf16 v[76:79], v[154:157], v[194:197], v[76:79]
	v_mfma_f32_16x16x32_bf16 v[68:71], v[162:165], v[194:197], v[68:71]
	s_setprio 0
	s_barrier
	s_add_i32 s47, s38, s25
	v_lshl_add_u64 v[198:199], s[18:19], 0, v[132:133]
	s_mov_b32 m0, s47
	ds_read_b128 v[202:205], v149
	ds_read_b128 v[206:209], v149 offset:1024
	ds_read_b128 v[210:213], v149 offset:2048
	ds_read_b128 v[214:217], v149 offset:3072
	global_load_lds_dwordx4 v[198:199], off
	v_lshl_add_u64 v[218:219], s[18:19], 0, v[128:129]
	s_add_i32 m0, s47, 0x2000
	s_nop 0
	global_load_lds_dwordx4 v[218:219], off
	s_barrier
	s_waitcnt lgkmcnt(0)
	s_setprio 1
	s_waitcnt lgkmcnt(0)
	v_mfma_f32_16x16x32_bf16 v[120:123], v[202:205], v[166:169], 0
	v_mfma_f32_16x16x32_bf16 v[112:115], v[210:213], v[166:169], 0
	v_mfma_f32_16x16x32_bf16 v[104:107], v[202:205], v[174:177], 0
	v_mfma_f32_16x16x32_bf16 v[96:99], v[210:213], v[174:177], 0
	v_mfma_f32_16x16x32_bf16 v[88:91], v[202:205], v[182:185], 0
	v_mfma_f32_16x16x32_bf16 v[80:83], v[210:213], v[182:185], 0
	v_mfma_f32_16x16x32_bf16 v[72:75], v[202:205], v[190:193], 0
	v_mfma_f32_16x16x32_bf16 v[64:67], v[210:213], v[190:193], 0
	v_mfma_f32_16x16x32_bf16 v[120:123], v[206:209], v[170:173], v[120:123]
	v_mfma_f32_16x16x32_bf16 v[112:115], v[214:217], v[170:173], v[112:115]
	v_mfma_f32_16x16x32_bf16 v[104:107], v[206:209], v[178:181], v[104:107]
	v_mfma_f32_16x16x32_bf16 v[96:99], v[214:217], v[178:181], v[96:99]
	v_mfma_f32_16x16x32_bf16 v[88:91], v[206:209], v[186:189], v[88:91]
	v_mfma_f32_16x16x32_bf16 v[80:83], v[214:217], v[186:189], v[80:83]
	v_mfma_f32_16x16x32_bf16 v[72:75], v[206:209], v[194:197], v[72:75]
	v_mfma_f32_16x16x32_bf16 v[64:67], v[214:217], v[194:197], v[64:67]
	s_setprio 0
	s_mov_b32 m0, s15
	v_lshl_add_u64 v[220:221], s[20:21], 0, v[134:135]
	s_barrier
	ds_read_b128 v[166:169], v148 offset:16384
	ds_read_b128 v[170:173], v148 offset:17408
	ds_read_b128 v[174:177], v148 offset:18432
	ds_read_b128 v[178:181], v148 offset:19456
	ds_read_b128 v[182:185], v148 offset:20480
	ds_read_b128 v[186:189], v148 offset:21504
	ds_read_b128 v[190:193], v148 offset:22528
	ds_read_b128 v[194:197], v148 offset:23552
	global_load_lds_dwordx4 v[220:221], off
	v_lshl_add_u64 v[222:223], s[20:21], 0, v[130:131]
	s_mov_b32 m0, s28
	s_nop 0
	global_load_lds_dwordx4 v[222:223], off
	s_barrier
	s_waitcnt lgkmcnt(0)
	s_setprio 1
	s_waitcnt lgkmcnt(0)
	v_mfma_f32_16x16x32_bf16 v[60:63], v[150:153], v[166:169], 0
	v_mfma_f32_16x16x32_bf16 v[56:59], v[158:161], v[166:169], 0
	v_mfma_f32_16x16x32_bf16 v[44:47], v[150:153], v[174:177], 0
	v_mfma_f32_16x16x32_bf16 v[40:43], v[158:161], v[174:177], 0
	v_mfma_f32_16x16x32_bf16 v[28:31], v[150:153], v[182:185], 0
	v_mfma_f32_16x16x32_bf16 v[24:27], v[158:161], v[182:185], 0
	v_mfma_f32_16x16x32_bf16 v[12:15], v[150:153], v[190:193], 0
	v_mfma_f32_16x16x32_bf16 v[8:11], v[158:161], v[190:193], 0
	v_mfma_f32_16x16x32_bf16 v[60:63], v[154:157], v[170:173], v[60:63]
	v_mfma_f32_16x16x32_bf16 v[56:59], v[162:165], v[170:173], v[56:59]
	v_mfma_f32_16x16x32_bf16 v[44:47], v[154:157], v[178:181], v[44:47]
	v_mfma_f32_16x16x32_bf16 v[40:43], v[162:165], v[178:181], v[40:43]
	v_mfma_f32_16x16x32_bf16 v[28:31], v[154:157], v[186:189], v[28:31]
	v_mfma_f32_16x16x32_bf16 v[24:27], v[162:165], v[186:189], v[24:27]
	v_mfma_f32_16x16x32_bf16 v[12:15], v[154:157], v[194:197], v[12:15]
	v_mfma_f32_16x16x32_bf16 v[8:11], v[162:165], v[194:197], v[8:11]
	s_setprio 0
	s_barrier
; #define PG8_STAGE(bufoff, gbase, voff) do { _Pragma("unroll") for (int _i = 0; _i < 2; ++_i) \
;         __builtin_amdgcn_global_load_lds((const unsigned*)((const char*)(gbase) + (voff)[_i]), (LAS unsigned*)(lds + (bufoff) + ldsw + _i * 8192), 16, 0, 0); } while (0)
; #define PG8_LDA(dst, b, h) do { _Pragma("unroll") for (int m = 0; m < 4; ++m) _Pragma("unroll") for (int k = 0; k < 2; ++k) dst[m][k] = *(const LAS bf16x8*)(lds + PG8_SA(b, h) + aoff + m * 2048 + k * 1024); } while (0)
; #define PG8_LDB(dst, b, h) do { _Pragma("unroll") for (int n = 0; n < 2; ++n) _Pragma("unroll") for (int k = 0; k < 2; ++k) dst[n][k] = *(const LAS bf16x8*)(lds + PG8_SB(b, h) + boff + n * 2048 + k * 1024); } while (0)
; #define PG8_MMA(ai, bj, At, Bt) do { __builtin_amdgcn_s_setprio(1); _Pragma("unroll") for (int m = 0; m < 4; ++m) _Pragma("unroll") for (int n = 0; n < 2; ++n) _Pragma("unroll") for (int k = 0; k < 2; ++k) \
;         acc[ai][bj][m][n] = __builtin_amdgcn_mfma_f32_16x16x32_bf16(Bt[n][k], At[m][k], acc[ai][bj][m][n], 0, 0, 0); __builtin_amdgcn_s_setprio(0); } while (0)
; #define PG8_WAIT_V(n) asm volatile("s_waitcnt vmcnt(" #n ")" ::: "memory")
; #define PG8_WAIT_L(n) asm volatile("s_waitcnt lgkmcnt(" #n ")" ::: "memory")
; #define PG8_BAR __builtin_amdgcn_s_barrier()
; #define PG8_SCHED __builtin_amdgcn_sched_barrier(0)
; template <class Epi, class Sched>
; __device__ __forceinline__ void gemm_phase(LAS unsigned char* lds, const Gemm g, const Sched& S, const Epi& E) {
;     ...
;             PG8_STAGE(PG8_SB(0, 1), b2 + hstep, voffB);
;             PG8_WAIT_V(6); PG8_BAR; PG8_MMA(1, 1, At, B1); PG8_BAR;
;             PG8_LDB(B0, 1, 0); PG8_SCHED; PG8_LDA(At, 1, 0); PG8_STAGE(PG8_SA(0, 1), a2 + hstep, voffA);
;             PG8_WAIT_L(8); PG8_BAR; PG8_WAIT_L(0); PG8_MMA(0, 0, At, B0); PG8_BAR; PG8_SCHED;
;             PG8_LDB(B1, 1, 1); PG8_STAGE(PG8_SB(1, 0), b3, voffB);
	s_add_u32 s48, s18, 0x40000
	s_addc_u32 s49, s19, 0
	s_add_i32 s47, s39, s25
	v_lshl_add_u64 v[150:151], s[48:49], 0, v[132:133]
	s_mov_b32 m0, s47
	s_nop 0
	global_load_lds_dwordx4 v[150:151], off
	v_lshl_add_u64 v[150:151], s[48:49], 0, v[128:129]
	s_add_i32 m0, s47, 0x2000
	s_nop 0
	global_load_lds_dwordx4 v[150:151], off
	s_waitcnt vmcnt(6)
	s_barrier
	s_setprio 1
	v_mfma_f32_16x16x32_bf16 v[52:55], v[202:205], v[166:169], 0
	v_mfma_f32_16x16x32_bf16 v[48:51], v[210:213], v[166:169], 0
	v_mfma_f32_16x16x32_bf16 v[36:39], v[202:205], v[174:177], 0
	v_mfma_f32_16x16x32_bf16 v[32:35], v[210:213], v[174:177], 0
	v_mfma_f32_16x16x32_bf16 v[20:23], v[202:205], v[182:185], 0
	v_mfma_f32_16x16x32_bf16 v[16:19], v[210:213], v[182:185], 0
	v_mfma_f32_16x16x32_bf16 v[4:7], v[202:205], v[190:193], 0
	v_mfma_f32_16x16x32_bf16 v[0:3], v[210:213], v[190:193], 0
	v_mfma_f32_16x16x32_bf16 v[52:55], v[206:209], v[170:173], v[52:55]
	v_mfma_f32_16x16x32_bf16 v[48:51], v[214:217], v[170:173], v[48:51]
	v_mfma_f32_16x16x32_bf16 v[36:39], v[206:209], v[178:181], v[36:39]
	v_mfma_f32_16x16x32_bf16 v[32:35], v[214:217], v[178:181], v[32:35]
	v_mfma_f32_16x16x32_bf16 v[20:23], v[206:209], v[186:189], v[20:23]
	v_mfma_f32_16x16x32_bf16 v[16:19], v[214:217], v[186:189], v[16:19]
	v_mfma_f32_16x16x32_bf16 v[4:7], v[206:209], v[194:197], v[4:7]
	v_mfma_f32_16x16x32_bf16 v[0:3], v[214:217], v[194:197], v[0:3]
	s_setprio 0
	s_add_i32 s47, 0, 0x18000
	v_add_u32_e32 v162, s47, v146
	s_barrier
	ds_read_b128 v[150:153], v162
	ds_read_b128 v[154:157], v162 offset:1024
	ds_read_b128 v[158:161], v162 offset:2048
	ds_read_b128 v[162:165], v162 offset:3072
	s_add_u32 s20, s20, 0x40000
	s_addc_u32 s21, s21, 0
	s_mov_b32 m0, s29
	v_lshl_add_u64 v[202:203], s[20:21], 0, v[134:135]
	ds_read_b128 v[166:169], v148 offset:32768
	ds_read_b128 v[170:173], v148 offset:33792
	ds_read_b128 v[174:177], v148 offset:34816
	ds_read_b128 v[178:181], v148 offset:35840
	ds_read_b128 v[182:185], v148 offset:36864
	ds_read_b128 v[186:189], v148 offset:37888
	ds_read_b128 v[190:193], v148 offset:38912
	ds_read_b128 v[194:197], v148 offset:39936
	global_load_lds_dwordx4 v[202:203], off
	v_lshl_add_u64 v[202:203], s[20:21], 0, v[130:131]
	s_mov_b32 m0, s30
	s_nop 0
	global_load_lds_dwordx4 v[202:203], off
	s_waitcnt lgkmcnt(8)
	s_barrier
	s_waitcnt lgkmcnt(0)
	s_setprio 1
	s_waitcnt lgkmcnt(0)
	v_mfma_f32_16x16x32_bf16 v[124:127], v[150:153], v[166:169], v[124:127]
	v_mfma_f32_16x16x32_bf16 v[116:119], v[158:161], v[166:169], v[116:119]
	v_mfma_f32_16x16x32_bf16 v[108:111], v[150:153], v[174:177], v[108:111]
	v_mfma_f32_16x16x32_bf16 v[100:103], v[158:161], v[174:177], v[100:103]
	v_mfma_f32_16x16x32_bf16 v[92:95], v[150:153], v[182:185], v[92:95]
	v_mfma_f32_16x16x32_bf16 v[84:87], v[158:161], v[182:185], v[84:87]
	v_mfma_f32_16x16x32_bf16 v[76:79], v[150:153], v[190:193], v[76:79]
	v_mfma_f32_16x16x32_bf16 v[68:71], v[158:161], v[190:193], v[68:71]
	v_mfma_f32_16x16x32_bf16 v[124:127], v[154:157], v[170:173], v[124:127]
	v_mfma_f32_16x16x32_bf16 v[116:119], v[162:165], v[170:173], v[116:119]
	v_mfma_f32_16x16x32_bf16 v[108:111], v[154:157], v[178:181], v[108:111]
	v_mfma_f32_16x16x32_bf16 v[100:103], v[162:165], v[178:181], v[100:103]
	v_mfma_f32_16x16x32_bf16 v[92:95], v[154:157], v[186:189], v[92:95]
	v_mfma_f32_16x16x32_bf16 v[84:87], v[162:165], v[186:189], v[84:87]
	v_mfma_f32_16x16x32_bf16 v[76:79], v[154:157], v[194:197], v[76:79]
	v_mfma_f32_16x16x32_bf16 v[68:71], v[162:165], v[194:197], v[68:71]
	s_setprio 0
	s_barrier
	s_add_i32 s20, 0, 0x1c000
	s_add_i32 s21, s47, s25
	v_add_u32_e32 v214, s20, v146
	v_lshl_add_u64 v[198:199], v[198:199], 0, s[0:1]
	s_mov_b32 m0, s21
	ds_read_b128 v[202:205], v214
	ds_read_b128 v[206:209], v214 offset:1024
	ds_read_b128 v[210:213], v214 offset:2048
	ds_read_b128 v[214:217], v214 offset:3072
	global_load_lds_dwordx4 v[198:199], off
	v_lshl_add_u64 v[198:199], v[218:219], 0, s[0:1]
	s_add_i32 m0, s21, 0x2000
	s_nop 0
	global_load_lds_dwordx4 v[198:199], off
	s_barrier
; #define PG8_STAGE(bufoff, gbase, voff) do { _Pragma("unroll") for (int _i = 0; _i < 2; ++_i) \
;         __builtin_amdgcn_global_load_lds((const unsigned*)((const char*)(gbase) + (voff)[_i]), (LAS unsigned*)(lds + (bufoff) + ldsw + _i * 8192), 16, 0, 0); } while (0)
; #define PG8_LDA(dst, b, h) do { _Pragma("unroll") for (int m = 0; m < 4; ++m) _Pragma("unroll") for (int k = 0; k < 2; ++k) dst[m][k] = *(const LAS bf16x8*)(lds + PG8_SA(b, h) + aoff + m * 2048 + k * 1024); } while (0)
; #define PG8_MMA(ai, bj, At, Bt) do { __builtin_amdgcn_s_setprio(1); _Pragma("unroll") for (int m = 0; m < 4; ++m) _Pragma("unroll") for (int n = 0; n < 2; ++n) _Pragma("unroll") for (int k = 0; k < 2; ++k) \
;         acc[ai][bj][m][n] = __builtin_amdgcn_mfma_f32_16x16x32_bf16(Bt[n][k], At[m][k], acc[ai][bj][m][n], 0, 0, 0); __builtin_amdgcn_s_setprio(0); } while (0)
; #define PG8_WAIT_V(n) asm volatile("s_waitcnt vmcnt(" #n ")" ::: "memory")
; #define PG8_WAIT_L(n) asm volatile("s_waitcnt lgkmcnt(" #n ")" ::: "memory")
; #define PG8_BAR __builtin_amdgcn_s_barrier()
; #define PG8_SCHED __builtin_amdgcn_sched_barrier(0)
; template <class Epi, class Sched>
; __device__ __forceinline__ void gemm_phase(LAS unsigned char* lds, const Gemm g, const Sched& S, const Epi& E) {
;     ...
;             PG8_BAR; PG8_WAIT_L(0); PG8_MMA(0, 1, At, B1); PG8_BAR;
;             PG8_LDA(At, 1, 1); PG8_STAGE(PG8_SA(1, 0), a3, voffA);
;             PG8_BAR; PG8_WAIT_L(0); PG8_MMA(1, 0, At, B0); PG8_BAR; PG8_SCHED;
;             PG8_STAGE(PG8_SB(1, 1), b3 + hstep, voffB);
;             PG8_WAIT_V(6); PG8_BAR; PG8_MMA(1, 1, At, B1); PG8_BAR;
	s_waitcnt lgkmcnt(0)
	s_setprio 1
	s_waitcnt lgkmcnt(0)
	v_mfma_f32_16x16x32_bf16 v[120:123], v[202:205], v[166:169], v[120:123]
	v_mfma_f32_16x16x32_bf16 v[112:115], v[210:213], v[166:169], v[112:115]
	v_mfma_f32_16x16x32_bf16 v[104:107], v[202:205], v[174:177], v[104:107]
	v_mfma_f32_16x16x32_bf16 v[96:99], v[210:213], v[174:177], v[96:99]
	v_mfma_f32_16x16x32_bf16 v[88:91], v[202:205], v[182:185], v[88:91]
	v_mfma_f32_16x16x32_bf16 v[80:83], v[210:213], v[182:185], v[80:83]
	v_mfma_f32_16x16x32_bf16 v[72:75], v[202:205], v[190:193], v[72:75]
	v_mfma_f32_16x16x32_bf16 v[64:67], v[210:213], v[190:193], v[64:67]
	v_mfma_f32_16x16x32_bf16 v[120:123], v[206:209], v[170:173], v[120:123]
	v_mfma_f32_16x16x32_bf16 v[112:115], v[214:217], v[170:173], v[112:115]
	v_mfma_f32_16x16x32_bf16 v[104:107], v[206:209], v[178:181], v[104:107]
	v_mfma_f32_16x16x32_bf16 v[96:99], v[214:217], v[178:181], v[96:99]
	v_mfma_f32_16x16x32_bf16 v[88:91], v[206:209], v[186:189], v[88:91]
	v_mfma_f32_16x16x32_bf16 v[80:83], v[214:217], v[186:189], v[80:83]
	v_mfma_f32_16x16x32_bf16 v[72:75], v[206:209], v[194:197], v[72:75]
	v_mfma_f32_16x16x32_bf16 v[64:67], v[214:217], v[194:197], v[64:67]
	s_setprio 0
	s_mov_b32 m0, s35
	v_lshl_add_u64 v[198:199], v[220:221], 0, s[0:1]
	s_barrier
	ds_read_b128 v[166:169], v148 offset:49152
	ds_read_b128 v[170:173], v148 offset:50176
	ds_read_b128 v[174:177], v148 offset:51200
	ds_read_b128 v[178:181], v148 offset:52224
	ds_read_b128 v[182:185], v148 offset:53248
	ds_read_b128 v[186:189], v148 offset:54272
	ds_read_b128 v[190:193], v148 offset:55296
	ds_read_b128 v[194:197], v148 offset:56320
	global_load_lds_dwordx4 v[198:199], off
	v_lshl_add_u64 v[198:199], v[222:223], 0, s[0:1]
	s_mov_b32 m0, s36
	s_nop 0
	global_load_lds_dwordx4 v[198:199], off
	s_barrier
	s_waitcnt lgkmcnt(0)
	s_setprio 1
	s_waitcnt lgkmcnt(0)
	v_mfma_f32_16x16x32_bf16 v[60:63], v[150:153], v[166:169], v[60:63]
	v_mfma_f32_16x16x32_bf16 v[56:59], v[158:161], v[166:169], v[56:59]
	v_mfma_f32_16x16x32_bf16 v[44:47], v[150:153], v[174:177], v[44:47]
	v_mfma_f32_16x16x32_bf16 v[40:43], v[158:161], v[174:177], v[40:43]
	v_mfma_f32_16x16x32_bf16 v[28:31], v[150:153], v[182:185], v[28:31]
	v_mfma_f32_16x16x32_bf16 v[24:27], v[158:161], v[182:185], v[24:27]
	v_mfma_f32_16x16x32_bf16 v[12:15], v[150:153], v[190:193], v[12:15]
	v_mfma_f32_16x16x32_bf16 v[8:11], v[158:161], v[190:193], v[8:11]
	v_mfma_f32_16x16x32_bf16 v[60:63], v[154:157], v[170:173], v[60:63]
	v_mfma_f32_16x16x32_bf16 v[56:59], v[162:165], v[170:173], v[56:59]
	v_mfma_f32_16x16x32_bf16 v[44:47], v[154:157], v[178:181], v[44:47]
	v_mfma_f32_16x16x32_bf16 v[40:43], v[162:165], v[178:181], v[40:43]
	v_mfma_f32_16x16x32_bf16 v[28:31], v[154:157], v[186:189], v[28:31]
	v_mfma_f32_16x16x32_bf16 v[24:27], v[162:165], v[186:189], v[24:27]
	v_mfma_f32_16x16x32_bf16 v[12:15], v[154:157], v[194:197], v[12:15]
	v_mfma_f32_16x16x32_bf16 v[8:11], v[162:165], v[194:197], v[8:11]
	s_setprio 0
	s_barrier
	s_add_u32 s18, s18, 0x40080
	s_addc_u32 s19, s19, 0
	s_add_i32 s20, s20, s25
	v_lshl_add_u64 v[150:151], s[18:19], 0, v[132:133]
	s_mov_b32 m0, s20
	s_nop 0
	global_load_lds_dwordx4 v[150:151], off
	v_lshl_add_u64 v[150:151], s[18:19], 0, v[128:129]
	s_add_i32 m0, s20, 0x2000
	s_nop 0
	global_load_lds_dwordx4 v[150:151], off
	s_waitcnt vmcnt(6)
	s_barrier
	s_setprio 1
	v_mfma_f32_16x16x32_bf16 v[52:55], v[202:205], v[166:169], v[52:55]
	v_mfma_f32_16x16x32_bf16 v[48:51], v[210:213], v[166:169], v[48:51]
	v_mfma_f32_16x16x32_bf16 v[36:39], v[202:205], v[174:177], v[36:39]
	v_mfma_f32_16x16x32_bf16 v[32:35], v[210:213], v[174:177], v[32:35]
	v_mfma_f32_16x16x32_bf16 v[20:23], v[202:205], v[182:185], v[20:23]
	v_mfma_f32_16x16x32_bf16 v[16:19], v[210:213], v[182:185], v[16:19]
	v_mfma_f32_16x16x32_bf16 v[4:7], v[202:205], v[190:193], v[4:7]
	v_mfma_f32_16x16x32_bf16 v[0:3], v[210:213], v[190:193], v[0:3]
	v_mfma_f32_16x16x32_bf16 v[52:55], v[206:209], v[170:173], v[52:55]
	v_mfma_f32_16x16x32_bf16 v[48:51], v[214:217], v[170:173], v[48:51]
	v_mfma_f32_16x16x32_bf16 v[36:39], v[206:209], v[178:181], v[36:39]
	v_mfma_f32_16x16x32_bf16 v[32:35], v[214:217], v[178:181], v[32:35]
	v_mfma_f32_16x16x32_bf16 v[20:23], v[206:209], v[186:189], v[20:23]
	v_mfma_f32_16x16x32_bf16 v[16:19], v[214:217], v[186:189], v[16:19]
	v_mfma_f32_16x16x32_bf16 v[4:7], v[206:209], v[194:197], v[4:7]
	v_mfma_f32_16x16x32_bf16 v[0:3], v[214:217], v[194:197], v[0:3]
	s_setprio 0
	s_add_i32 s46, s46, 2
	s_add_u32 s16, s16, 0x100
	s_addc_u32 s17, s17, 0
	s_add_u32 s44, s44, 0x100
	s_addc_u32 s45, s45, 0
	s_cmp_gt_u32 s46, 13
	s_barrier

; #define PG8_STAGE(bufoff, gbase, voff) do { _Pragma("unroll") for (int _i = 0; _i < 2; ++_i) \
;         __builtin_amdgcn_global_load_lds((const unsigned*)((const char*)(gbase) + (voff)[_i]), (LAS unsigned*)(lds + (bufoff) + ldsw + _i * 8192), 16, 0, 0); } while (0)
; #define PG8_LDA(dst, b, h) do { _Pragma("unroll") for (int m = 0; m < 4; ++m) _Pragma("unroll") for (int k = 0; k < 2; ++k) dst[m][k] = *(const LAS bf16x8*)(lds + PG8_SA(b, h) + aoff + m * 2048 + k * 1024); } while (0)
; #define PG8_LDB(dst, b, h) do { _Pragma("unroll") for (int n = 0; n < 2; ++n) _Pragma("unroll") for (int k = 0; k < 2; ++k) dst[n][k] = *(const LAS bf16x8*)(lds + PG8_SB(b, h) + boff + n * 2048 + k * 1024); } while (0)
; #define PG8_MMA(ai, bj, At, Bt) do { __builtin_amdgcn_s_setprio(1); _Pragma("unroll") for (int m = 0; m < 4; ++m) _Pragma("unroll") for (int n = 0; n < 2; ++n) _Pragma("unroll") for (int k = 0; k < 2; ++k) \
;         acc[ai][bj][m][n] = __builtin_amdgcn_mfma_f32_16x16x32_bf16(Bt[n][k], At[m][k], acc[ai][bj][m][n], 0, 0, 0); __builtin_amdgcn_s_setprio(0); } while (0)
; #define PG8_WAIT_L(n) asm volatile("s_waitcnt lgkmcnt(" #n ")" ::: "memory")
; #define PG8_BAR __builtin_amdgcn_s_barrier()
; #define PG8_SCHED __builtin_amdgcn_sched_barrier(0)
; template <class Epi, class Sched>
; __device__ __forceinline__ void gemm_phase(LAS unsigned char* lds, const Gemm g, const Sched& S, const Epi& E) {
;     ...
;             PG8_LDB(B0, 0, 0); PG8_SCHED; PG8_LDA(At, 0, 0); PG8_STAGE(PG8_SA(1, 1), a1 + hstep, voffA);
;             PG8_WAIT_L(8); PG8_BAR; PG8_WAIT_L(0); PG8_MMA(0, 0, At, B0); PG8_BAR; PG8_SCHED;
;             PG8_LDB(B1, 0, 1); PG8_STAGE(PG8_SB(0, 0), b2, voffB);
;             PG8_BAR; PG8_WAIT_L(0); PG8_MMA(0, 1, At, B1); PG8_BAR;
;             PG8_LDA(At, 0, 1); PG8_STAGE(PG8_SA(0, 0), a2, voffA);
;             PG8_BAR; PG8_WAIT_L(0); PG8_MMA(1, 0, At, B0); PG8_BAR; PG8_SCHED;
;     ...
; #pragma unroll
;         for (int a = 0; a < 2; ++a)
; #pragma unroll
;             for (int b = 0; b < 2; ++b)
; #pragma unroll
;                 for (int m = 0; m < 4; ++m)
; #pragma unroll
;                     for (int n = 0; n < 2; ++n) acc[a][b][m][n] = (f32x4){0.f, 0.f, 0.f, 0.f};
.LBB0_1096:
	s_add_u32 s54, s24, 0x100
	s_addc_u32 s55, s25, 0
	s_mov_b32 s56, -2
	ds_read_b128 v[128:131], v241
	ds_read_b128 v[132:135], v241 offset:1024
	ds_read_b128 v[136:139], v241 offset:2048
	ds_read_b128 v[140:143], v241 offset:3072
	s_add_u32 s24, s22, 0x100
	s_addc_u32 s25, s23, 0
	s_cmp_eq_u32 s56, 40
	s_cselect_b32 s29, s5, s25
	s_cselect_b32 s28, s4, s24
	s_cselect_b32 s27, s7, s55
	s_cselect_b32 s26, s6, s54
	v_lshl_add_u64 v[176:177], s[22:23], 0, v[196:197]
	s_add_i32 m0, s35, 0xc000
	ds_read_b128 v[144:147], v242
	ds_read_b128 v[148:151], v242 offset:1024
	ds_read_b128 v[152:155], v242 offset:2048
	ds_read_b128 v[156:159], v242 offset:3072
	ds_read_b128 v[160:163], v242 offset:4096
	ds_read_b128 v[164:167], v242 offset:5120
	ds_read_b128 v[168:171], v242 offset:6144
	ds_read_b128 v[172:175], v242 offset:7168
	global_load_lds_dwordx4 v[176:177], off
	v_lshl_add_u64 v[176:177], s[22:23], 0, v[198:199]
	s_add_i32 m0, s35, 0xe000
	s_nop 0
	global_load_lds_dwordx4 v[176:177], off
	s_waitcnt lgkmcnt(8)
	s_barrier
	s_waitcnt lgkmcnt(0)
	s_setprio 1
	s_waitcnt lgkmcnt(0)
	v_mfma_f32_16x16x32_bf16 v[124:127], v[128:131], v[144:147], 0
	v_mfma_f32_16x16x32_bf16 v[120:123], v[136:139], v[144:147], 0
	v_mfma_f32_16x16x32_bf16 v[108:111], v[128:131], v[152:155], 0
	v_mfma_f32_16x16x32_bf16 v[104:107], v[136:139], v[152:155], 0
	v_mfma_f32_16x16x32_bf16 v[92:95], v[128:131], v[160:163], 0
	v_mfma_f32_16x16x32_bf16 v[88:91], v[136:139], v[160:163], 0
	v_mfma_f32_16x16x32_bf16 v[76:79], v[128:131], v[168:171], 0
	v_mfma_f32_16x16x32_bf16 v[72:75], v[136:139], v[168:171], 0
	v_mfma_f32_16x16x32_bf16 v[124:127], v[132:135], v[148:151], v[124:127]
	v_mfma_f32_16x16x32_bf16 v[120:123], v[140:143], v[148:151], v[120:123]
	v_mfma_f32_16x16x32_bf16 v[108:111], v[132:135], v[156:159], v[108:111]
	v_mfma_f32_16x16x32_bf16 v[104:107], v[140:143], v[156:159], v[104:107]
	v_mfma_f32_16x16x32_bf16 v[92:95], v[132:135], v[164:167], v[92:95]
	v_mfma_f32_16x16x32_bf16 v[88:91], v[140:143], v[164:167], v[88:91]
	v_mfma_f32_16x16x32_bf16 v[76:79], v[132:135], v[172:175], v[76:79]
	v_mfma_f32_16x16x32_bf16 v[72:75], v[140:143], v[172:175], v[72:75]
	s_setprio 0
	s_barrier
	s_add_i32 s22, s48, s34
	v_lshl_add_u64 v[210:211], s[26:27], 0, v[190:191]
	s_mov_b32 m0, s22
	ds_read_b128 v[176:179], v243
	ds_read_b128 v[180:183], v243 offset:1024
	ds_read_b128 v[184:187], v243 offset:2048
	ds_read_b128 v[206:209], v243 offset:3072
	global_load_lds_dwordx4 v[210:211], off
	v_lshl_add_u64 v[212:213], s[26:27], 0, v[194:195]
	s_add_i32 m0, s22, 0x2000
	s_nop 0
	global_load_lds_dwordx4 v[212:213], off
	s_barrier
	s_waitcnt lgkmcnt(0)
	s_setprio 1
	s_waitcnt lgkmcnt(0)
	v_mfma_f32_16x16x32_bf16 v[116:119], v[176:179], v[144:147], 0
	v_mfma_f32_16x16x32_bf16 v[112:115], v[184:187], v[144:147], 0
	v_mfma_f32_16x16x32_bf16 v[100:103], v[176:179], v[152:155], 0
	v_mfma_f32_16x16x32_bf16 v[96:99], v[184:187], v[152:155], 0
	v_mfma_f32_16x16x32_bf16 v[84:87], v[176:179], v[160:163], 0
	v_mfma_f32_16x16x32_bf16 v[80:83], v[184:187], v[160:163], 0
	v_mfma_f32_16x16x32_bf16 v[68:71], v[176:179], v[168:171], 0
	v_mfma_f32_16x16x32_bf16 v[64:67], v[184:187], v[168:171], 0
	v_mfma_f32_16x16x32_bf16 v[116:119], v[180:183], v[148:151], v[116:119]
	v_mfma_f32_16x16x32_bf16 v[112:115], v[206:209], v[148:151], v[112:115]
	v_mfma_f32_16x16x32_bf16 v[100:103], v[180:183], v[156:159], v[100:103]
	v_mfma_f32_16x16x32_bf16 v[96:99], v[206:209], v[156:159], v[96:99]
	v_mfma_f32_16x16x32_bf16 v[84:87], v[180:183], v[164:167], v[84:87]
	v_mfma_f32_16x16x32_bf16 v[80:83], v[206:209], v[164:167], v[80:83]
	v_mfma_f32_16x16x32_bf16 v[68:71], v[180:183], v[172:175], v[68:71]
	v_mfma_f32_16x16x32_bf16 v[64:67], v[206:209], v[172:175], v[64:67]
	s_setprio 0
	s_mov_b32 m0, s35
	v_lshl_add_u64 v[214:215], s[28:29], 0, v[188:189]
	s_barrier
	ds_read_b128 v[144:147], v242 offset:16384
	ds_read_b128 v[148:151], v242 offset:17408
	ds_read_b128 v[152:155], v242 offset:18432
	ds_read_b128 v[156:159], v242 offset:19456
	ds_read_b128 v[160:163], v242 offset:20480
	ds_read_b128 v[164:167], v242 offset:21504
	ds_read_b128 v[168:171], v242 offset:22528
	ds_read_b128 v[172:175], v242 offset:23552
	global_load_lds_dwordx4 v[214:215], off
	v_lshl_add_u64 v[216:217], s[28:29], 0, v[192:193]
	s_mov_b32 m0, s36
	s_nop 0
	global_load_lds_dwordx4 v[216:217], off
	s_barrier
	s_waitcnt lgkmcnt(0)
	s_setprio 1
	s_waitcnt lgkmcnt(0)
	v_mfma_f32_16x16x32_bf16 v[60:63], v[128:131], v[144:147], 0
	v_mfma_f32_16x16x32_bf16 v[56:59], v[136:139], v[144:147], 0
	v_mfma_f32_16x16x32_bf16 v[44:47], v[128:131], v[152:155], 0
	v_mfma_f32_16x16x32_bf16 v[40:43], v[136:139], v[152:155], 0
	v_mfma_f32_16x16x32_bf16 v[28:31], v[128:131], v[160:163], 0
	v_mfma_f32_16x16x32_bf16 v[24:27], v[136:139], v[160:163], 0
	v_mfma_f32_16x16x32_bf16 v[12:15], v[128:131], v[168:171], 0
	v_mfma_f32_16x16x32_bf16 v[8:11], v[136:139], v[168:171], 0
	v_mfma_f32_16x16x32_bf16 v[60:63], v[132:135], v[148:151], v[60:63]
	v_mfma_f32_16x16x32_bf16 v[56:59], v[140:143], v[148:151], v[56:59]
	v_mfma_f32_16x16x32_bf16 v[44:47], v[132:135], v[156:159], v[44:47]
	v_mfma_f32_16x16x32_bf16 v[40:43], v[140:143], v[156:159], v[40:43]
	v_mfma_f32_16x16x32_bf16 v[28:31], v[132:135], v[164:167], v[28:31]
	v_mfma_f32_16x16x32_bf16 v[24:27], v[140:143], v[164:167], v[24:27]
	v_mfma_f32_16x16x32_bf16 v[12:15], v[132:135], v[172:175], v[12:15]
	v_mfma_f32_16x16x32_bf16 v[8:11], v[140:143], v[172:175], v[8:11]
	s_setprio 0
	s_barrier
; #define PG8_STAGE(bufoff, gbase, voff) do { _Pragma("unroll") for (int _i = 0; _i < 2; ++_i) \
;         __builtin_amdgcn_global_load_lds((const unsigned*)((const char*)(gbase) + (voff)[_i]), (LAS unsigned*)(lds + (bufoff) + ldsw + _i * 8192), 16, 0, 0); } while (0)
; #define PG8_LDA(dst, b, h) do { _Pragma("unroll") for (int m = 0; m < 4; ++m) _Pragma("unroll") for (int k = 0; k < 2; ++k) dst[m][k] = *(const LAS bf16x8*)(lds + PG8_SA(b, h) + aoff + m * 2048 + k * 1024); } while (0)
; #define PG8_LDB(dst, b, h) do { _Pragma("unroll") for (int n = 0; n < 2; ++n) _Pragma("unroll") for (int k = 0; k < 2; ++k) dst[n][k] = *(const LAS bf16x8*)(lds + PG8_SB(b, h) + boff + n * 2048 + k * 1024); } while (0)
; #define PG8_MMA(ai, bj, At, Bt) do { __builtin_amdgcn_s_setprio(1); _Pragma("unroll") for (int m = 0; m < 4; ++m) _Pragma("unroll") for (int n = 0; n < 2; ++n) _Pragma("unroll") for (int k = 0; k < 2; ++k) \
;         acc[ai][bj][m][n] = __builtin_amdgcn_mfma_f32_16x16x32_bf16(Bt[n][k], At[m][k], acc[ai][bj][m][n], 0, 0, 0); __builtin_amdgcn_s_setprio(0); } while (0)
; #define PG8_WAIT_V(n) asm volatile("s_waitcnt vmcnt(" #n ")" ::: "memory")
; #define PG8_WAIT_L(n) asm volatile("s_waitcnt lgkmcnt(" #n ")" ::: "memory")
; #define PG8_BAR __builtin_amdgcn_s_barrier()
; #define PG8_SCHED __builtin_amdgcn_sched_barrier(0)
; template <class Epi, class Sched>
; __device__ __forceinline__ void gemm_phase(LAS unsigned char* lds, const Gemm g, const Sched& S, const Epi& E) {
;     ...
;             PG8_STAGE(PG8_SB(0, 1), b2 + hstep, voffB);
;             PG8_WAIT_V(6); PG8_BAR; PG8_MMA(1, 1, At, B1); PG8_BAR;
;             PG8_LDB(B0, 1, 0); PG8_SCHED; PG8_LDA(At, 1, 0); PG8_STAGE(PG8_SA(0, 1), a2 + hstep, voffA);
;             PG8_WAIT_L(8); PG8_BAR; PG8_WAIT_L(0); PG8_MMA(0, 0, At, B0); PG8_BAR; PG8_SCHED;
;             PG8_LDB(B1, 1, 1); PG8_STAGE(PG8_SB(1, 0), b3, voffB);
	s_add_u32 s22, s26, 0xb0000
	s_addc_u32 s23, s27, 0
	s_add_i32 s57, s49, s34
	v_lshl_add_u64 v[128:129], s[22:23], 0, v[190:191]
	s_mov_b32 m0, s57
	s_nop 0
	global_load_lds_dwordx4 v[128:129], off
	v_lshl_add_u64 v[128:129], s[22:23], 0, v[194:195]
	s_add_i32 m0, s57, 0x2000
	s_nop 0
	global_load_lds_dwordx4 v[128:129], off
	s_waitcnt vmcnt(6)
	s_barrier
	s_setprio 1
	v_mfma_f32_16x16x32_bf16 v[52:55], v[176:179], v[144:147], 0
	v_mfma_f32_16x16x32_bf16 v[48:51], v[184:187], v[144:147], 0
	v_mfma_f32_16x16x32_bf16 v[36:39], v[176:179], v[152:155], 0
	v_mfma_f32_16x16x32_bf16 v[32:35], v[184:187], v[152:155], 0
	v_mfma_f32_16x16x32_bf16 v[20:23], v[176:179], v[160:163], 0
	v_mfma_f32_16x16x32_bf16 v[16:19], v[184:187], v[160:163], 0
	v_mfma_f32_16x16x32_bf16 v[4:7], v[176:179], v[168:171], 0
	v_mfma_f32_16x16x32_bf16 v[0:3], v[184:187], v[168:171], 0
	v_mfma_f32_16x16x32_bf16 v[52:55], v[180:183], v[148:151], v[52:55]
	v_mfma_f32_16x16x32_bf16 v[48:51], v[206:209], v[148:151], v[48:51]
	v_mfma_f32_16x16x32_bf16 v[36:39], v[180:183], v[156:159], v[36:39]
	v_mfma_f32_16x16x32_bf16 v[32:35], v[206:209], v[156:159], v[32:35]
	v_mfma_f32_16x16x32_bf16 v[20:23], v[180:183], v[164:167], v[20:23]
	v_mfma_f32_16x16x32_bf16 v[16:19], v[206:209], v[164:167], v[16:19]
	v_mfma_f32_16x16x32_bf16 v[4:7], v[180:183], v[172:175], v[4:7]
	v_mfma_f32_16x16x32_bf16 v[0:3], v[206:209], v[172:175], v[0:3]
	s_setprio 0
	s_add_i32 s57, 0, 0x18000
	v_add_u32_e32 v140, s57, v240
	s_barrier
	ds_read_b128 v[128:131], v140
	ds_read_b128 v[132:135], v140 offset:1024
	ds_read_b128 v[136:139], v140 offset:2048
	ds_read_b128 v[140:143], v140 offset:3072
	s_add_u32 s22, s28, 0xb0000
	s_addc_u32 s23, s29, 0
	s_mov_b32 m0, s37
	v_lshl_add_u64 v[176:177], s[22:23], 0, v[188:189]
	ds_read_b128 v[144:147], v242 offset:32768
	ds_read_b128 v[148:151], v242 offset:33792
	ds_read_b128 v[152:155], v242 offset:34816
	ds_read_b128 v[156:159], v242 offset:35840
	ds_read_b128 v[160:163], v242 offset:36864
	ds_read_b128 v[164:167], v242 offset:37888
	ds_read_b128 v[168:171], v242 offset:38912
	ds_read_b128 v[172:175], v242 offset:39936
	global_load_lds_dwordx4 v[176:177], off
	v_lshl_add_u64 v[176:177], s[22:23], 0, v[192:193]
	s_mov_b32 m0, s38
	s_nop 0
	global_load_lds_dwordx4 v[176:177], off
	s_waitcnt lgkmcnt(8)
	s_barrier
	s_waitcnt lgkmcnt(0)
	s_setprio 1
	s_waitcnt lgkmcnt(0)
	v_mfma_f32_16x16x32_bf16 v[124:127], v[128:131], v[144:147], v[124:127]
	v_mfma_f32_16x16x32_bf16 v[120:123], v[136:139], v[144:147], v[120:123]
	v_mfma_f32_16x16x32_bf16 v[108:111], v[128:131], v[152:155], v[108:111]
	v_mfma_f32_16x16x32_bf16 v[104:107], v[136:139], v[152:155], v[104:107]
	v_mfma_f32_16x16x32_bf16 v[92:95], v[128:131], v[160:163], v[92:95]
	v_mfma_f32_16x16x32_bf16 v[88:91], v[136:139], v[160:163], v[88:91]
	v_mfma_f32_16x16x32_bf16 v[76:79], v[128:131], v[168:171], v[76:79]
	v_mfma_f32_16x16x32_bf16 v[72:75], v[136:139], v[168:171], v[72:75]
	v_mfma_f32_16x16x32_bf16 v[124:127], v[132:135], v[148:151], v[124:127]
	v_mfma_f32_16x16x32_bf16 v[120:123], v[140:143], v[148:151], v[120:123]
	v_mfma_f32_16x16x32_bf16 v[108:111], v[132:135], v[156:159], v[108:111]
	v_mfma_f32_16x16x32_bf16 v[104:107], v[140:143], v[156:159], v[104:107]
	v_mfma_f32_16x16x32_bf16 v[92:95], v[132:135], v[164:167], v[92:95]
	v_mfma_f32_16x16x32_bf16 v[88:91], v[140:143], v[164:167], v[88:91]
	v_mfma_f32_16x16x32_bf16 v[76:79], v[132:135], v[172:175], v[76:79]
	v_mfma_f32_16x16x32_bf16 v[72:75], v[140:143], v[172:175], v[72:75]
	s_setprio 0
	s_barrier
	s_add_i32 s28, 0, 0x1c000
	s_add_i32 s22, s57, s34
	v_add_u32_e32 v206, s28, v240
	v_lshl_add_u64 v[210:211], v[210:211], 0, s[0:1]
	s_mov_b32 m0, s22
	ds_read_b128 v[176:179], v206
	ds_read_b128 v[180:183], v206 offset:1024
	ds_read_b128 v[184:187], v206 offset:2048
	ds_read_b128 v[206:209], v206 offset:3072
	global_load_lds_dwordx4 v[210:211], off
	v_lshl_add_u64 v[210:211], v[212:213], 0, s[0:1]
	s_add_i32 m0, s22, 0x2000
	s_nop 0
	global_load_lds_dwordx4 v[210:211], off
	s_barrier
; #define PG8_STAGE(bufoff, gbase, voff) do { _Pragma("unroll") for (int _i = 0; _i < 2; ++_i) \
;         __builtin_amdgcn_global_load_lds((const unsigned*)((const char*)(gbase) + (voff)[_i]), (LAS unsigned*)(lds + (bufoff) + ldsw + _i * 8192), 16, 0, 0); } while (0)
; #define PG8_LDA(dst, b, h) do { _Pragma("unroll") for (int m = 0; m < 4; ++m) _Pragma("unroll") for (int k = 0; k < 2; ++k) dst[m][k] = *(const LAS bf16x8*)(lds + PG8_SA(b, h) + aoff + m * 2048 + k * 1024); } while (0)
; #define PG8_MMA(ai, bj, At, Bt) do { __builtin_amdgcn_s_setprio(1); _Pragma("unroll") for (int m = 0; m < 4; ++m) _Pragma("unroll") for (int n = 0; n < 2; ++n) _Pragma("unroll") for (int k = 0; k < 2; ++k) \
;         acc[ai][bj][m][n] = __builtin_amdgcn_mfma_f32_16x16x32_bf16(Bt[n][k], At[m][k], acc[ai][bj][m][n], 0, 0, 0); __builtin_amdgcn_s_setprio(0); } while (0)
; #define PG8_WAIT_V(n) asm volatile("s_waitcnt vmcnt(" #n ")" ::: "memory")
; #define PG8_WAIT_L(n) asm volatile("s_waitcnt lgkmcnt(" #n ")" ::: "memory")
; #define PG8_BAR __builtin_amdgcn_s_barrier()
; #define PG8_SCHED __builtin_amdgcn_sched_barrier(0)
; template <class Epi, class Sched>
; __device__ __forceinline__ void gemm_phase(LAS unsigned char* lds, const Gemm g, const Sched& S, const Epi& E) {
;     ...
;             PG8_BAR; PG8_WAIT_L(0); PG8_MMA(0, 1, At, B1); PG8_BAR;
;             PG8_LDA(At, 1, 1); PG8_STAGE(PG8_SA(1, 0), a3, voffA);
;             PG8_BAR; PG8_WAIT_L(0); PG8_MMA(1, 0, At, B0); PG8_BAR; PG8_SCHED;
;             PG8_STAGE(PG8_SB(1, 1), b3 + hstep, voffB);
;             PG8_WAIT_V(6); PG8_BAR; PG8_MMA(1, 1, At, B1); PG8_BAR;
	s_waitcnt lgkmcnt(0)
	s_setprio 1
	s_waitcnt lgkmcnt(0)
	v_mfma_f32_16x16x32_bf16 v[116:119], v[176:179], v[144:147], v[116:119]
	v_mfma_f32_16x16x32_bf16 v[112:115], v[184:187], v[144:147], v[112:115]
	v_mfma_f32_16x16x32_bf16 v[100:103], v[176:179], v[152:155], v[100:103]
	v_mfma_f32_16x16x32_bf16 v[96:99], v[184:187], v[152:155], v[96:99]
	v_mfma_f32_16x16x32_bf16 v[84:87], v[176:179], v[160:163], v[84:87]
	v_mfma_f32_16x16x32_bf16 v[80:83], v[184:187], v[160:163], v[80:83]
	v_mfma_f32_16x16x32_bf16 v[68:71], v[176:179], v[168:171], v[68:71]
	v_mfma_f32_16x16x32_bf16 v[64:67], v[184:187], v[168:171], v[64:67]
	v_mfma_f32_16x16x32_bf16 v[116:119], v[180:183], v[148:151], v[116:119]
	v_mfma_f32_16x16x32_bf16 v[112:115], v[206:209], v[148:151], v[112:115]
	v_mfma_f32_16x16x32_bf16 v[100:103], v[180:183], v[156:159], v[100:103]
	v_mfma_f32_16x16x32_bf16 v[96:99], v[206:209], v[156:159], v[96:99]
	v_mfma_f32_16x16x32_bf16 v[84:87], v[180:183], v[164:167], v[84:87]
	v_mfma_f32_16x16x32_bf16 v[80:83], v[206:209], v[164:167], v[80:83]
	v_mfma_f32_16x16x32_bf16 v[68:71], v[180:183], v[172:175], v[68:71]
	v_mfma_f32_16x16x32_bf16 v[64:67], v[206:209], v[172:175], v[64:67]
	s_setprio 0
	s_mov_b32 m0, s44
	v_lshl_add_u64 v[210:211], v[214:215], 0, s[0:1]
	s_barrier
	ds_read_b128 v[144:147], v242 offset:49152
	ds_read_b128 v[148:151], v242 offset:50176
	ds_read_b128 v[152:155], v242 offset:51200
	ds_read_b128 v[156:159], v242 offset:52224
	ds_read_b128 v[160:163], v242 offset:53248
	ds_read_b128 v[164:167], v242 offset:54272
	ds_read_b128 v[168:171], v242 offset:55296
	ds_read_b128 v[172:175], v242 offset:56320
	global_load_lds_dwordx4 v[210:211], off
	v_lshl_add_u64 v[210:211], v[216:217], 0, s[0:1]
	s_mov_b32 m0, s45
	s_nop 0
	global_load_lds_dwordx4 v[210:211], off
	s_barrier
	s_waitcnt lgkmcnt(0)
	s_setprio 1
	s_waitcnt lgkmcnt(0)
	v_mfma_f32_16x16x32_bf16 v[60:63], v[128:131], v[144:147], v[60:63]
	v_mfma_f32_16x16x32_bf16 v[56:59], v[136:139], v[144:147], v[56:59]
	v_mfma_f32_16x16x32_bf16 v[44:47], v[128:131], v[152:155], v[44:47]
	v_mfma_f32_16x16x32_bf16 v[40:43], v[136:139], v[152:155], v[40:43]
	v_mfma_f32_16x16x32_bf16 v[28:31], v[128:131], v[160:163], v[28:31]
	v_mfma_f32_16x16x32_bf16 v[24:27], v[136:139], v[160:163], v[24:27]
	v_mfma_f32_16x16x32_bf16 v[12:15], v[128:131], v[168:171], v[12:15]
	v_mfma_f32_16x16x32_bf16 v[8:11], v[136:139], v[168:171], v[8:11]
	v_mfma_f32_16x16x32_bf16 v[60:63], v[132:135], v[148:151], v[60:63]
	v_mfma_f32_16x16x32_bf16 v[56:59], v[140:143], v[148:151], v[56:59]
	v_mfma_f32_16x16x32_bf16 v[44:47], v[132:135], v[156:159], v[44:47]
	v_mfma_f32_16x16x32_bf16 v[40:43], v[140:143], v[156:159], v[40:43]
	v_mfma_f32_16x16x32_bf16 v[28:31], v[132:135], v[164:167], v[28:31]
	v_mfma_f32_16x16x32_bf16 v[24:27], v[140:143], v[164:167], v[24:27]
	v_mfma_f32_16x16x32_bf16 v[12:15], v[132:135], v[172:175], v[12:15]
	v_mfma_f32_16x16x32_bf16 v[8:11], v[140:143], v[172:175], v[8:11]
	s_setprio 0
	s_barrier
	s_add_u32 s22, s26, 0xb0080
	s_addc_u32 s23, s27, 0
	s_add_i32 s26, s28, s34
	v_lshl_add_u64 v[128:129], s[22:23], 0, v[190:191]
	s_mov_b32 m0, s26
	s_nop 0
	global_load_lds_dwordx4 v[128:129], off
	v_lshl_add_u64 v[128:129], s[22:23], 0, v[194:195]
	s_add_i32 m0, s26, 0x2000
	s_nop 0
	global_load_lds_dwordx4 v[128:129], off
	s_waitcnt vmcnt(6)
	s_barrier
	s_setprio 1
	v_mfma_f32_16x16x32_bf16 v[52:55], v[176:179], v[144:147], v[52:55]
	v_mfma_f32_16x16x32_bf16 v[48:51], v[184:187], v[144:147], v[48:51]
	v_mfma_f32_16x16x32_bf16 v[36:39], v[176:179], v[152:155], v[36:39]
	v_mfma_f32_16x16x32_bf16 v[32:35], v[184:187], v[152:155], v[32:35]
	v_mfma_f32_16x16x32_bf16 v[20:23], v[176:179], v[160:163], v[20:23]
	v_mfma_f32_16x16x32_bf16 v[16:19], v[184:187], v[160:163], v[16:19]
	v_mfma_f32_16x16x32_bf16 v[4:7], v[176:179], v[168:171], v[4:7]
	v_mfma_f32_16x16x32_bf16 v[0:3], v[184:187], v[168:171], v[0:3]
	v_mfma_f32_16x16x32_bf16 v[52:55], v[180:183], v[148:151], v[52:55]
	v_mfma_f32_16x16x32_bf16 v[48:51], v[206:209], v[148:151], v[48:51]
	v_mfma_f32_16x16x32_bf16 v[36:39], v[180:183], v[156:159], v[36:39]
	v_mfma_f32_16x16x32_bf16 v[32:35], v[206:209], v[156:159], v[32:35]
	v_mfma_f32_16x16x32_bf16 v[20:23], v[180:183], v[164:167], v[20:23]
	v_mfma_f32_16x16x32_bf16 v[16:19], v[206:209], v[164:167], v[16:19]
	v_mfma_f32_16x16x32_bf16 v[4:7], v[180:183], v[172:175], v[4:7]
	v_mfma_f32_16x16x32_bf16 v[0:3], v[206:209], v[172:175], v[0:3]
	s_setprio 0
	s_add_i32 s56, s56, 2
	s_add_u32 s54, s54, 0x100
	s_addc_u32 s55, s55, 0
	s_cmp_gt_u32 s56, 41
	s_mov_b64 s[22:23], s[24:25]
	s_barrier
